# removed compiler full-drain before gemm256 K-loop entry (3 sites); moved pre-staging drains in merge/out epilogues; out-phase gate sums cached in extra static LDS; V operand via ds_read_b64_tr_b16
# speedup vs baseline: 1.0461x; 1.0141x over previous
.LBB0_361:
	v_and_b32_e32 v2, 15, v1
	v_and_b32_e32 v3, 48, v1
	v_lshlrev_b32_e32 v2, 6, v2
	v_lshlrev_b32_e32 v1, 2, v1
	v_or_b32_e32 v4, v2, v3
	v_and_b32_e32 v1, 32, v1
	s_lshl_b32 s38, s38, 13
	v_bitop3_b32 v4, v4, s38, v1 bitop3:0xde
	s_lshl_b32 s38, s47, 6
	v_bitop3_b32 v2, v2, v1, v3 bitop3:0x36
	s_and_b32 s38, s38, 0x3000
	v_or_b32_e32 v137, s38, v2
	s_add_u32 s38, s0, 0x80
	s_addc_u32 s39, s1, 0
	v_add_u32_e32 v138, s93, v0
	v_lshl_add_u64 v[2:3], s[38:39], 0, v[192:193]
	v_readfirstlane_b32 s38, v138
	v_add_u32_e32 v139, 0x2000, v138
	s_mov_b32 m0, s38
	v_readfirstlane_b32 s38, v139
	s_waitcnt vmcnt(4)
	s_barrier
	global_load_lds_dwordx4 v[2:3], off
	s_mov_b32 m0, s38
	s_add_u32 s38, s2, 0x80
	v_lshl_add_u64 v[2:3], v[2:3], 0, s[4:5]
	s_addc_u32 s39, s3, 0
	v_add_u32_e32 v140, 0x8000, v131
	global_load_lds_dwordx4 v[2:3], off
	v_lshl_add_u64 v[2:3], s[38:39], 0, v[192:193]
	v_readfirstlane_b32 s38, v140
	v_add_u32_e32 v141, 0xa000, v131
	s_mov_b32 m0, s38
	v_readfirstlane_b32 s38, v141
	global_load_lds_dwordx4 v[2:3], off
	s_mov_b32 m0, s38
	s_add_u32 s38, s12, 0x80
	v_lshl_add_u64 v[2:3], v[2:3], 0, s[4:5]
	s_addc_u32 s39, s13, 0
	v_add_u32_e32 v142, s89, v0
	global_load_lds_dwordx4 v[2:3], off
	v_lshl_add_u64 v[2:3], s[38:39], 0, v[192:193]
	v_readfirstlane_b32 s38, v142
	v_add_u32_e32 v143, 0x2000, v142
	s_mov_b32 m0, s38
	v_readfirstlane_b32 s38, v143
	global_load_lds_dwordx4 v[2:3], off
	v_lshl_add_u64 v[0:1], v[2:3], 0, s[4:5]
	s_mov_b32 m0, s38
	s_mov_b32 s48, -2
	global_load_lds_dwordx4 v[0:1], off
	s_waitcnt vmcnt(6)
	v_mov_b32_e32 v0, 0
	s_mov_b64 s[38:39], 0
	v_add_u32_e32 v128, 0, v4
	v_mov_b32_e32 v1, v0
	v_mov_b32_e32 v2, v0
	v_mov_b32_e32 v3, v0
	v_mov_b32_e32 v4, v0
	v_mov_b32_e32 v5, v0
	v_mov_b32_e32 v6, v0
	v_mov_b32_e32 v7, v0
	v_mov_b32_e32 v8, v0
	v_mov_b32_e32 v9, v0
	v_mov_b32_e32 v10, v0
	v_mov_b32_e32 v11, v0
	v_mov_b32_e32 v12, v0
	v_mov_b32_e32 v13, v0
	v_mov_b32_e32 v14, v0
	v_mov_b32_e32 v15, v0
	v_mov_b32_e32 v16, v0
	v_mov_b32_e32 v17, v0
	v_mov_b32_e32 v18, v0
	v_mov_b32_e32 v19, v0
	v_mov_b32_e32 v20, v0
	v_mov_b32_e32 v21, v0
	v_mov_b32_e32 v22, v0
	v_mov_b32_e32 v23, v0
	v_mov_b32_e32 v24, v0
	v_mov_b32_e32 v25, v0
	v_mov_b32_e32 v26, v0
	v_mov_b32_e32 v27, v0
	v_mov_b32_e32 v28, v0
	v_mov_b32_e32 v29, v0
	v_mov_b32_e32 v30, v0
	v_mov_b32_e32 v31, v0
	v_mov_b32_e32 v32, v0
	v_mov_b32_e32 v33, v0
	v_mov_b32_e32 v34, v0
	v_mov_b32_e32 v35, v0
	v_mov_b32_e32 v36, v0
	v_mov_b32_e32 v37, v0
	v_mov_b32_e32 v38, v0
	v_mov_b32_e32 v39, v0
	v_mov_b32_e32 v40, v0
	v_mov_b32_e32 v41, v0
	v_mov_b32_e32 v42, v0
	v_mov_b32_e32 v43, v0
	v_mov_b32_e32 v44, v0
	v_mov_b32_e32 v45, v0
	v_mov_b32_e32 v46, v0
	v_mov_b32_e32 v47, v0
	v_mov_b32_e32 v48, v0
	v_mov_b32_e32 v49, v0
	v_mov_b32_e32 v50, v0
	v_mov_b32_e32 v51, v0
	v_mov_b32_e32 v52, v0
	v_mov_b32_e32 v53, v0
	v_mov_b32_e32 v54, v0
	v_mov_b32_e32 v55, v0
	v_mov_b32_e32 v56, v0
	v_mov_b32_e32 v57, v0
	v_mov_b32_e32 v58, v0
	v_mov_b32_e32 v59, v0
	v_mov_b32_e32 v60, v0
	v_mov_b32_e32 v61, v0
	v_mov_b32_e32 v62, v0
	v_mov_b32_e32 v63, v0
	v_mov_b32_e32 v64, v0
	v_mov_b32_e32 v65, v0
	v_mov_b32_e32 v66, v0
	v_mov_b32_e32 v67, v0
	v_mov_b32_e32 v68, v0
	v_mov_b32_e32 v69, v0
	v_mov_b32_e32 v70, v0
	v_mov_b32_e32 v71, v0
	v_mov_b32_e32 v72, v0
	v_mov_b32_e32 v73, v0
	v_mov_b32_e32 v74, v0
	v_mov_b32_e32 v75, v0
	v_mov_b32_e32 v76, v0
	v_mov_b32_e32 v77, v0
	v_mov_b32_e32 v78, v0
	v_mov_b32_e32 v79, v0
	v_mov_b32_e32 v80, v0
	v_mov_b32_e32 v81, v0
	v_mov_b32_e32 v82, v0
	v_mov_b32_e32 v83, v0
	v_mov_b32_e32 v84, v0
	v_mov_b32_e32 v85, v0
	v_mov_b32_e32 v86, v0
	v_mov_b32_e32 v87, v0
	v_mov_b32_e32 v88, v0
	v_mov_b32_e32 v89, v0
	v_mov_b32_e32 v90, v0
	v_mov_b32_e32 v91, v0
	v_mov_b32_e32 v92, v0
	v_mov_b32_e32 v93, v0
	v_mov_b32_e32 v94, v0
	v_mov_b32_e32 v95, v0
	v_mov_b32_e32 v96, v0
	v_mov_b32_e32 v97, v0
	v_mov_b32_e32 v98, v0
	v_mov_b32_e32 v99, v0
	v_mov_b32_e32 v100, v0
	v_mov_b32_e32 v101, v0
	v_mov_b32_e32 v102, v0
	v_mov_b32_e32 v103, v0
	v_mov_b32_e32 v104, v0
	v_mov_b32_e32 v105, v0
	v_mov_b32_e32 v106, v0
	v_mov_b32_e32 v107, v0
	v_mov_b32_e32 v108, v0
	v_mov_b32_e32 v109, v0
	v_mov_b32_e32 v110, v0
	v_mov_b32_e32 v111, v0
	v_mov_b32_e32 v112, v0
	v_mov_b32_e32 v113, v0
	v_mov_b32_e32 v114, v0
	v_mov_b32_e32 v115, v0
	v_mov_b32_e32 v116, v0
	v_mov_b32_e32 v117, v0
	v_mov_b32_e32 v118, v0
	v_mov_b32_e32 v119, v0
	v_mov_b32_e32 v120, v0
	v_mov_b32_e32 v121, v0
	v_mov_b32_e32 v122, v0
	v_mov_b32_e32 v123, v0
	v_mov_b32_e32 v124, v0
	v_mov_b32_e32 v125, v0
	v_mov_b32_e32 v126, v0
	v_mov_b32_e32 v127, v0
	s_barrier

.LBB0_633:
	s_or_b64 exec, exec, s[2:3]
	v_cmp_lt_i32_e32 vcc, v246, v239
	s_movk_i32 s2, 0x80
	v_lshl_add_u32 v11, v4, 8, s92
	v_cndmask_b32_e32 v4, v237, v246, vcc
	v_cmp_gt_u32_e64 s[40:41], s2, v195
	s_movk_i32 s2, 0x210
	v_lshl_add_u32 v10, v3, 7, s92
	v_lshlrev_b32_e32 v124, 2, v4
	v_lshlrev_b32_e32 v4, 2, v190
	v_add_u32_e32 v127, s79, v3
	v_mul_lo_u32 v3, v111, s2
	v_lshlrev_b32_e32 v21, 6, v2
	v_lshl_or_b32 v18, v196, 3, v4
	v_add3_u32 v128, s92, v3, v21
	v_lshlrev_b32_e32 v3, 4, v195
	v_and_b32_e32 v21, 0xffffffe0, v3
	v_and_b32_e32 v22, 16, v3
	v_or_b32_e32 v3, 1, v18
	v_cmp_gt_i32_e64 s[46:47], v197, v3
	v_or_b32_e32 v3, 2, v18
	v_ashrrev_i32_e32 v8, 7, v195
	v_cmp_gt_i32_e64 s[48:49], v197, v3
	v_or_b32_e32 v3, 3, v18
	v_lshl_add_u32 v12, v5, 8, s92
	v_lshl_or_b32 v5, v8, 4, v4
	s_movk_i32 s11, 0x50
	s_movk_i32 s3, 0x90
	v_cmp_gt_i32_e64 s[50:51], v197, v3
	v_or_b32_e32 v3, 8, v4
	v_mov_b32_e32 v9, s92
	v_lshlrev_b32_e32 v130, 7, v5
	v_mul_lo_u32 v23, v5, s3
	v_cmp_gt_i32_e64 s[44:45], v197, v18
	v_mul_lo_u32 v31, v18, s11
	v_lshlrev_b32_e32 v18, 1, v3
	v_lshlrev_b32_e32 v5, 2, v72
	v_mul_u32_u24_e32 v3, 0x210, v3
	v_cmp_eq_u32_e32 vcc, 2, v196
	v_mad_u32_u24 v17, v197, s3, v9
	v_add3_u32 v132, s92, v3, v5
	v_cndmask_b32_e64 v3, 12, 8, vcc
	v_cmp_eq_u32_e64 s[2:3], 1, v196
	v_cmp_gt_u32_e64 s[54:55], 64, v195
	v_cmp_eq_u32_e64 s[38:39], 0, v190
	v_cndmask_b32_e64 v3, v3, 4, s[2:3]
	v_cndmask_b32_e64 v108, v3, 0, s[54:55]
	v_cndmask_b32_e64 v3, 13, 9, vcc
	v_cndmask_b32_e64 v3, v3, 5, s[2:3]
	v_cndmask_b32_e64 v110, v3, 1, s[54:55]
	v_cndmask_b32_e64 v3, 14, 10, vcc
	v_cndmask_b32_e64 v3, v3, 6, s[2:3]
	s_and_b64 s[72:73], s[40:41], s[38:39]
	v_cndmask_b32_e64 v112, v3, 2, s[54:55]
	v_cndmask_b32_e64 v3, 15, 11, vcc
	v_lshlrev_b32_e32 v1, 3, v2
	v_mul_u32_u24_e32 v4, 0x840, v190
	v_cndmask_b32_e64 v3, v3, 7, s[2:3]
	s_add_u32 s2, s58, s74
	s_mov_b64 s[16:17], s[24:25]
	v_add3_u32 v131, s92, v4, v5
	s_addc_u32 s3, s59, 0
	v_lshlrev_b32_e32 v4, 1, v1
	v_mov_b32_e32 v5, v193
	s_lshl_b32 s43, s43, 1
	s_mov_b64 s[20:21], s[28:29]
	v_lshl_add_u64 v[116:117], s[2:3], 0, v[4:5]
	s_add_u32 s2, s20, s43
	v_cndmask_b32_e64 v114, v3, 3, s[54:55]
	s_addc_u32 s3, s21, 0
	v_lshlrev_b32_e32 v2, 5, v2
	v_mov_b32_e32 v3, v193
	v_lshlrev_b32_e32 v6, 3, v6
	v_and_b32_e32 v7, 0x7f, v195
	v_mul_u32_u24_e32 v14, 0x50, v199
	v_mul_lo_u32 v20, v72, s11
	v_lshl_add_u64 v[118:119], s[2:3], 0, v[2:3]
	s_add_u32 s2, s58, s43
	v_lshl_add_u32 v13, v197, 5, s92
	v_lshlrev_b32_e32 v123, 4, v190
	v_lshl_add_u32 v125, v199, 1, s92
	v_lshlrev_b32_e32 v15, 5, v8
	v_lshlrev_b32_e32 v16, 1, v7
	v_mad_u32_u24 v7, v7, s11, v9
	v_lshl_add_u32 v19, v197, 1, s92
	v_add_u32_e32 v20, s92, v20
	v_mad_u32_u24 v9, v197, s11, v9
	v_add_u32_e32 v21, s92, v21
	v_or_b32_e32 v24, 0x80, v130
	v_or_b32_e32 v25, 0x100, v130
	v_or_b32_e32 v26, 0x180, v130
	v_add3_u32 v14, s92, v14, v198
	v_or_b32_e32 v27, 0x400, v130
	v_or_b32_e32 v28, 0x480, v130
	v_or_b32_e32 v29, 0x500, v130
	v_or_b32_e32 v30, 0x580, v130
	v_lshl_add_u32 v8, v8, 12, s92
	v_or_b32_e32 v56, 32, v198
	v_or_b32_e32 v57, 48, v198
	s_addc_u32 s3, s59, 0
	v_lshlrev_b32_e32 v2, 1, v6
	v_cvt_pk_bf16_f32 v52, v200, v201
	v_cvt_pk_bf16_f32 v53, v202, v203
	v_cvt_pk_bf16_f32 v54, v204, v205
	v_cvt_pk_bf16_f32 v55, v206, v207
	s_mov_b32 s10, 1
	v_add_u32_e32 v126, s92, v123
	s_mov_b32 s75, 6
	v_lshl_add_u32 v129, v199, 2, s92
	v_add_u32_e32 v133, 0x1080, v132
	v_add_u32_e32 v134, 0x2100, v132
	v_lshl_add_u64 v[120:121], s[2:3], 0, v[2:3]
	v_add_u32_e32 v135, v10, v192
	v_add_u32_e32 v136, v11, v0
	v_add_u32_e32 v137, v12, v0
	v_add_u32_e32 v138, v21, v22
	v_add_u32_e32 v139, v13, v123
	v_add_u32_e32 v140, v125, v23
	v_add_u32_e32 v141, v125, v24
	v_add_u32_e32 v142, v125, v25
	v_add_u32_e32 v143, v125, v26
	v_add_u32_e32 v144, v14, v15
	v_add_u32_e32 v145, v125, v27
	v_add_u32_e32 v146, v125, v28
	v_add_u32_e32 v147, v125, v29
	v_add_u32_e32 v148, v125, v30
	v_add_u32_e32 v149, v8, v16
	v_add_u32_e32 v150, v7, v15
	v_add_u32_e32 v151, v17, v123
	v_add_u32_e32 v152, v19, v31
	v_add_u32_e32 v153, v20, v123
	v_add_u32_e32 v154, v9, v123
	v_add_u32_e32 v155, v73, v18
	v_add_u32_e32 v156, v73, v56
	v_add_u32_e32 v157, v73, v57
	s_mov_b64 s[18:19], s[26:27]
	s_waitcnt vmcnt(0)
	v_and_b32_e32 v232, 3, v235
	v_lshlrev_b32_e32 v232, 3, v232
	v_bfe_u32 v233, v235, 2, 2
	v_lshl_or_b32 v232, v233, 8, v232
	v_bfe_u32 v233, v235, 4, 1
	v_lshl_or_b32 v232, v233, 5, v232
	v_bfe_u32 v233, v235, 5, 1
	v_lshl_or_b32 v232, v233, 11, v232
	v_lshrrev_b32_e32 v233, 6, v235
	v_lshl_or_b32 v232, v233, 6, v232
	v_add_u32_e32 v232, s92, v232
	s_branch .LBB0_635
.LBB0_634:
	s_or_b64 exec, exec, s[2:3]
	ds_read_b64_tr_b16 v[228:229], v232 offset:55040
	ds_read_b64_tr_b16 v[230:231], v232 offset:56064
	ds_read_b64_tr_b16 v[240:241], v232 offset:59136
	ds_read_b64_tr_b16 v[242:243], v232 offset:60160
	s_waitcnt lgkmcnt(0)
	s_barrier
	ds_read_b128 v[0:3], v151
	ds_read_b128 v[4:7], v151 offset:4608
	ds_read_b128 v[16:19], v151 offset:32
	ds_read_b128 v[20:23], v151 offset:4640
	s_waitcnt lgkmcnt(2)
	v_mfma_f32_32x32x16_bf16 v[0:15], v[0:3], v[4:7], 0
	v_add_u32_e32 v182, v73, v123
	s_add_i32 s43, s10, -1
	s_add_i32 s54, s75, 1
	s_and_b64 s[2:3], s[36:37], exec
	s_cselect_b32 s2, s54, s43
	s_add_i32 s75, s75, -1
	s_waitcnt lgkmcnt(0)
	v_mfma_f32_32x32x16_bf16 v[0:15], v[16:19], v[20:23], v[0:15]
	ds_read_b128 v[16:19], v151 offset:64
	ds_read_b128 v[20:23], v151 offset:4672
	ds_read_b128 v[24:27], v151 offset:96
	ds_read_b128 v[28:31], v151 offset:4704
	s_add_i32 s10, s10, 1
	s_cmp_eq_u32 s75, -2
	s_waitcnt lgkmcnt(2)
	v_mfma_f32_32x32x16_bf16 v[0:15], v[16:19], v[20:23], v[0:15]
	s_waitcnt lgkmcnt(0)
	v_mfma_f32_32x32x16_bf16 v[0:15], v[24:27], v[28:31], v[0:15]
	s_nop 11
	v_cmp_eq_u32_e32 vcc, 0, v108
	s_cbranch_vccnz .Lgsel_w0
	v_cmp_eq_u32_e32 vcc, 4, v108
	s_cbranch_vccnz .Lgsel_w1
	v_cmp_eq_u32_e32 vcc, 8, v108
	s_cbranch_vccnz .Lgsel_w2
	v_cvt_pk_bf16_f32 v16, v12, v12
	v_cvt_pk_bf16_f32 v17, v13, v13
	v_cvt_pk_bf16_f32 v18, v14, v14
	v_cvt_pk_bf16_f32 v19, v15, v15
	s_branch .Lgsel_done

.Lgsel_done:
	v_cndmask_b32_e64 v16, v16, 0, s[44:45]
	v_cndmask_b32_e64 v17, v17, 0, s[46:47]
	v_cndmask_b32_e64 v18, v18, 0, s[48:49]
	v_cndmask_b32_e64 v19, v19, 0, s[50:51]
	ds_write_b16 v152, v16 offset:24576
	ds_write_b16 v152, v17 offset:24656
	ds_write_b16 v152, v18 offset:24736
	ds_write_b16 v152, v19 offset:24816
	s_waitcnt lgkmcnt(0)
	s_barrier
	ds_read_b128 v[0:3], v154 offset:9216
	ds_read_b128 v[56:59], v151 offset:96
	ds_read_b128 v[4:7], v154 offset:24576
	ds_read_b128 v[28:31], v154 offset:9248
	s_waitcnt lgkmcnt(3)
	v_mfma_f32_32x32x16_bf16 v[8:23], v[0:3], v[228:231], 0
	ds_read_b128 v[162:165], v154 offset:24608
	ds_read_b128 v[166:169], v182 offset:27136
	ds_read_b128 v[64:67], v151 offset:32
	ds_read_b128 v[60:63], v151 offset:64
	ds_read_b128 v[170:173], v151
	ds_read_b128 v[0:3], v126 offset:45568
	s_waitcnt lgkmcnt(6)
	v_mfma_f32_32x32x16_bf16 v[8:23], v[28:31], v[240:243], v[8:23]
	s_waitcnt lgkmcnt(0)
	s_nop 10
	v_pk_fma_f32 v[74:75], v[74:75], v[0:1], v[8:9]
	v_pk_fma_f32 v[76:77], v[76:77], v[2:3], v[10:11]
	v_cvt_pk_bf16_f32 v0, v74, v75
	v_cvt_pk_bf16_f32 v1, v76, v77
	ds_write_b64 v109, v[0:1] offset:27136
	ds_read_b128 v[0:3], v126 offset:45600
	s_waitcnt lgkmcnt(0)
	v_pk_fma_f32 v[78:79], v[78:79], v[0:1], v[12:13]
	v_pk_fma_f32 v[80:81], v[80:81], v[2:3], v[14:15]
	v_cvt_pk_bf16_f32 v0, v78, v79
	v_cvt_pk_bf16_f32 v1, v80, v81
	ds_write_b64 v155, v[0:1] offset:27136
	ds_read_b128 v[28:31], v126 offset:45632
	ds_read_b128 v[68:71], v182 offset:27168
	v_mfma_f32_32x32x16_bf16 v[0:15], v[4:7], v[228:231], 0
	s_waitcnt lgkmcnt(1)
	v_fma_f32 v82, v82, v28, v16
	v_fma_f32 v83, v83, v29, v17
	v_fma_f32 v84, v84, v30, v18
	v_fma_f32 v85, v85, v31, v19
	v_cvt_pk_bf16_f32 v16, v82, v83
	v_cvt_pk_bf16_f32 v17, v84, v85
	ds_write_b64 v156, v[16:17] offset:27136
	ds_read_b128 v[16:19], v126 offset:45664
	v_mfma_f32_32x32x16_bf16 v[0:15], v[162:165], v[240:243], v[0:15]
	s_waitcnt lgkmcnt(0)
	v_fma_f32 v86, v86, v16, v20
	v_fma_f32 v87, v87, v17, v21
	v_fma_f32 v88, v88, v18, v22
	v_fma_f32 v89, v89, v19, v23
	v_cvt_pk_bf16_f32 v16, v86, v87
	v_cvt_pk_bf16_f32 v17, v88, v89
	ds_write_b64 v157, v[16:17] offset:27136
	ds_read_b128 v[16:19], v154 offset:11776
	ds_read_b128 v[162:165], v126 offset:45696
	s_waitcnt lgkmcnt(1)
	v_mfma_f32_32x32x16_bf16 v[16:31], v[16:19], v[228:231], 0
	ds_read_b128 v[174:177], v154 offset:11808
	ds_read_b128 v[178:181], v182 offset:27200
	s_waitcnt lgkmcnt(1)
	v_mfma_f32_32x32x16_bf16 v[16:31], v[174:177], v[240:243], v[16:31]
	v_mfma_f32_32x32x16_bf16 v[0:15], v[170:173], v[166:169], v[0:15]
	s_nop 10
	v_fma_f32 v90, v90, v162, v16
	v_fma_f32 v91, v91, v163, v17
	v_fma_f32 v92, v92, v164, v18
	v_fma_f32 v93, v93, v165, v19
	v_cvt_pk_bf16_f32 v16, v90, v91
	v_cvt_pk_bf16_f32 v17, v92, v93
	ds_write_b64 v109, v[16:17] offset:27200
	ds_read_b128 v[16:19], v126 offset:45728
	s_waitcnt lgkmcnt(0)
	v_pk_fma_f32 v[94:95], v[94:95], v[16:17], v[20:21]
	v_mfma_f32_32x32x16_bf16 v[0:15], v[64:67], v[68:71], v[0:15]
	v_fma_f32 v96, v96, v18, v22
	v_fma_f32 v97, v97, v19, v23
	v_cvt_pk_bf16_f32 v16, v94, v95
	v_cvt_pk_bf16_f32 v17, v96, v97
	ds_write_b64 v109, v[16:17] offset:27216
	ds_read_b128 v[16:19], v126 offset:45760
	ds_read_b128 v[20:23], v182 offset:27232
	s_waitcnt lgkmcnt(1)
	v_pk_fma_f32 v[98:99], v[98:99], v[16:17], v[24:25]
	v_mfma_f32_32x32x16_bf16 v[0:15], v[60:63], v[178:181], v[0:15]
	v_fma_f32 v100, v100, v18, v26
	v_fma_f32 v101, v101, v19, v27
	v_cvt_pk_bf16_f32 v16, v98, v99
	v_cvt_pk_bf16_f32 v17, v100, v101
	ds_write_b64 v109, v[16:17] offset:27232
	ds_read_b128 v[16:19], v126 offset:45792
	s_waitcnt lgkmcnt(0)
	v_pk_fma_f32 v[102:103], v[102:103], v[16:17], v[28:29]
	v_mfma_f32_32x32x16_bf16 v[0:15], v[56:59], v[20:23], v[0:15]
	v_fma_f32 v104, v104, v18, v30
	v_fma_f32 v105, v105, v19, v31
	v_cvt_pk_bf16_f32 v16, v102, v103
	v_cvt_pk_bf16_f32 v17, v104, v105
	ds_write_b64 v109, v[16:17] offset:27248
	v_add_u32_e32 v16, 0xb600, v131
	s_nop 5
	ds_write2_b32 v16, v0, v1 offset0:64 offset1:196
	v_add_u32_e32 v0, 0xba00, v131
	ds_write2_b32 v0, v2, v3 offset0:72 offset1:204
	ds_write_b32 v132, v4 offset:46848
	v_add_u32_e32 v0, 0xc800, v131
	ds_write2_b32 v0, v5, v6 offset0:100 offset1:232
	ds_write_b32 v131, v7 offset:52656
	ds_write_b32 v133, v8 offset:46848
	v_add_u32_e32 v0, 0xda00, v131
	ds_write2_b32 v0, v9, v10 offset0:4 offset1:136
	ds_write_b32 v131, v11 offset:56880
	ds_write_b32 v134, v12 offset:46848
	v_add_u32_e32 v0, 0xea00, v131
	ds_write2_b32 v0, v13, v14 offset0:36 offset1:168
	ds_write_b32 v131, v15 offset:61104
	s_waitcnt lgkmcnt(0)
	s_barrier
	v_lshl_add_u32 v16, s2, 5, v127
	ds_read_b128 v[0:3], v128 offset:46848
	ds_read_b128 v[4:7], v128 offset:46864
	ds_read_b128 v[8:11], v128 offset:46880
	ds_read_b128 v[12:15], v128 offset:46896
	v_ashrrev_i32_e32 v17, 31, v16
	v_lshl_add_u64 v[16:17], v[16:17], 0, s[12:13]
	v_lshlrev_b64 v[16:17], 10, v[16:17]
	v_lshl_add_u64 v[16:17], v[118:119], 0, v[16:17]
	s_waitcnt lgkmcnt(3)
	v_cvt_pk_bf16_f32 v0, v0, v1
	v_cvt_pk_bf16_f32 v1, v2, v3
	s_waitcnt lgkmcnt(2)
	v_cvt_pk_bf16_f32 v2, v4, v5
	v_cvt_pk_bf16_f32 v3, v6, v7
	global_store_dwordx4 v[16:17], v[0:3], off
	s_waitcnt lgkmcnt(1)
	s_nop 0
	v_cvt_pk_bf16_f32 v0, v8, v9
	v_cvt_pk_bf16_f32 v1, v10, v11
	s_waitcnt lgkmcnt(0)
	v_cvt_pk_bf16_f32 v2, v12, v13
	v_cvt_pk_bf16_f32 v3, v14, v15
	global_store_dwordx4 v[16:17], v[0:3], off offset:16
	s_cbranch_scc1 .LBB0_643

.LBB0_826:
	v_mov_b32_e32 v213, v234
	s_add_u32 s0, s66, s90
	v_lshlrev_b32_e32 v214, 3, v213
	v_and_b32_e32 v64, 0xf8, v214
	v_ashrrev_i32_e32 v195, 5, v213
	v_lshlrev_b32_e32 v192, 1, v64
	v_add_u32_e32 v64, s47, v195
	s_addc_u32 s1, s67, 0
	v_ashrrev_i32_e32 v65, 31, v64
	v_lshl_add_u64 v[184:185], s[0:1], 0, v[192:193]
	v_mov_b64_e32 v[186:187], s[58:59]
	v_lshlrev_b64 v[224:225], 11, v[64:65]
	v_mad_i64_i32 v[66:67], s[0:1], v64, s94, v[186:187]
	v_lshl_add_u64 v[64:65], v[184:185], 0, v[224:225]
	global_load_dwordx4 v[220:223], v[64:65], off
	v_add_u32_e32 v64, 0x200, v213
	v_lshl_add_u64 v[66:67], v[66:67], 0, s[90:91]
	v_ashrrev_i32_e32 v206, 5, v64
	v_lshl_add_u64 v[66:67], v[66:67], 0, v[192:193]
	v_add_u32_e32 v64, s47, v206
	v_add_co_u32_e32 v66, vcc, s8, v66
	v_ashrrev_i32_e32 v65, 31, v64
	s_nop 0
	v_addc_co_u32_e32 v67, vcc, 0, v67, vcc
	v_lshlrev_b64 v[204:205], 11, v[64:65]
	global_load_dwordx4 v[216:219], v[66:67], off offset:2080 nt
	v_mad_i64_i32 v[66:67], s[0:1], v64, s94, v[186:187]
	v_lshl_add_u64 v[64:65], v[184:185], 0, v[204:205]
	global_load_dwordx4 v[112:115], v[64:65], off
	v_add_u32_e32 v64, 0x400, v213
	v_lshl_add_u64 v[66:67], v[66:67], 0, s[90:91]
	v_ashrrev_i32_e32 v207, 5, v64
	v_lshl_add_u64 v[66:67], v[66:67], 0, v[192:193]
	v_add_u32_e32 v64, s47, v207
	v_add_co_u32_e32 v66, vcc, s8, v66
	v_ashrrev_i32_e32 v65, 31, v64
	s_nop 0
	v_addc_co_u32_e32 v67, vcc, 0, v67, vcc
	v_lshlrev_b64 v[202:203], 11, v[64:65]
	global_load_dwordx4 v[144:147], v[66:67], off offset:2080 nt
	v_mad_i64_i32 v[66:67], s[0:1], v64, s94, v[186:187]
	v_lshl_add_u64 v[64:65], v[184:185], 0, v[202:203]
	global_load_dwordx4 v[104:107], v[64:65], off
	v_add_u32_e32 v64, 0x600, v213
	v_lshl_add_u64 v[66:67], v[66:67], 0, s[90:91]
	v_ashrrev_i32_e32 v208, 5, v64
	v_lshl_add_u64 v[66:67], v[66:67], 0, v[192:193]
	v_add_u32_e32 v64, s47, v208
	v_add_co_u32_e32 v66, vcc, s8, v66
	v_ashrrev_i32_e32 v65, 31, v64
	s_nop 0
	v_addc_co_u32_e32 v67, vcc, 0, v67, vcc
	v_lshlrev_b64 v[200:201], 11, v[64:65]
	global_load_dwordx4 v[108:111], v[66:67], off offset:2080 nt
	v_mad_i64_i32 v[66:67], s[0:1], v64, s94, v[186:187]
	v_lshl_add_u64 v[64:65], v[184:185], 0, v[200:201]
	global_load_dwordx4 v[96:99], v[64:65], off
	v_add_u32_e32 v64, 0x800, v213
	v_lshl_add_u64 v[66:67], v[66:67], 0, s[90:91]
	v_ashrrev_i32_e32 v209, 5, v64
	v_lshl_add_u64 v[66:67], v[66:67], 0, v[192:193]
	v_add_u32_e32 v64, s47, v209
	v_add_co_u32_e32 v66, vcc, s8, v66
	v_ashrrev_i32_e32 v65, 31, v64
	s_nop 0
	v_addc_co_u32_e32 v67, vcc, 0, v67, vcc
	v_lshlrev_b64 v[198:199], 11, v[64:65]
	global_load_dwordx4 v[100:103], v[66:67], off offset:2080 nt
	v_mad_i64_i32 v[66:67], s[0:1], v64, s94, v[186:187]
	v_lshl_add_u64 v[64:65], v[184:185], 0, v[198:199]
	global_load_dwordx4 v[88:91], v[64:65], off
	v_add_u32_e32 v64, 0xa00, v213
	v_lshl_add_u64 v[66:67], v[66:67], 0, s[90:91]
	v_ashrrev_i32_e32 v210, 5, v64
	v_lshl_add_u64 v[66:67], v[66:67], 0, v[192:193]
	v_add_u32_e32 v64, s47, v210
	v_add_co_u32_e32 v66, vcc, s8, v66
	v_ashrrev_i32_e32 v65, 31, v64
	s_nop 0
	v_addc_co_u32_e32 v67, vcc, 0, v67, vcc
	v_lshlrev_b64 v[196:197], 11, v[64:65]
	global_load_dwordx4 v[92:95], v[66:67], off offset:2080 nt
	v_mad_i64_i32 v[66:67], s[0:1], v64, s94, v[186:187]
	v_lshl_add_u64 v[64:65], v[184:185], 0, v[196:197]
	v_lshl_add_u64 v[66:67], v[66:67], 0, s[90:91]
	global_load_dwordx4 v[80:83], v[64:65], off
	v_add_u32_e32 v64, 0xc00, v213
	v_lshl_add_u64 v[66:67], v[66:67], 0, v[192:193]
	v_ashrrev_i32_e32 v211, 5, v64
	v_add_co_u32_e32 v66, vcc, s8, v66
	v_add_u32_e32 v64, s47, v211
	s_nop 0
	v_addc_co_u32_e32 v67, vcc, 0, v67, vcc
	v_ashrrev_i32_e32 v65, 31, v64
	global_load_dwordx4 v[84:87], v[66:67], off offset:2080 nt
	v_mad_i64_i32 v[66:67], s[0:1], v64, s94, v[186:187]
	v_lshlrev_b64 v[190:191], 11, v[64:65]
	v_lshl_add_u64 v[66:67], v[66:67], 0, s[90:91]
	v_lshl_add_u64 v[64:65], v[184:185], 0, v[190:191]
	v_lshl_add_u64 v[66:67], v[66:67], 0, v[192:193]
	global_load_dwordx4 v[72:75], v[64:65], off
	v_add_u32_e32 v64, 0xe00, v213
	v_add_co_u32_e32 v66, vcc, s8, v66
	v_ashrrev_i32_e32 v212, 5, v64
	s_nop 0
	v_addc_co_u32_e32 v67, vcc, 0, v67, vcc
	v_add_u32_e32 v64, s47, v212
	global_load_dwordx4 v[76:79], v[66:67], off offset:2080 nt
	v_mad_i64_i32 v[66:67], s[0:1], v64, s94, v[186:187]
	v_lshl_add_u64 v[66:67], v[66:67], 0, s[90:91]
	v_ashrrev_i32_e32 v65, 31, v64
	v_lshl_add_u64 v[66:67], v[66:67], 0, v[192:193]
	v_add_co_u32_e32 v66, vcc, s8, v66
	v_lshlrev_b64 v[188:189], 11, v[64:65]
	s_nop 0
	v_addc_co_u32_e32 v67, vcc, 0, v67, vcc
	v_lshl_add_u64 v[64:65], v[184:185], 0, v[188:189]
	global_load_dwordx4 v[68:71], v[66:67], off offset:2080 nt
	v_lshrrev_b32_e32 v230, 3, v213
	global_load_dwordx4 v[64:67], v[64:65], off
	v_lshrrev_b32_e32 v227, 1, v213
	v_and_b32_e32 v230, 48, v230
	s_movk_i32 s0, 0xf8
	v_and_b32_e32 v215, 15, v213
	v_bfe_u32 v226, v213, 4, 2
	v_and_b32_e32 v227, 0x60, v227
	v_bitop3_b32 v214, v214, v230, s0 bitop3:0x6c
	v_or_b32_e32 v228, v227, v215
	v_lshlrev_b32_e32 v229, 4, v226
	v_lshl_add_u32 v214, v214, 2, 0
	v_lshlrev_b32_e32 v213, 8, v213
	v_bitop3_b32 v215, v227, v229, v215 bitop3:0x36
	v_and_b32_e32 v213, 0xffff0000, v213
	v_lshlrev_b32_e32 v215, 2, v215
	v_lshl_or_b32 v226, v226, 12, v213
	v_add3_u32 v213, 0, v215, v226
	s_barrier
	ds_write2st64_b32 v213, v148, v149 offset1:4
	ds_write2st64_b32 v213, v150, v151 offset0:8 offset1:12
	v_bitop3_b32 v148, v228, v229, 16 bitop3:0x36
	v_lshlrev_b32_e32 v148, 2, v148
	v_add3_u32 v148, 0, v148, v226
	s_movk_i32 s0, 0x80
	ds_write2st64_b32 v148, v116, v117 offset1:4
	ds_write2st64_b32 v148, v118, v119 offset0:8 offset1:12
	ds_write2st64_b32 v213, v120, v121 offset0:64 offset1:68
	ds_write2st64_b32 v213, v122, v123 offset0:72 offset1:76
	ds_write2st64_b32 v148, v124, v125 offset0:64 offset1:68
	ds_write2st64_b32 v148, v126, v127 offset0:72 offset1:76
	ds_write2st64_b32 v213, v128, v129 offset0:128 offset1:132
	ds_write2st64_b32 v213, v130, v131 offset0:136 offset1:140
	ds_write2st64_b32 v148, v132, v133 offset0:128 offset1:132
	ds_write2st64_b32 v148, v134, v135 offset0:136 offset1:140
	ds_write2st64_b32 v213, v136, v137 offset0:192 offset1:196
	ds_write2st64_b32 v213, v138, v139 offset0:200 offset1:204
	ds_write2st64_b32 v148, v140, v141 offset0:192 offset1:196
	ds_write2st64_b32 v148, v142, v143 offset0:200 offset1:204
	v_bitop3_b32 v116, v228, v229, s0 bitop3:0x36
	v_lshlrev_b32_e32 v116, 2, v116
	s_movk_i32 s0, 0x90
	v_add3_u32 v136, 0, v116, v226
	v_bitop3_b32 v116, v228, v229, s0 bitop3:0x36
	v_lshlrev_b32_e32 v116, 2, v116
	v_add3_u32 v137, 0, v116, v226
	s_waitcnt vmcnt(0)
	v_lshlrev_b32_e32 v118, 16, v216
	v_lshl_add_u64 v[116:117], s[66:67], 0, v[224:225]
	v_and_b32_e32 v119, 0xffff0000, v216
	v_lshl_add_u64 v[124:125], v[116:117], 0, s[90:91]
	v_mul_f32_e32 v116, 0xbfb8aa3b, v118
	v_exp_f32_e32 v116, v116
	v_mul_f32_e32 v117, 0xbfb8aa3b, v119
	v_exp_f32_e32 v117, v117
	v_lshlrev_b32_e32 v120, 16, v217
	v_add_f32_e32 v116, 1.0, v116
	v_rcp_f32_e32 v138, v116
	v_add_f32_e32 v116, 1.0, v117
	v_and_b32_e32 v121, 0xffff0000, v217
	v_lshlrev_b32_e32 v129, 16, v218
	v_rcp_f32_e32 v139, v116
	v_mul_f32_e32 v116, 0xbfb8aa3b, v120
	v_and_b32_e32 v141, 0xffff0000, v218
	v_exp_f32_e32 v140, v116
	v_mul_f32_e32 v116, 0xbfb8aa3b, v121
	v_mul_f32_e32 v129, 0xbfb8aa3b, v129
	v_exp_f32_e32 v142, v116
	v_exp_f32_e32 v129, v129
	v_mul_f32_e32 v141, 0xbfb8aa3b, v141
	v_exp_f32_e32 v150, v141
	v_lshlrev_b32_e32 v143, 16, v219
	v_and_b32_e32 v149, 0xffff0000, v219
	v_add_f32_e32 v142, 1.0, v142
	v_add_f32_e32 v129, 1.0, v129
	v_mul_f32_e32 v143, 0xbfb8aa3b, v143
	v_rcp_f32_e32 v141, v142
	v_rcp_f32_e32 v142, v129
	v_add_f32_e32 v129, 1.0, v150
	v_exp_f32_e32 v150, v143
	v_mul_f32_e32 v143, 0xbfb8aa3b, v149
	v_exp_f32_e32 v149, v143
	v_lshl_add_u32 v128, v195, 10, v214
	v_rcp_f32_e32 v143, v129
	v_add_f32_e32 v129, 1.0, v150
	ds_write2st64_b32 v136, v180, v181 offset1:4
	ds_write2st64_b32 v136, v182, v183 offset0:8 offset1:12
	ds_write2st64_b32 v137, v152, v153 offset1:4
	ds_write2st64_b32 v137, v154, v155 offset0:8 offset1:12
	ds_write2st64_b32 v136, v156, v157 offset0:64 offset1:68
	ds_write2st64_b32 v136, v158, v159 offset0:72 offset1:76
	ds_write2st64_b32 v137, v160, v161 offset0:64 offset1:68
	ds_write2st64_b32 v137, v162, v163 offset0:72 offset1:76
	ds_write2st64_b32 v136, v164, v165 offset0:128 offset1:132
	ds_write2st64_b32 v136, v166, v167 offset0:136 offset1:140
	ds_write2st64_b32 v137, v168, v169 offset0:128 offset1:132
	ds_write2st64_b32 v137, v170, v171 offset0:136 offset1:140
	ds_write2st64_b32 v136, v172, v173 offset0:192 offset1:196
	ds_write2st64_b32 v136, v174, v175 offset0:200 offset1:204
	ds_write2st64_b32 v137, v176, v177 offset0:192 offset1:196
	ds_write2st64_b32 v137, v178, v179 offset0:200 offset1:204
	s_waitcnt lgkmcnt(0)
	s_barrier
	ds_read_b128 v[116:119], v128
	ds_read_b128 v[120:123], v128 offset:16
	v_add_f32_e32 v140, 1.0, v140
	v_rcp_f32_e32 v150, v129
	v_add_f32_e32 v129, 1.0, v149
	v_rcp_f32_e32 v140, v140
	v_rcp_f32_e32 v151, v129
	v_lshlrev_b32_e32 v126, 16, v220
	v_and_b32_e32 v127, 0xffff0000, v220
	v_lshlrev_b32_e32 v130, 16, v221
	v_and_b32_e32 v131, 0xffff0000, v221
	v_lshlrev_b32_e32 v132, 16, v222
	v_and_b32_e32 v133, 0xffff0000, v222
	v_lshlrev_b32_e32 v134, 16, v223
	v_and_b32_e32 v135, 0xffff0000, v223
	s_waitcnt lgkmcnt(1)
	v_pk_fma_f32 v[116:117], v[138:139], v[116:117], v[126:127]
	v_pk_fma_f32 v[118:119], v[140:141], v[118:119], v[130:131]
	s_waitcnt lgkmcnt(0)
	v_pk_fma_f32 v[120:121], v[142:143], v[120:121], v[132:133]
	v_pk_fma_f32 v[122:123], v[150:151], v[122:123], v[134:135]
	v_lshl_add_u64 v[124:125], v[124:125], 0, v[192:193]
	v_cvt_pk_bf16_f32 v116, v116, v117
	v_cvt_pk_bf16_f32 v117, v118, v119
	v_cvt_pk_bf16_f32 v118, v120, v121
	v_cvt_pk_bf16_f32 v119, v122, v123
	global_store_dwordx4 v[124:125], v[116:119], off
	v_lshlrev_b32_e32 v122, 16, v112
	v_and_b32_e32 v123, 0xffff0000, v112
	v_lshlrev_b32_e32 v118, 16, v144
	v_and_b32_e32 v119, 0xffff0000, v144
	v_mul_f32_e32 v112, 0xbfb8aa3b, v118
	v_lshlrev_b32_e32 v124, 16, v113
	v_and_b32_e32 v125, 0xffff0000, v113
	v_exp_f32_e32 v112, v112
	v_mul_f32_e32 v113, 0xbfb8aa3b, v119
	v_exp_f32_e32 v113, v113
	v_lshlrev_b32_e32 v134, 16, v145
	v_add_f32_e32 v112, 1.0, v112
	v_rcp_f32_e32 v132, v112
	v_add_f32_e32 v112, 1.0, v113
	v_and_b32_e32 v135, 0xffff0000, v145
	v_lshlrev_b32_e32 v138, 16, v146
	v_and_b32_e32 v139, 0xffff0000, v146
	v_lshlrev_b32_e32 v140, 16, v147
	v_and_b32_e32 v141, 0xffff0000, v147
	v_rcp_f32_e32 v133, v112
	v_mul_f32_e32 v112, 0xbfb8aa3b, v134
	v_exp_f32_e32 v134, v112
	v_mul_f32_e32 v112, 0xbfb8aa3b, v135
	v_mul_f32_e32 v138, 0xbfb8aa3b, v138
	v_mul_f32_e32 v139, 0xbfb8aa3b, v139
	v_mul_f32_e32 v140, 0xbfb8aa3b, v140
	v_mul_f32_e32 v141, 0xbfb8aa3b, v141
	v_exp_f32_e32 v135, v112
	v_exp_f32_e32 v138, v138
	v_exp_f32_e32 v139, v139
	v_exp_f32_e32 v140, v140
	v_exp_f32_e32 v141, v141
	v_lshl_add_u32 v129, v206, 10, v214
	v_lshl_add_u64 v[116:117], s[66:67], 0, v[204:205]
	v_lshl_add_u64 v[120:121], v[116:117], 0, s[90:91]
	v_lshlrev_b32_e32 v126, 16, v114
	v_and_b32_e32 v127, 0xffff0000, v114
	v_lshlrev_b32_e32 v130, 16, v115
	v_and_b32_e32 v131, 0xffff0000, v115
	ds_read_b128 v[112:115], v129
	ds_read_b128 v[116:119], v129 offset:16
	v_add_f32_e32 v134, 1.0, v134
	v_add_f32_e32 v135, 1.0, v135
	v_add_f32_e32 v138, 1.0, v138
	v_add_f32_e32 v139, 1.0, v139
	v_add_f32_e32 v140, 1.0, v140
	v_add_f32_e32 v141, 1.0, v141
	v_rcp_f32_e32 v134, v134
	v_rcp_f32_e32 v135, v135
	v_rcp_f32_e32 v138, v138
	v_rcp_f32_e32 v139, v139
	v_rcp_f32_e32 v140, v140
	v_rcp_f32_e32 v141, v141
	s_waitcnt lgkmcnt(1)
	v_pk_fma_f32 v[112:113], v[132:133], v[112:113], v[122:123]
	v_pk_fma_f32 v[114:115], v[134:135], v[114:115], v[124:125]
	s_waitcnt lgkmcnt(0)
	v_pk_fma_f32 v[116:117], v[138:139], v[116:117], v[126:127]
	v_pk_fma_f32 v[118:119], v[140:141], v[118:119], v[130:131]
	v_lshl_add_u64 v[120:121], v[120:121], 0, v[192:193]
	v_cvt_pk_bf16_f32 v112, v112, v113
	v_cvt_pk_bf16_f32 v113, v114, v115
	v_cvt_pk_bf16_f32 v114, v116, v117
	v_cvt_pk_bf16_f32 v115, v118, v119
	global_store_dwordx4 v[120:121], v[112:115], off
	v_lshlrev_b32_e32 v121, 16, v108
	v_and_b32_e32 v122, 0xffff0000, v108
	v_lshlrev_b32_e32 v114, 16, v104
	v_and_b32_e32 v115, 0xffff0000, v104
	v_mul_f32_e32 v104, 0xbfb8aa3b, v121
	v_lshlrev_b32_e32 v116, 16, v105
	v_and_b32_e32 v117, 0xffff0000, v105
	v_exp_f32_e32 v104, v104
	v_mul_f32_e32 v105, 0xbfb8aa3b, v122
	v_exp_f32_e32 v105, v105
	v_lshlrev_b32_e32 v124, 16, v109
	v_add_f32_e32 v104, 1.0, v104
	v_lshlrev_b32_e32 v131, 16, v111
	v_rcp_f32_e32 v122, v104
	v_add_f32_e32 v104, 1.0, v105
	v_and_b32_e32 v125, 0xffff0000, v109
	v_lshlrev_b32_e32 v126, 16, v110
	v_and_b32_e32 v127, 0xffff0000, v110
	v_and_b32_e32 v132, 0xffff0000, v111
	v_rcp_f32_e32 v123, v104
	v_mul_f32_e32 v104, 0xbfb8aa3b, v124
	v_mul_f32_e32 v131, 0xbfb8aa3b, v131
	v_exp_f32_e32 v124, v104
	v_mul_f32_e32 v104, 0xbfb8aa3b, v125
	v_mul_f32_e32 v126, 0xbfb8aa3b, v126
	v_mul_f32_e32 v127, 0xbfb8aa3b, v127
	v_exp_f32_e32 v131, v131
	v_mul_f32_e32 v132, 0xbfb8aa3b, v132
	v_exp_f32_e32 v125, v104
	v_exp_f32_e32 v126, v126
	v_exp_f32_e32 v127, v127
	v_exp_f32_e32 v133, v132
	v_lshl_add_u32 v130, v207, 10, v214
	v_lshl_add_u64 v[108:109], s[66:67], 0, v[202:203]
	v_add_f32_e32 v131, 1.0, v131
	v_lshl_add_u64 v[112:113], v[108:109], 0, s[90:91]
	v_lshlrev_b32_e32 v118, 16, v106
	v_and_b32_e32 v119, 0xffff0000, v106
	v_lshlrev_b32_e32 v120, 16, v107
	v_and_b32_e32 v121, 0xffff0000, v107
	ds_read_b128 v[104:107], v130
	ds_read_b128 v[108:111], v130 offset:16
	v_add_f32_e32 v124, 1.0, v124
	v_add_f32_e32 v125, 1.0, v125
	v_add_f32_e32 v126, 1.0, v126
	v_add_f32_e32 v127, 1.0, v127
	v_rcp_f32_e32 v132, v131
	v_add_f32_e32 v131, 1.0, v133
	v_rcp_f32_e32 v124, v124
	v_rcp_f32_e32 v125, v125
	v_rcp_f32_e32 v126, v126
	v_rcp_f32_e32 v127, v127
	v_rcp_f32_e32 v133, v131
	s_waitcnt lgkmcnt(1)
	v_pk_fma_f32 v[104:105], v[122:123], v[104:105], v[114:115]
	v_pk_fma_f32 v[106:107], v[124:125], v[106:107], v[116:117]
	s_waitcnt lgkmcnt(0)
	v_pk_fma_f32 v[108:109], v[126:127], v[108:109], v[118:119]
	v_pk_fma_f32 v[110:111], v[132:133], v[110:111], v[120:121]
	v_lshl_add_u64 v[112:113], v[112:113], 0, v[192:193]
	v_cvt_pk_bf16_f32 v104, v104, v105
	v_cvt_pk_bf16_f32 v105, v106, v107
	v_cvt_pk_bf16_f32 v106, v108, v109
	v_cvt_pk_bf16_f32 v107, v110, v111
	global_store_dwordx4 v[112:113], v[104:107], off
	v_lshlrev_b32_e32 v113, 16, v100
	v_and_b32_e32 v114, 0xffff0000, v100
	v_lshlrev_b32_e32 v106, 16, v96
	v_and_b32_e32 v107, 0xffff0000, v96
	v_mul_f32_e32 v96, 0xbfb8aa3b, v113
	v_lshlrev_b32_e32 v108, 16, v97
	v_and_b32_e32 v109, 0xffff0000, v97
	v_exp_f32_e32 v96, v96
	v_mul_f32_e32 v97, 0xbfb8aa3b, v114
	v_exp_f32_e32 v97, v97
	v_lshlrev_b32_e32 v116, 16, v101
	v_add_f32_e32 v96, 1.0, v96
	v_rcp_f32_e32 v114, v96
	v_add_f32_e32 v96, 1.0, v97
	v_and_b32_e32 v117, 0xffff0000, v101
	v_lshlrev_b32_e32 v118, 16, v102
	v_and_b32_e32 v119, 0xffff0000, v102
	v_lshlrev_b32_e32 v120, 16, v103
	v_and_b32_e32 v121, 0xffff0000, v103
	v_rcp_f32_e32 v115, v96
	v_mul_f32_e32 v96, 0xbfb8aa3b, v116
	v_exp_f32_e32 v116, v96
	v_mul_f32_e32 v96, 0xbfb8aa3b, v117
	v_mul_f32_e32 v118, 0xbfb8aa3b, v118
	v_mul_f32_e32 v119, 0xbfb8aa3b, v119
	v_mul_f32_e32 v120, 0xbfb8aa3b, v120
	v_mul_f32_e32 v121, 0xbfb8aa3b, v121
	v_exp_f32_e32 v117, v96
	v_exp_f32_e32 v118, v118
	v_exp_f32_e32 v119, v119
	v_exp_f32_e32 v120, v120
	v_exp_f32_e32 v121, v121
	v_lshl_add_u32 v131, v208, 10, v214
	v_lshl_add_u64 v[100:101], s[66:67], 0, v[200:201]
	v_lshl_add_u64 v[104:105], v[100:101], 0, s[90:91]
	v_lshlrev_b32_e32 v110, 16, v98
	v_and_b32_e32 v111, 0xffff0000, v98
	v_lshlrev_b32_e32 v112, 16, v99
	v_and_b32_e32 v113, 0xffff0000, v99
	ds_read_b128 v[96:99], v131
	ds_read_b128 v[100:103], v131 offset:16
	v_add_f32_e32 v116, 1.0, v116
	v_add_f32_e32 v117, 1.0, v117
	v_add_f32_e32 v118, 1.0, v118
	v_add_f32_e32 v119, 1.0, v119
	v_add_f32_e32 v120, 1.0, v120
	v_add_f32_e32 v121, 1.0, v121
	v_rcp_f32_e32 v116, v116
	v_rcp_f32_e32 v117, v117
	v_rcp_f32_e32 v118, v118
	v_rcp_f32_e32 v119, v119
	v_rcp_f32_e32 v120, v120
	v_rcp_f32_e32 v121, v121
	s_waitcnt lgkmcnt(1)
	v_pk_fma_f32 v[96:97], v[114:115], v[96:97], v[106:107]
	v_pk_fma_f32 v[98:99], v[116:117], v[98:99], v[108:109]
	s_waitcnt lgkmcnt(0)
	v_pk_fma_f32 v[100:101], v[118:119], v[100:101], v[110:111]
	v_pk_fma_f32 v[102:103], v[120:121], v[102:103], v[112:113]
	v_lshl_add_u64 v[104:105], v[104:105], 0, v[192:193]
	v_cvt_pk_bf16_f32 v96, v96, v97
	v_cvt_pk_bf16_f32 v97, v98, v99
	v_cvt_pk_bf16_f32 v98, v100, v101
	v_cvt_pk_bf16_f32 v99, v102, v103
	global_store_dwordx4 v[104:105], v[96:99], off
	v_lshlrev_b32_e32 v105, 16, v92
	v_and_b32_e32 v106, 0xffff0000, v92
	v_lshlrev_b32_e32 v98, 16, v88
	v_and_b32_e32 v99, 0xffff0000, v88
	v_mul_f32_e32 v88, 0xbfb8aa3b, v105
	v_lshlrev_b32_e32 v100, 16, v89
	v_and_b32_e32 v101, 0xffff0000, v89
	v_exp_f32_e32 v88, v88
	v_mul_f32_e32 v89, 0xbfb8aa3b, v106
	v_exp_f32_e32 v89, v89
	v_lshlrev_b32_e32 v108, 16, v93
	v_add_f32_e32 v88, 1.0, v88
	v_rcp_f32_e32 v106, v88
	v_add_f32_e32 v88, 1.0, v89
	v_and_b32_e32 v109, 0xffff0000, v93
	v_lshlrev_b32_e32 v110, 16, v94
	v_and_b32_e32 v111, 0xffff0000, v94
	v_lshlrev_b32_e32 v112, 16, v95
	v_and_b32_e32 v113, 0xffff0000, v95
	v_rcp_f32_e32 v107, v88
	v_mul_f32_e32 v88, 0xbfb8aa3b, v108
	v_exp_f32_e32 v108, v88
	v_mul_f32_e32 v88, 0xbfb8aa3b, v109
	v_mul_f32_e32 v110, 0xbfb8aa3b, v110
	v_mul_f32_e32 v111, 0xbfb8aa3b, v111
	v_mul_f32_e32 v112, 0xbfb8aa3b, v112
	v_mul_f32_e32 v113, 0xbfb8aa3b, v113
	v_exp_f32_e32 v109, v88
	v_exp_f32_e32 v110, v110
	v_exp_f32_e32 v111, v111
	v_exp_f32_e32 v112, v112
	v_exp_f32_e32 v113, v113
	v_lshl_add_u32 v132, v209, 10, v214
	v_lshl_add_u64 v[92:93], s[66:67], 0, v[198:199]
	v_lshl_add_u64 v[96:97], v[92:93], 0, s[90:91]
	v_lshlrev_b32_e32 v102, 16, v90
	v_and_b32_e32 v103, 0xffff0000, v90
	v_lshlrev_b32_e32 v104, 16, v91
	v_and_b32_e32 v105, 0xffff0000, v91
	ds_read_b128 v[88:91], v132
	ds_read_b128 v[92:95], v132 offset:16
	v_add_f32_e32 v108, 1.0, v108
	v_add_f32_e32 v109, 1.0, v109
	v_add_f32_e32 v110, 1.0, v110
	v_add_f32_e32 v111, 1.0, v111
	v_add_f32_e32 v112, 1.0, v112
	v_add_f32_e32 v113, 1.0, v113
	v_rcp_f32_e32 v108, v108
	v_rcp_f32_e32 v109, v109
	v_rcp_f32_e32 v110, v110
	v_rcp_f32_e32 v111, v111
	v_rcp_f32_e32 v112, v112
	v_rcp_f32_e32 v113, v113
	s_waitcnt lgkmcnt(1)
	v_pk_fma_f32 v[88:89], v[106:107], v[88:89], v[98:99]
	v_pk_fma_f32 v[90:91], v[108:109], v[90:91], v[100:101]
	s_waitcnt lgkmcnt(0)
	v_pk_fma_f32 v[92:93], v[110:111], v[92:93], v[102:103]
	v_pk_fma_f32 v[94:95], v[112:113], v[94:95], v[104:105]
	v_lshl_add_u64 v[96:97], v[96:97], 0, v[192:193]
	v_cvt_pk_bf16_f32 v88, v88, v89
	v_cvt_pk_bf16_f32 v89, v90, v91
	v_cvt_pk_bf16_f32 v90, v92, v93
	v_cvt_pk_bf16_f32 v91, v94, v95
	global_store_dwordx4 v[96:97], v[88:91], off
	v_lshlrev_b32_e32 v97, 16, v84
	v_and_b32_e32 v98, 0xffff0000, v84
	v_lshlrev_b32_e32 v90, 16, v80
	v_and_b32_e32 v91, 0xffff0000, v80
	v_mul_f32_e32 v80, 0xbfb8aa3b, v97
	v_lshlrev_b32_e32 v92, 16, v81
	v_and_b32_e32 v93, 0xffff0000, v81
	v_exp_f32_e32 v80, v80
	v_mul_f32_e32 v81, 0xbfb8aa3b, v98
	v_exp_f32_e32 v81, v81
	v_lshlrev_b32_e32 v100, 16, v85
	v_add_f32_e32 v80, 1.0, v80
	v_rcp_f32_e32 v98, v80
	v_add_f32_e32 v80, 1.0, v81
	v_and_b32_e32 v101, 0xffff0000, v85
	v_lshlrev_b32_e32 v102, 16, v86
	v_and_b32_e32 v103, 0xffff0000, v86
	v_lshlrev_b32_e32 v104, 16, v87
	v_and_b32_e32 v105, 0xffff0000, v87
	v_rcp_f32_e32 v99, v80
	v_mul_f32_e32 v80, 0xbfb8aa3b, v100
	v_exp_f32_e32 v100, v80
	v_mul_f32_e32 v80, 0xbfb8aa3b, v101
	v_mul_f32_e32 v102, 0xbfb8aa3b, v102
	v_mul_f32_e32 v103, 0xbfb8aa3b, v103
	v_mul_f32_e32 v104, 0xbfb8aa3b, v104
	v_mul_f32_e32 v105, 0xbfb8aa3b, v105
	v_exp_f32_e32 v101, v80
	v_exp_f32_e32 v102, v102
	v_exp_f32_e32 v103, v103
	v_exp_f32_e32 v104, v104
	v_exp_f32_e32 v105, v105
	v_lshl_add_u32 v133, v210, 10, v214
	v_lshl_add_u64 v[84:85], s[66:67], 0, v[196:197]
	v_lshl_add_u64 v[88:89], v[84:85], 0, s[90:91]
	v_lshlrev_b32_e32 v94, 16, v82
	v_and_b32_e32 v95, 0xffff0000, v82
	v_lshlrev_b32_e32 v96, 16, v83
	v_and_b32_e32 v97, 0xffff0000, v83
	ds_read_b128 v[80:83], v133
	ds_read_b128 v[84:87], v133 offset:16
	v_add_f32_e32 v100, 1.0, v100
	v_add_f32_e32 v101, 1.0, v101
	v_add_f32_e32 v102, 1.0, v102
	v_add_f32_e32 v103, 1.0, v103
	v_add_f32_e32 v104, 1.0, v104
	v_add_f32_e32 v105, 1.0, v105
	v_rcp_f32_e32 v100, v100
	v_rcp_f32_e32 v101, v101
	v_rcp_f32_e32 v102, v102
	v_rcp_f32_e32 v103, v103
	v_rcp_f32_e32 v104, v104
	v_rcp_f32_e32 v105, v105
	s_waitcnt lgkmcnt(1)
	v_pk_fma_f32 v[80:81], v[98:99], v[80:81], v[90:91]
	v_pk_fma_f32 v[82:83], v[100:101], v[82:83], v[92:93]
	s_waitcnt lgkmcnt(0)
	v_pk_fma_f32 v[84:85], v[102:103], v[84:85], v[94:95]
	v_pk_fma_f32 v[86:87], v[104:105], v[86:87], v[96:97]
	v_lshl_add_u64 v[88:89], v[88:89], 0, v[192:193]
	v_cvt_pk_bf16_f32 v80, v80, v81
	v_cvt_pk_bf16_f32 v81, v82, v83
	v_cvt_pk_bf16_f32 v82, v84, v85
	v_cvt_pk_bf16_f32 v83, v86, v87
	global_store_dwordx4 v[88:89], v[80:83], off
	v_lshlrev_b32_e32 v89, 16, v76
	v_and_b32_e32 v90, 0xffff0000, v76
	v_lshlrev_b32_e32 v82, 16, v72
	v_and_b32_e32 v83, 0xffff0000, v72
	v_mul_f32_e32 v72, 0xbfb8aa3b, v89
	v_lshlrev_b32_e32 v84, 16, v73
	v_and_b32_e32 v85, 0xffff0000, v73
	v_exp_f32_e32 v72, v72
	v_mul_f32_e32 v73, 0xbfb8aa3b, v90
	v_exp_f32_e32 v73, v73
	v_lshlrev_b32_e32 v92, 16, v77
	v_add_f32_e32 v72, 1.0, v72
	v_rcp_f32_e32 v90, v72
	v_add_f32_e32 v72, 1.0, v73
	v_and_b32_e32 v93, 0xffff0000, v77
	v_lshlrev_b32_e32 v94, 16, v78
	v_and_b32_e32 v95, 0xffff0000, v78
	v_lshlrev_b32_e32 v96, 16, v79
	v_and_b32_e32 v97, 0xffff0000, v79
	v_rcp_f32_e32 v91, v72
	v_mul_f32_e32 v72, 0xbfb8aa3b, v92
	v_exp_f32_e32 v92, v72
	v_mul_f32_e32 v72, 0xbfb8aa3b, v93
	v_mul_f32_e32 v94, 0xbfb8aa3b, v94
	v_mul_f32_e32 v95, 0xbfb8aa3b, v95
	v_mul_f32_e32 v96, 0xbfb8aa3b, v96
	v_mul_f32_e32 v97, 0xbfb8aa3b, v97
	v_exp_f32_e32 v93, v72
	v_exp_f32_e32 v94, v94
	v_exp_f32_e32 v95, v95
	v_exp_f32_e32 v96, v96
	v_exp_f32_e32 v97, v97
	v_lshl_add_u32 v134, v211, 10, v214
	v_lshl_add_u64 v[76:77], s[66:67], 0, v[190:191]
	v_lshl_add_u64 v[80:81], v[76:77], 0, s[90:91]
	v_lshlrev_b32_e32 v86, 16, v74
	v_and_b32_e32 v87, 0xffff0000, v74
	v_lshlrev_b32_e32 v88, 16, v75
	v_and_b32_e32 v89, 0xffff0000, v75
	ds_read_b128 v[72:75], v134
	ds_read_b128 v[76:79], v134 offset:16
	v_add_f32_e32 v92, 1.0, v92
	v_add_f32_e32 v93, 1.0, v93
	v_add_f32_e32 v94, 1.0, v94
	v_add_f32_e32 v95, 1.0, v95
	v_add_f32_e32 v96, 1.0, v96
	v_add_f32_e32 v97, 1.0, v97
	v_rcp_f32_e32 v92, v92
	v_rcp_f32_e32 v93, v93
	v_rcp_f32_e32 v94, v94
	v_rcp_f32_e32 v95, v95
	v_rcp_f32_e32 v96, v96
	v_rcp_f32_e32 v97, v97
	s_waitcnt lgkmcnt(1)
	v_pk_fma_f32 v[72:73], v[90:91], v[72:73], v[82:83]
	v_pk_fma_f32 v[74:75], v[92:93], v[74:75], v[84:85]
	s_waitcnt lgkmcnt(0)
	v_pk_fma_f32 v[76:77], v[94:95], v[76:77], v[86:87]
	v_pk_fma_f32 v[78:79], v[96:97], v[78:79], v[88:89]
	v_lshl_add_u64 v[80:81], v[80:81], 0, v[192:193]
	v_cvt_pk_bf16_f32 v72, v72, v73
	v_cvt_pk_bf16_f32 v73, v74, v75
	v_cvt_pk_bf16_f32 v74, v76, v77
	v_cvt_pk_bf16_f32 v75, v78, v79
	global_store_dwordx4 v[80:81], v[72:75], off
	v_lshlrev_b32_e32 v81, 16, v68
	v_and_b32_e32 v82, 0xffff0000, v68
	v_lshlrev_b32_e32 v74, 16, v64
	v_and_b32_e32 v75, 0xffff0000, v64
	v_mul_f32_e32 v64, 0xbfb8aa3b, v81
	v_lshlrev_b32_e32 v76, 16, v65
	v_and_b32_e32 v77, 0xffff0000, v65
	v_exp_f32_e32 v64, v64
	v_mul_f32_e32 v65, 0xbfb8aa3b, v82
	v_exp_f32_e32 v65, v65
	v_lshlrev_b32_e32 v84, 16, v69
	v_add_f32_e32 v64, 1.0, v64
	v_rcp_f32_e32 v82, v64
	v_add_f32_e32 v64, 1.0, v65
	v_and_b32_e32 v85, 0xffff0000, v69
	v_lshlrev_b32_e32 v86, 16, v70
	v_and_b32_e32 v87, 0xffff0000, v70
	v_lshlrev_b32_e32 v88, 16, v71
	v_and_b32_e32 v89, 0xffff0000, v71
	v_rcp_f32_e32 v83, v64
	v_mul_f32_e32 v64, 0xbfb8aa3b, v84
	v_exp_f32_e32 v84, v64
	v_mul_f32_e32 v64, 0xbfb8aa3b, v85
	v_mul_f32_e32 v86, 0xbfb8aa3b, v86
	v_mul_f32_e32 v87, 0xbfb8aa3b, v87
	v_mul_f32_e32 v88, 0xbfb8aa3b, v88
	v_mul_f32_e32 v89, 0xbfb8aa3b, v89
	v_exp_f32_e32 v85, v64
	v_exp_f32_e32 v86, v86
	v_exp_f32_e32 v87, v87
	v_exp_f32_e32 v88, v88
	v_exp_f32_e32 v89, v89
	v_lshl_add_u32 v135, v212, 10, v214
	v_lshl_add_u64 v[68:69], s[66:67], 0, v[188:189]
	v_lshl_add_u64 v[72:73], v[68:69], 0, s[90:91]
	v_lshlrev_b32_e32 v78, 16, v66
	v_and_b32_e32 v79, 0xffff0000, v66
	v_lshlrev_b32_e32 v80, 16, v67
	v_and_b32_e32 v81, 0xffff0000, v67
	ds_read_b128 v[64:67], v135
	ds_read_b128 v[68:71], v135 offset:16
	v_add_f32_e32 v84, 1.0, v84
	v_add_f32_e32 v85, 1.0, v85
	v_add_f32_e32 v86, 1.0, v86
	v_add_f32_e32 v87, 1.0, v87
	v_add_f32_e32 v88, 1.0, v88
	v_add_f32_e32 v89, 1.0, v89
	v_rcp_f32_e32 v84, v84
	v_rcp_f32_e32 v85, v85
	v_rcp_f32_e32 v86, v86
	v_rcp_f32_e32 v87, v87
	v_rcp_f32_e32 v88, v88
	v_rcp_f32_e32 v89, v89
	s_waitcnt lgkmcnt(1)
	v_pk_fma_f32 v[64:65], v[82:83], v[64:65], v[74:75]
	v_pk_fma_f32 v[66:67], v[84:85], v[66:67], v[76:77]
	s_waitcnt lgkmcnt(0)
	v_pk_fma_f32 v[68:69], v[86:87], v[68:69], v[78:79]
	v_pk_fma_f32 v[70:71], v[88:89], v[70:71], v[80:81]
	v_lshl_add_u64 v[72:73], v[72:73], 0, v[192:193]
	v_cvt_pk_bf16_f32 v64, v64, v65
	v_cvt_pk_bf16_f32 v65, v66, v67
	v_cvt_pk_bf16_f32 v66, v68, v69
	v_cvt_pk_bf16_f32 v67, v70, v71
	global_store_dwordx4 v[72:73], v[64:67], off
	s_nop 1
	v_add_u32_e32 v64, s46, v195
	v_mad_i64_i32 v[66:67], s[0:1], v64, s94, v[186:187]
	v_ashrrev_i32_e32 v65, 31, v64
	v_lshl_add_u64 v[66:67], v[66:67], 0, s[90:91]
	v_lshl_add_u64 v[66:67], v[66:67], 0, v[192:193]
	v_lshlrev_b64 v[146:147], 11, v[64:65]
	v_add_co_u32_e32 v66, vcc, s8, v66
	v_lshl_add_u64 v[64:65], v[184:185], 0, v[146:147]
	s_nop 0
	v_addc_co_u32_e32 v67, vcc, 0, v67, vcc
	global_load_dwordx4 v[142:145], v[64:65], off
	v_add_u32_e32 v64, s46, v206
	global_load_dwordx4 v[138:141], v[66:67], off offset:2080 nt
	v_mad_i64_i32 v[66:67], s[0:1], v64, s94, v[186:187]
	v_ashrrev_i32_e32 v65, 31, v64
	v_lshl_add_u64 v[66:67], v[66:67], 0, s[90:91]
	v_lshl_add_u64 v[66:67], v[66:67], 0, v[192:193]
	v_lshlrev_b64 v[154:155], 11, v[64:65]
	v_add_co_u32_e32 v66, vcc, s8, v66
	v_lshl_add_u64 v[64:65], v[184:185], 0, v[154:155]
	s_nop 0
	v_addc_co_u32_e32 v67, vcc, 0, v67, vcc
	global_load_dwordx4 v[112:115], v[64:65], off
	v_add_u32_e32 v64, s46, v207
	global_load_dwordx4 v[150:153], v[66:67], off offset:2080 nt
	v_mad_i64_i32 v[66:67], s[0:1], v64, s94, v[186:187]
	v_ashrrev_i32_e32 v65, 31, v64
	v_lshl_add_u64 v[66:67], v[66:67], 0, s[90:91]
	v_lshl_add_u64 v[66:67], v[66:67], 0, v[192:193]
	v_lshlrev_b64 v[126:127], 11, v[64:65]
	v_add_co_u32_e32 v66, vcc, s8, v66
	v_lshl_add_u64 v[64:65], v[184:185], 0, v[126:127]
	s_nop 0
	v_addc_co_u32_e32 v67, vcc, 0, v67, vcc
	global_load_dwordx4 v[104:107], v[64:65], off
	v_add_u32_e32 v64, s46, v208
	global_load_dwordx4 v[108:111], v[66:67], off offset:2080 nt
	v_mad_i64_i32 v[66:67], s[0:1], v64, s94, v[186:187]
	v_ashrrev_i32_e32 v65, 31, v64
	v_lshl_add_u64 v[66:67], v[66:67], 0, s[90:91]
	v_lshl_add_u64 v[66:67], v[66:67], 0, v[192:193]
	v_lshlrev_b64 v[124:125], 11, v[64:65]
	v_add_co_u32_e32 v66, vcc, s8, v66
	v_lshl_add_u64 v[64:65], v[184:185], 0, v[124:125]
	s_nop 0
	v_addc_co_u32_e32 v67, vcc, 0, v67, vcc
	global_load_dwordx4 v[96:99], v[64:65], off
	v_add_u32_e32 v64, s46, v209
	global_load_dwordx4 v[100:103], v[66:67], off offset:2080 nt
	v_mad_i64_i32 v[66:67], s[0:1], v64, s94, v[186:187]
	v_ashrrev_i32_e32 v65, 31, v64
	v_lshl_add_u64 v[66:67], v[66:67], 0, s[90:91]
	v_lshl_add_u64 v[66:67], v[66:67], 0, v[192:193]
	v_lshlrev_b64 v[122:123], 11, v[64:65]
	v_add_co_u32_e32 v66, vcc, s8, v66
	v_lshl_add_u64 v[64:65], v[184:185], 0, v[122:123]
	s_nop 0
	v_addc_co_u32_e32 v67, vcc, 0, v67, vcc
	global_load_dwordx4 v[88:91], v[64:65], off
	v_add_u32_e32 v64, s46, v210
	global_load_dwordx4 v[92:95], v[66:67], off offset:2080 nt
	v_mad_i64_i32 v[66:67], s[0:1], v64, s94, v[186:187]
	v_ashrrev_i32_e32 v65, 31, v64
	v_lshl_add_u64 v[66:67], v[66:67], 0, s[90:91]
	v_lshl_add_u64 v[66:67], v[66:67], 0, v[192:193]
	v_lshlrev_b64 v[120:121], 11, v[64:65]
	v_add_co_u32_e32 v66, vcc, s8, v66
	v_lshl_add_u64 v[64:65], v[184:185], 0, v[120:121]
	s_nop 0
	v_addc_co_u32_e32 v67, vcc, 0, v67, vcc
	global_load_dwordx4 v[80:83], v[64:65], off
	v_add_u32_e32 v64, s46, v211
	global_load_dwordx4 v[84:87], v[66:67], off offset:2080 nt
	v_mad_i64_i32 v[66:67], s[0:1], v64, s94, v[186:187]
	v_ashrrev_i32_e32 v65, 31, v64
	v_lshl_add_u64 v[66:67], v[66:67], 0, s[90:91]
	v_lshl_add_u64 v[66:67], v[66:67], 0, v[192:193]
	v_lshlrev_b64 v[118:119], 11, v[64:65]
	v_add_co_u32_e32 v66, vcc, s8, v66
	v_lshl_add_u64 v[64:65], v[184:185], 0, v[118:119]
	s_nop 0
	v_addc_co_u32_e32 v67, vcc, 0, v67, vcc
	global_load_dwordx4 v[72:75], v[64:65], off
	v_add_u32_e32 v64, s46, v212
	global_load_dwordx4 v[76:79], v[66:67], off offset:2080 nt
	v_mad_i64_i32 v[66:67], s[0:1], v64, s94, v[186:187]
	v_lshl_add_u64 v[66:67], v[66:67], 0, s[90:91]
	v_ashrrev_i32_e32 v65, 31, v64
	v_lshl_add_u64 v[66:67], v[66:67], 0, v[192:193]
	v_add_co_u32_e32 v66, vcc, s8, v66
	v_lshlrev_b64 v[116:117], 11, v[64:65]
	s_nop 0
	v_addc_co_u32_e32 v67, vcc, 0, v67, vcc
	v_lshl_add_u64 v[64:65], v[184:185], 0, v[116:117]
	global_load_dwordx4 v[68:71], v[66:67], off offset:2080 nt
	s_nop 0
	global_load_dwordx4 v[64:67], v[64:65], off
	s_barrier
	ds_write2st64_b32 v213, v0, v1 offset1:4
	ds_write2st64_b32 v213, v2, v3 offset0:8 offset1:12
	ds_write2st64_b32 v148, v4, v5 offset1:4
	ds_write2st64_b32 v148, v6, v7 offset0:8 offset1:12
	ds_write2st64_b32 v213, v8, v9 offset0:64 offset1:68
	ds_write2st64_b32 v213, v10, v11 offset0:72 offset1:76
	ds_write2st64_b32 v148, v12, v13 offset0:64 offset1:68
	ds_write2st64_b32 v148, v14, v15 offset0:72 offset1:76
	ds_write2st64_b32 v213, v16, v17 offset0:128 offset1:132
	ds_write2st64_b32 v213, v18, v19 offset0:136 offset1:140
	ds_write2st64_b32 v148, v20, v21 offset0:128 offset1:132
	ds_write2st64_b32 v148, v22, v23 offset0:136 offset1:140
	ds_write2st64_b32 v213, v24, v25 offset0:192 offset1:196
	ds_write2st64_b32 v213, v26, v27 offset0:200 offset1:204
	ds_write2st64_b32 v148, v28, v29 offset0:192 offset1:196
	ds_write2st64_b32 v148, v30, v31 offset0:200 offset1:204
	ds_write2st64_b32 v136, v32, v33 offset1:4
	ds_write2st64_b32 v136, v34, v35 offset0:8 offset1:12
	ds_write2st64_b32 v137, v36, v37 offset1:4
	ds_write2st64_b32 v137, v38, v39 offset0:8 offset1:12
	ds_write2st64_b32 v136, v40, v41 offset0:64 offset1:68
	ds_write2st64_b32 v136, v42, v43 offset0:72 offset1:76
	ds_write2st64_b32 v137, v44, v45 offset0:64 offset1:68
	ds_write2st64_b32 v137, v46, v47 offset0:72 offset1:76
	ds_write2st64_b32 v136, v48, v49 offset0:128 offset1:132
	ds_write2st64_b32 v136, v50, v51 offset0:136 offset1:140
	ds_write2st64_b32 v137, v52, v53 offset0:128 offset1:132
	ds_write2st64_b32 v137, v54, v55 offset0:136 offset1:140
	ds_write2st64_b32 v136, v56, v57 offset0:192 offset1:196
	ds_write2st64_b32 v136, v58, v59 offset0:200 offset1:204
	ds_write2st64_b32 v137, v60, v61 offset0:192 offset1:196
	ds_write2st64_b32 v137, v62, v63 offset0:200 offset1:204
	s_waitcnt vmcnt(14)
	v_lshlrev_b32_e32 v2, 16, v138
	v_lshl_add_u64 v[0:1], s[66:67], 0, v[146:147]
	v_and_b32_e32 v3, 0xffff0000, v138
	v_lshl_add_u64 v[8:9], v[0:1], 0, s[90:91]
	v_mul_f32_e32 v0, 0xbfb8aa3b, v2
	v_exp_f32_e32 v0, v0
	v_mul_f32_e32 v1, 0xbfb8aa3b, v3
	v_exp_f32_e32 v1, v1
	v_lshlrev_b32_e32 v4, 16, v139
	v_add_f32_e32 v0, 1.0, v0
	v_rcp_f32_e32 v18, v0
	v_add_f32_e32 v0, 1.0, v1
	v_and_b32_e32 v5, 0xffff0000, v139
	v_lshlrev_b32_e32 v21, 16, v140
	v_rcp_f32_e32 v19, v0
	v_mul_f32_e32 v0, 0xbfb8aa3b, v4
	v_and_b32_e32 v22, 0xffff0000, v140
	v_exp_f32_e32 v20, v0
	v_mul_f32_e32 v0, 0xbfb8aa3b, v5
	v_mul_f32_e32 v21, 0xbfb8aa3b, v21
	v_exp_f32_e32 v25, v0
	v_exp_f32_e32 v26, v21
	v_mul_f32_e32 v21, 0xbfb8aa3b, v22
	v_exp_f32_e32 v27, v21
	v_lshlrev_b32_e32 v23, 16, v141
	v_and_b32_e32 v24, 0xffff0000, v141
	v_mul_f32_e32 v23, 0xbfb8aa3b, v23
	v_add_f32_e32 v25, 1.0, v25
	v_add_f32_e32 v22, 1.0, v26
	v_exp_f32_e32 v26, v23
	v_mul_f32_e32 v23, 0xbfb8aa3b, v24
	v_rcp_f32_e32 v21, v25
	v_add_f32_e32 v25, 1.0, v27
	v_exp_f32_e32 v27, v23
	s_waitcnt lgkmcnt(0)
	s_barrier
	ds_read_b128 v[0:3], v128
	ds_read_b128 v[4:7], v128 offset:16
	v_add_f32_e32 v20, 1.0, v20
	v_rcp_f32_e32 v23, v25
	v_add_f32_e32 v24, 1.0, v26
	v_add_f32_e32 v25, 1.0, v27
	v_rcp_f32_e32 v20, v20
	v_rcp_f32_e32 v22, v22
	v_rcp_f32_e32 v24, v24
	v_rcp_f32_e32 v25, v25
	v_lshlrev_b32_e32 v10, 16, v142
	v_and_b32_e32 v11, 0xffff0000, v142
	v_lshlrev_b32_e32 v12, 16, v143
	v_and_b32_e32 v13, 0xffff0000, v143
	v_lshlrev_b32_e32 v14, 16, v144
	v_and_b32_e32 v15, 0xffff0000, v144
	v_lshlrev_b32_e32 v16, 16, v145
	v_and_b32_e32 v17, 0xffff0000, v145
	s_waitcnt lgkmcnt(1)
	v_pk_fma_f32 v[0:1], v[18:19], v[0:1], v[10:11]
	v_pk_fma_f32 v[2:3], v[20:21], v[2:3], v[12:13]
	s_waitcnt lgkmcnt(0)
	v_pk_fma_f32 v[4:5], v[22:23], v[4:5], v[14:15]
	v_pk_fma_f32 v[6:7], v[24:25], v[6:7], v[16:17]
	v_lshl_add_u64 v[8:9], v[8:9], 0, v[192:193]
	v_cvt_pk_bf16_f32 v0, v0, v1
	v_cvt_pk_bf16_f32 v1, v2, v3
	v_cvt_pk_bf16_f32 v2, v4, v5
	v_cvt_pk_bf16_f32 v3, v6, v7
	global_store_dwordx4 v[8:9], v[0:3], off
	s_waitcnt vmcnt(13)
	v_lshlrev_b32_e32 v4, 16, v151
	v_and_b32_e32 v5, 0xffff0000, v151
	v_lshlrev_b32_e32 v2, 16, v150
	v_lshl_add_u64 v[0:1], s[66:67], 0, v[154:155]
	v_and_b32_e32 v3, 0xffff0000, v150
	v_lshl_add_u64 v[8:9], v[0:1], 0, s[90:91]
	v_mul_f32_e32 v0, 0xbfb8aa3b, v2
	v_exp_f32_e32 v0, v0
	v_mul_f32_e32 v1, 0xbfb8aa3b, v3
	v_exp_f32_e32 v1, v1
	v_lshlrev_b32_e32 v21, 16, v152
	v_add_f32_e32 v0, 1.0, v0
	v_rcp_f32_e32 v18, v0
	v_add_f32_e32 v0, 1.0, v1
	v_rcp_f32_e32 v19, v0
	v_mul_f32_e32 v0, 0xbfb8aa3b, v4
	v_and_b32_e32 v22, 0xffff0000, v152
	v_exp_f32_e32 v20, v0
	v_mul_f32_e32 v0, 0xbfb8aa3b, v5
	v_mul_f32_e32 v21, 0xbfb8aa3b, v21
	v_exp_f32_e32 v25, v0
	v_exp_f32_e32 v26, v21
	v_mul_f32_e32 v21, 0xbfb8aa3b, v22
	v_exp_f32_e32 v27, v21
	v_lshlrev_b32_e32 v23, 16, v153
	v_and_b32_e32 v24, 0xffff0000, v153
	v_mul_f32_e32 v23, 0xbfb8aa3b, v23
	v_add_f32_e32 v25, 1.0, v25
	v_add_f32_e32 v22, 1.0, v26
	v_exp_f32_e32 v26, v23
	v_mul_f32_e32 v23, 0xbfb8aa3b, v24
	v_rcp_f32_e32 v21, v25
	v_add_f32_e32 v25, 1.0, v27
	v_exp_f32_e32 v27, v23
	ds_read_b128 v[0:3], v129
	ds_read_b128 v[4:7], v129 offset:16
	v_add_f32_e32 v20, 1.0, v20
	v_rcp_f32_e32 v23, v25
	v_add_f32_e32 v24, 1.0, v26
	v_add_f32_e32 v25, 1.0, v27
	v_rcp_f32_e32 v20, v20
	v_rcp_f32_e32 v22, v22
	v_rcp_f32_e32 v24, v24
	v_rcp_f32_e32 v25, v25
	v_lshlrev_b32_e32 v10, 16, v112
	v_and_b32_e32 v11, 0xffff0000, v112
	v_lshlrev_b32_e32 v12, 16, v113
	v_and_b32_e32 v13, 0xffff0000, v113
	v_lshlrev_b32_e32 v14, 16, v114
	v_and_b32_e32 v15, 0xffff0000, v114
	v_lshlrev_b32_e32 v16, 16, v115
	v_and_b32_e32 v17, 0xffff0000, v115
	s_waitcnt lgkmcnt(1)
	v_pk_fma_f32 v[0:1], v[18:19], v[0:1], v[10:11]
	v_pk_fma_f32 v[2:3], v[20:21], v[2:3], v[12:13]
	s_waitcnt lgkmcnt(0)
	v_pk_fma_f32 v[4:5], v[22:23], v[4:5], v[14:15]
	v_pk_fma_f32 v[6:7], v[24:25], v[6:7], v[16:17]
	v_lshl_add_u64 v[8:9], v[8:9], 0, v[192:193]
	v_cvt_pk_bf16_f32 v0, v0, v1
	v_cvt_pk_bf16_f32 v1, v2, v3
	v_cvt_pk_bf16_f32 v2, v4, v5
	v_cvt_pk_bf16_f32 v3, v6, v7
	global_store_dwordx4 v[8:9], v[0:3], off
	s_waitcnt vmcnt(12)
	v_lshlrev_b32_e32 v4, 16, v109
	v_and_b32_e32 v5, 0xffff0000, v109
	v_lshlrev_b32_e32 v2, 16, v108
	v_lshl_add_u64 v[0:1], s[66:67], 0, v[126:127]
	v_and_b32_e32 v3, 0xffff0000, v108
	v_lshl_add_u64 v[8:9], v[0:1], 0, s[90:91]
	v_mul_f32_e32 v0, 0xbfb8aa3b, v2
	v_exp_f32_e32 v0, v0
	v_mul_f32_e32 v1, 0xbfb8aa3b, v3
	v_exp_f32_e32 v1, v1
	v_lshlrev_b32_e32 v21, 16, v110
	v_add_f32_e32 v0, 1.0, v0
	v_rcp_f32_e32 v18, v0
	v_add_f32_e32 v0, 1.0, v1
	v_rcp_f32_e32 v19, v0
	v_mul_f32_e32 v0, 0xbfb8aa3b, v4
	v_and_b32_e32 v22, 0xffff0000, v110
	v_exp_f32_e32 v20, v0
	v_mul_f32_e32 v0, 0xbfb8aa3b, v5
	v_mul_f32_e32 v21, 0xbfb8aa3b, v21
	v_exp_f32_e32 v25, v0
	v_exp_f32_e32 v26, v21
	v_mul_f32_e32 v21, 0xbfb8aa3b, v22
	v_exp_f32_e32 v27, v21
	v_lshlrev_b32_e32 v23, 16, v111
	v_and_b32_e32 v24, 0xffff0000, v111
	v_mul_f32_e32 v23, 0xbfb8aa3b, v23
	v_add_f32_e32 v25, 1.0, v25
	v_add_f32_e32 v22, 1.0, v26
	v_exp_f32_e32 v26, v23
	v_mul_f32_e32 v23, 0xbfb8aa3b, v24
	v_rcp_f32_e32 v21, v25
	v_add_f32_e32 v25, 1.0, v27
	v_exp_f32_e32 v27, v23
	ds_read_b128 v[0:3], v130
	ds_read_b128 v[4:7], v130 offset:16
	v_add_f32_e32 v20, 1.0, v20
	v_rcp_f32_e32 v23, v25
	v_add_f32_e32 v24, 1.0, v26
	v_add_f32_e32 v25, 1.0, v27
	v_rcp_f32_e32 v20, v20
	v_rcp_f32_e32 v22, v22
	v_rcp_f32_e32 v24, v24
	v_rcp_f32_e32 v25, v25
	v_lshlrev_b32_e32 v10, 16, v104
	v_and_b32_e32 v11, 0xffff0000, v104
	v_lshlrev_b32_e32 v12, 16, v105
	v_and_b32_e32 v13, 0xffff0000, v105
	v_lshlrev_b32_e32 v14, 16, v106
	v_and_b32_e32 v15, 0xffff0000, v106
	v_lshlrev_b32_e32 v16, 16, v107
	v_and_b32_e32 v17, 0xffff0000, v107
	s_waitcnt lgkmcnt(1)
	v_pk_fma_f32 v[0:1], v[18:19], v[0:1], v[10:11]
	v_pk_fma_f32 v[2:3], v[20:21], v[2:3], v[12:13]
	s_waitcnt lgkmcnt(0)
	v_pk_fma_f32 v[4:5], v[22:23], v[4:5], v[14:15]
	v_pk_fma_f32 v[6:7], v[24:25], v[6:7], v[16:17]
	v_lshl_add_u64 v[8:9], v[8:9], 0, v[192:193]
	v_cvt_pk_bf16_f32 v0, v0, v1
	v_cvt_pk_bf16_f32 v1, v2, v3
	v_cvt_pk_bf16_f32 v2, v4, v5
	v_cvt_pk_bf16_f32 v3, v6, v7
	global_store_dwordx4 v[8:9], v[0:3], off
	s_waitcnt vmcnt(11)
	v_lshlrev_b32_e32 v4, 16, v101
	v_and_b32_e32 v5, 0xffff0000, v101
	v_lshlrev_b32_e32 v2, 16, v100
	v_lshl_add_u64 v[0:1], s[66:67], 0, v[124:125]
	v_and_b32_e32 v3, 0xffff0000, v100
	v_lshl_add_u64 v[8:9], v[0:1], 0, s[90:91]
	v_mul_f32_e32 v0, 0xbfb8aa3b, v2
	v_exp_f32_e32 v0, v0
	v_mul_f32_e32 v1, 0xbfb8aa3b, v3
	v_exp_f32_e32 v1, v1
	v_lshlrev_b32_e32 v21, 16, v102
	v_add_f32_e32 v0, 1.0, v0
	v_rcp_f32_e32 v18, v0
	v_add_f32_e32 v0, 1.0, v1
	v_rcp_f32_e32 v19, v0
	v_mul_f32_e32 v0, 0xbfb8aa3b, v4
	v_and_b32_e32 v22, 0xffff0000, v102
	v_exp_f32_e32 v20, v0
	v_mul_f32_e32 v0, 0xbfb8aa3b, v5
	v_mul_f32_e32 v21, 0xbfb8aa3b, v21
	v_exp_f32_e32 v25, v0
	v_exp_f32_e32 v26, v21
	v_mul_f32_e32 v21, 0xbfb8aa3b, v22
	v_exp_f32_e32 v27, v21
	v_lshlrev_b32_e32 v23, 16, v103
	v_and_b32_e32 v24, 0xffff0000, v103
	v_mul_f32_e32 v23, 0xbfb8aa3b, v23
	v_add_f32_e32 v25, 1.0, v25
	v_add_f32_e32 v22, 1.0, v26
	v_exp_f32_e32 v26, v23
	v_mul_f32_e32 v23, 0xbfb8aa3b, v24
	v_rcp_f32_e32 v21, v25
	v_add_f32_e32 v25, 1.0, v27
	v_exp_f32_e32 v27, v23
	ds_read_b128 v[0:3], v131
	ds_read_b128 v[4:7], v131 offset:16
	v_add_f32_e32 v20, 1.0, v20
	v_rcp_f32_e32 v23, v25
	v_add_f32_e32 v24, 1.0, v26
	v_add_f32_e32 v25, 1.0, v27
	v_rcp_f32_e32 v20, v20
	v_rcp_f32_e32 v22, v22
	v_rcp_f32_e32 v24, v24
	v_rcp_f32_e32 v25, v25
	v_lshlrev_b32_e32 v10, 16, v96
	v_and_b32_e32 v11, 0xffff0000, v96
	v_lshlrev_b32_e32 v12, 16, v97
	v_and_b32_e32 v13, 0xffff0000, v97
	v_lshlrev_b32_e32 v14, 16, v98
	v_and_b32_e32 v15, 0xffff0000, v98
	v_lshlrev_b32_e32 v16, 16, v99
	v_and_b32_e32 v17, 0xffff0000, v99
	s_waitcnt lgkmcnt(1)
	v_pk_fma_f32 v[0:1], v[18:19], v[0:1], v[10:11]
	v_pk_fma_f32 v[2:3], v[20:21], v[2:3], v[12:13]
	s_waitcnt lgkmcnt(0)
	v_pk_fma_f32 v[4:5], v[22:23], v[4:5], v[14:15]
	v_pk_fma_f32 v[6:7], v[24:25], v[6:7], v[16:17]
	v_lshl_add_u64 v[8:9], v[8:9], 0, v[192:193]
	v_cvt_pk_bf16_f32 v0, v0, v1
	v_cvt_pk_bf16_f32 v1, v2, v3
	v_cvt_pk_bf16_f32 v2, v4, v5
	v_cvt_pk_bf16_f32 v3, v6, v7
	global_store_dwordx4 v[8:9], v[0:3], off
	s_waitcnt vmcnt(10)
	v_lshlrev_b32_e32 v4, 16, v93
	v_and_b32_e32 v5, 0xffff0000, v93
	v_lshlrev_b32_e32 v2, 16, v92
	v_lshl_add_u64 v[0:1], s[66:67], 0, v[122:123]
	v_and_b32_e32 v3, 0xffff0000, v92
	v_lshl_add_u64 v[8:9], v[0:1], 0, s[90:91]
	v_mul_f32_e32 v0, 0xbfb8aa3b, v2
	v_exp_f32_e32 v0, v0
	v_mul_f32_e32 v1, 0xbfb8aa3b, v3
	v_exp_f32_e32 v1, v1
	v_lshlrev_b32_e32 v21, 16, v94
	v_add_f32_e32 v0, 1.0, v0
	v_rcp_f32_e32 v18, v0
	v_add_f32_e32 v0, 1.0, v1
	v_rcp_f32_e32 v19, v0
	v_mul_f32_e32 v0, 0xbfb8aa3b, v4
	v_and_b32_e32 v22, 0xffff0000, v94
	v_exp_f32_e32 v20, v0
	v_mul_f32_e32 v0, 0xbfb8aa3b, v5
	v_mul_f32_e32 v21, 0xbfb8aa3b, v21
	v_exp_f32_e32 v25, v0
	v_exp_f32_e32 v26, v21
	v_mul_f32_e32 v21, 0xbfb8aa3b, v22
	v_exp_f32_e32 v27, v21
	v_lshlrev_b32_e32 v23, 16, v95
	v_and_b32_e32 v24, 0xffff0000, v95
	v_mul_f32_e32 v23, 0xbfb8aa3b, v23
	v_add_f32_e32 v25, 1.0, v25
	v_add_f32_e32 v22, 1.0, v26
	v_exp_f32_e32 v26, v23
	v_mul_f32_e32 v23, 0xbfb8aa3b, v24
	v_rcp_f32_e32 v21, v25
	v_add_f32_e32 v25, 1.0, v27
	v_exp_f32_e32 v27, v23
	ds_read_b128 v[0:3], v132
	ds_read_b128 v[4:7], v132 offset:16
	v_add_f32_e32 v20, 1.0, v20
	v_rcp_f32_e32 v23, v25
	v_add_f32_e32 v24, 1.0, v26
	v_add_f32_e32 v25, 1.0, v27
	v_rcp_f32_e32 v20, v20
	v_rcp_f32_e32 v22, v22
	v_rcp_f32_e32 v24, v24
	v_rcp_f32_e32 v25, v25
	v_lshlrev_b32_e32 v10, 16, v88
	v_and_b32_e32 v11, 0xffff0000, v88
	v_lshlrev_b32_e32 v12, 16, v89
	v_and_b32_e32 v13, 0xffff0000, v89
	v_lshlrev_b32_e32 v14, 16, v90
	v_and_b32_e32 v15, 0xffff0000, v90
	v_lshlrev_b32_e32 v16, 16, v91
	v_and_b32_e32 v17, 0xffff0000, v91
	s_waitcnt lgkmcnt(1)
	v_pk_fma_f32 v[0:1], v[18:19], v[0:1], v[10:11]
	v_pk_fma_f32 v[2:3], v[20:21], v[2:3], v[12:13]
	s_waitcnt lgkmcnt(0)
	v_pk_fma_f32 v[4:5], v[22:23], v[4:5], v[14:15]
	v_pk_fma_f32 v[6:7], v[24:25], v[6:7], v[16:17]
	v_lshl_add_u64 v[8:9], v[8:9], 0, v[192:193]
	v_cvt_pk_bf16_f32 v0, v0, v1
	v_cvt_pk_bf16_f32 v1, v2, v3
	v_cvt_pk_bf16_f32 v2, v4, v5
	v_cvt_pk_bf16_f32 v3, v6, v7
	global_store_dwordx4 v[8:9], v[0:3], off
	s_waitcnt vmcnt(9)
	v_lshlrev_b32_e32 v4, 16, v85
	v_and_b32_e32 v5, 0xffff0000, v85
	v_lshlrev_b32_e32 v2, 16, v84
	v_lshl_add_u64 v[0:1], s[66:67], 0, v[120:121]
	v_and_b32_e32 v3, 0xffff0000, v84
	v_lshl_add_u64 v[8:9], v[0:1], 0, s[90:91]
	v_mul_f32_e32 v0, 0xbfb8aa3b, v2
	v_exp_f32_e32 v0, v0
	v_mul_f32_e32 v1, 0xbfb8aa3b, v3
	v_exp_f32_e32 v1, v1
	v_lshlrev_b32_e32 v21, 16, v86
	v_add_f32_e32 v0, 1.0, v0
	v_rcp_f32_e32 v18, v0
	v_add_f32_e32 v0, 1.0, v1
	v_rcp_f32_e32 v19, v0
	v_mul_f32_e32 v0, 0xbfb8aa3b, v4
	v_and_b32_e32 v22, 0xffff0000, v86
	v_exp_f32_e32 v20, v0
	v_mul_f32_e32 v0, 0xbfb8aa3b, v5
	v_mul_f32_e32 v21, 0xbfb8aa3b, v21
	v_exp_f32_e32 v25, v0
	v_exp_f32_e32 v26, v21
	v_mul_f32_e32 v21, 0xbfb8aa3b, v22
	v_exp_f32_e32 v27, v21
	v_lshlrev_b32_e32 v23, 16, v87
	v_and_b32_e32 v24, 0xffff0000, v87
	v_mul_f32_e32 v23, 0xbfb8aa3b, v23
	v_add_f32_e32 v25, 1.0, v25
	v_add_f32_e32 v22, 1.0, v26
	v_exp_f32_e32 v26, v23
	v_mul_f32_e32 v23, 0xbfb8aa3b, v24
	v_rcp_f32_e32 v21, v25
	v_add_f32_e32 v25, 1.0, v27
	v_exp_f32_e32 v27, v23
	ds_read_b128 v[0:3], v133
	ds_read_b128 v[4:7], v133 offset:16
	v_add_f32_e32 v20, 1.0, v20
	v_rcp_f32_e32 v23, v25
	v_add_f32_e32 v24, 1.0, v26
	v_add_f32_e32 v25, 1.0, v27
	v_rcp_f32_e32 v20, v20
	v_rcp_f32_e32 v22, v22
	v_rcp_f32_e32 v24, v24
	v_rcp_f32_e32 v25, v25
	v_lshlrev_b32_e32 v10, 16, v80
	v_and_b32_e32 v11, 0xffff0000, v80
	v_lshlrev_b32_e32 v12, 16, v81
	v_and_b32_e32 v13, 0xffff0000, v81
	v_lshlrev_b32_e32 v14, 16, v82
	v_and_b32_e32 v15, 0xffff0000, v82
	v_lshlrev_b32_e32 v16, 16, v83
	v_and_b32_e32 v17, 0xffff0000, v83
	s_waitcnt lgkmcnt(1)
	v_pk_fma_f32 v[0:1], v[18:19], v[0:1], v[10:11]
	v_pk_fma_f32 v[2:3], v[20:21], v[2:3], v[12:13]
	s_waitcnt lgkmcnt(0)
	v_pk_fma_f32 v[4:5], v[22:23], v[4:5], v[14:15]
	v_pk_fma_f32 v[6:7], v[24:25], v[6:7], v[16:17]
	v_lshl_add_u64 v[8:9], v[8:9], 0, v[192:193]
	v_cvt_pk_bf16_f32 v0, v0, v1
	v_cvt_pk_bf16_f32 v1, v2, v3
	v_cvt_pk_bf16_f32 v2, v4, v5
	v_cvt_pk_bf16_f32 v3, v6, v7
	global_store_dwordx4 v[8:9], v[0:3], off
	s_waitcnt vmcnt(8)
	v_lshlrev_b32_e32 v4, 16, v77
	v_and_b32_e32 v5, 0xffff0000, v77
	v_lshlrev_b32_e32 v2, 16, v76
	v_lshl_add_u64 v[0:1], s[66:67], 0, v[118:119]
	v_and_b32_e32 v3, 0xffff0000, v76
	v_lshl_add_u64 v[8:9], v[0:1], 0, s[90:91]
	v_mul_f32_e32 v0, 0xbfb8aa3b, v2
	v_exp_f32_e32 v0, v0
	v_mul_f32_e32 v1, 0xbfb8aa3b, v3
	v_exp_f32_e32 v1, v1
	v_lshlrev_b32_e32 v21, 16, v78
	v_add_f32_e32 v0, 1.0, v0
	v_rcp_f32_e32 v18, v0
	v_add_f32_e32 v0, 1.0, v1
	v_rcp_f32_e32 v19, v0
	v_mul_f32_e32 v0, 0xbfb8aa3b, v4
	v_and_b32_e32 v22, 0xffff0000, v78
	v_exp_f32_e32 v20, v0
	v_mul_f32_e32 v0, 0xbfb8aa3b, v5
	v_mul_f32_e32 v21, 0xbfb8aa3b, v21
	v_exp_f32_e32 v25, v0
	v_exp_f32_e32 v26, v21
	v_mul_f32_e32 v21, 0xbfb8aa3b, v22
	v_exp_f32_e32 v27, v21
	v_lshlrev_b32_e32 v23, 16, v79
	v_and_b32_e32 v24, 0xffff0000, v79
	v_mul_f32_e32 v23, 0xbfb8aa3b, v23
	v_add_f32_e32 v25, 1.0, v25
	v_add_f32_e32 v22, 1.0, v26
	v_exp_f32_e32 v26, v23
	v_mul_f32_e32 v23, 0xbfb8aa3b, v24
	v_rcp_f32_e32 v21, v25
	v_add_f32_e32 v25, 1.0, v27
	v_exp_f32_e32 v27, v23
	ds_read_b128 v[0:3], v134
	ds_read_b128 v[4:7], v134 offset:16
	v_add_f32_e32 v20, 1.0, v20
	v_rcp_f32_e32 v23, v25
	v_add_f32_e32 v24, 1.0, v26
	v_add_f32_e32 v25, 1.0, v27
	v_rcp_f32_e32 v20, v20
	v_rcp_f32_e32 v22, v22
	v_rcp_f32_e32 v24, v24
	v_rcp_f32_e32 v25, v25
	v_lshlrev_b32_e32 v10, 16, v72
	v_and_b32_e32 v11, 0xffff0000, v72
	v_lshlrev_b32_e32 v12, 16, v73
	v_and_b32_e32 v13, 0xffff0000, v73
	v_lshlrev_b32_e32 v14, 16, v74
	v_and_b32_e32 v15, 0xffff0000, v74
	v_lshlrev_b32_e32 v16, 16, v75
	v_and_b32_e32 v17, 0xffff0000, v75
	s_waitcnt lgkmcnt(1)
	v_pk_fma_f32 v[0:1], v[18:19], v[0:1], v[10:11]
	v_pk_fma_f32 v[2:3], v[20:21], v[2:3], v[12:13]
	s_waitcnt lgkmcnt(0)
	v_pk_fma_f32 v[4:5], v[22:23], v[4:5], v[14:15]
	v_pk_fma_f32 v[6:7], v[24:25], v[6:7], v[16:17]
	v_lshl_add_u64 v[8:9], v[8:9], 0, v[192:193]
	v_cvt_pk_bf16_f32 v0, v0, v1
	v_cvt_pk_bf16_f32 v1, v2, v3
	v_cvt_pk_bf16_f32 v2, v4, v5
	v_cvt_pk_bf16_f32 v3, v6, v7
	global_store_dwordx4 v[8:9], v[0:3], off
	s_waitcnt vmcnt(8)
	v_lshlrev_b32_e32 v4, 16, v69
	v_and_b32_e32 v5, 0xffff0000, v69
	v_lshlrev_b32_e32 v2, 16, v68
	v_lshl_add_u64 v[0:1], s[66:67], 0, v[116:117]
	v_and_b32_e32 v3, 0xffff0000, v68
	v_lshl_add_u64 v[8:9], v[0:1], 0, s[90:91]
	v_mul_f32_e32 v0, 0xbfb8aa3b, v2
	v_exp_f32_e32 v0, v0
	v_mul_f32_e32 v1, 0xbfb8aa3b, v3
	v_exp_f32_e32 v1, v1
	v_lshlrev_b32_e32 v21, 16, v70
	v_add_f32_e32 v0, 1.0, v0
	v_rcp_f32_e32 v18, v0
	v_add_f32_e32 v0, 1.0, v1
	v_rcp_f32_e32 v19, v0
	v_mul_f32_e32 v0, 0xbfb8aa3b, v4
	v_and_b32_e32 v22, 0xffff0000, v70
	v_exp_f32_e32 v20, v0
	v_mul_f32_e32 v0, 0xbfb8aa3b, v5
	v_mul_f32_e32 v21, 0xbfb8aa3b, v21
	v_exp_f32_e32 v25, v0
	v_exp_f32_e32 v26, v21
	v_mul_f32_e32 v21, 0xbfb8aa3b, v22
	v_exp_f32_e32 v27, v21
	v_lshlrev_b32_e32 v23, 16, v71
	v_and_b32_e32 v24, 0xffff0000, v71
	v_mul_f32_e32 v23, 0xbfb8aa3b, v23
	v_add_f32_e32 v25, 1.0, v25
	v_add_f32_e32 v22, 1.0, v26
	v_exp_f32_e32 v26, v23
	v_mul_f32_e32 v23, 0xbfb8aa3b, v24
	v_rcp_f32_e32 v21, v25
	v_add_f32_e32 v25, 1.0, v27
	v_exp_f32_e32 v27, v23
	ds_read_b128 v[0:3], v135
	ds_read_b128 v[4:7], v135 offset:16
	v_add_f32_e32 v20, 1.0, v20
	v_rcp_f32_e32 v23, v25
	v_add_f32_e32 v24, 1.0, v26
	v_add_f32_e32 v25, 1.0, v27
	v_rcp_f32_e32 v20, v20
	v_rcp_f32_e32 v22, v22
	v_rcp_f32_e32 v24, v24
	v_rcp_f32_e32 v25, v25
	s_add_i32 s45, s45, 1
	v_readlane_b32 s0, v255, 18
	s_waitcnt vmcnt(7)
	v_lshlrev_b32_e32 v10, 16, v64
	v_and_b32_e32 v11, 0xffff0000, v64
	v_lshlrev_b32_e32 v12, 16, v65
	v_and_b32_e32 v13, 0xffff0000, v65
	v_lshlrev_b32_e32 v14, 16, v66
	v_and_b32_e32 v15, 0xffff0000, v66
	v_lshlrev_b32_e32 v16, 16, v67
	v_and_b32_e32 v17, 0xffff0000, v67
	s_mul_i32 s0, s45, s0
	v_readlane_b32 s1, v255, 33
	s_waitcnt lgkmcnt(1)
	v_pk_fma_f32 v[0:1], v[18:19], v[0:1], v[10:11]
	v_pk_fma_f32 v[2:3], v[20:21], v[2:3], v[12:13]
	s_waitcnt lgkmcnt(0)
	v_pk_fma_f32 v[4:5], v[22:23], v[4:5], v[14:15]
	v_pk_fma_f32 v[6:7], v[24:25], v[6:7], v[16:17]
	s_add_i32 s0, s0, s1
	v_lshl_add_u64 v[8:9], v[8:9], 0, v[192:193]
	v_cvt_pk_bf16_f32 v0, v0, v1
	v_cvt_pk_bf16_f32 v1, v2, v3
	v_cvt_pk_bf16_f32 v2, v4, v5
	v_cvt_pk_bf16_f32 v3, v6, v7
	s_cmp_lt_u32 s0, 24
	v_readlane_b32 s52, v255, 52
	global_store_dwordx4 v[8:9], v[0:3], off
	s_barrier
	s_cbranch_scc0 .LBB0_839

.LBB0_829:
	v_and_b32_e32 v2, 15, v1
	v_and_b32_e32 v3, 48, v1
	v_lshlrev_b32_e32 v2, 6, v2
	v_lshlrev_b32_e32 v1, 2, v1
	v_or_b32_e32 v4, v2, v3
	v_and_b32_e32 v1, 32, v1
	s_lshl_b32 s38, s38, 13
	v_bitop3_b32 v4, v4, s38, v1 bitop3:0xde
	s_lshl_b32 s38, s47, 6
	v_bitop3_b32 v2, v2, v1, v3 bitop3:0x36
	s_and_b32 s38, s38, 0x3000
	v_or_b32_e32 v136, s38, v2
	s_add_u32 s38, s0, 0x80
	s_addc_u32 s39, s1, 0
	v_add_u32_e32 v137, s93, v0
	v_lshl_add_u64 v[2:3], s[38:39], 0, v[192:193]
	v_readfirstlane_b32 s38, v137
	v_add_u32_e32 v138, 0x2000, v137
	s_mov_b32 m0, s38
	v_readfirstlane_b32 s38, v138
	s_waitcnt vmcnt(4)
	s_barrier
	global_load_lds_dwordx4 v[2:3], off
	s_mov_b32 m0, s38
	s_add_u32 s38, s2, 0x80
	v_lshl_add_u64 v[2:3], v[2:3], 0, s[6:7]
	s_addc_u32 s39, s3, 0
	v_add_u32_e32 v139, 0x8000, v130
	global_load_lds_dwordx4 v[2:3], off
	v_lshl_add_u64 v[2:3], s[38:39], 0, v[192:193]
	v_readfirstlane_b32 s38, v139
	v_add_u32_e32 v140, 0xa000, v130
	s_mov_b32 m0, s38
	v_readfirstlane_b32 s38, v140
	global_load_lds_dwordx4 v[2:3], off
	s_mov_b32 m0, s38
	s_add_u32 s38, s36, 0x80
	v_lshl_add_u64 v[2:3], v[2:3], 0, s[6:7]
	s_addc_u32 s39, s37, 0
	v_add_u32_e32 v141, s89, v0
	global_load_lds_dwordx4 v[2:3], off
	v_lshl_add_u64 v[2:3], s[38:39], 0, v[192:193]
	v_readfirstlane_b32 s38, v141
	v_add_u32_e32 v142, 0x2000, v141
	s_mov_b32 m0, s38
	v_readfirstlane_b32 s38, v142
	global_load_lds_dwordx4 v[2:3], off
	v_lshl_add_u64 v[0:1], v[2:3], 0, s[6:7]
	s_mov_b32 m0, s38
	s_mov_b32 s52, -2
	global_load_lds_dwordx4 v[0:1], off
	s_waitcnt vmcnt(6)
	v_mov_b32_e32 v0, 0
	s_mov_b64 s[38:39], 0
	v_add_u32_e32 v148, 0, v4
	v_mov_b32_e32 v1, v0
	v_mov_b32_e32 v2, v0
	v_mov_b32_e32 v3, v0
	v_mov_b32_e32 v4, v0
	v_mov_b32_e32 v5, v0
	v_mov_b32_e32 v6, v0
	v_mov_b32_e32 v7, v0
	v_mov_b32_e32 v8, v0
	v_mov_b32_e32 v9, v0
	v_mov_b32_e32 v10, v0
	v_mov_b32_e32 v11, v0
	v_mov_b32_e32 v12, v0
	v_mov_b32_e32 v13, v0
	v_mov_b32_e32 v14, v0
	v_mov_b32_e32 v15, v0
	v_mov_b32_e32 v16, v0
	v_mov_b32_e32 v17, v0
	v_mov_b32_e32 v18, v0
	v_mov_b32_e32 v19, v0
	v_mov_b32_e32 v20, v0
	v_mov_b32_e32 v21, v0
	v_mov_b32_e32 v22, v0
	v_mov_b32_e32 v23, v0
	v_mov_b32_e32 v24, v0
	v_mov_b32_e32 v25, v0
	v_mov_b32_e32 v26, v0
	v_mov_b32_e32 v27, v0
	v_mov_b32_e32 v28, v0
	v_mov_b32_e32 v29, v0
	v_mov_b32_e32 v30, v0
	v_mov_b32_e32 v31, v0
	v_mov_b32_e32 v32, v0
	v_mov_b32_e32 v33, v0
	v_mov_b32_e32 v34, v0
	v_mov_b32_e32 v35, v0
	v_mov_b32_e32 v36, v0
	v_mov_b32_e32 v37, v0
	v_mov_b32_e32 v38, v0
	v_mov_b32_e32 v39, v0
	v_mov_b32_e32 v40, v0
	v_mov_b32_e32 v41, v0
	v_mov_b32_e32 v42, v0
	v_mov_b32_e32 v43, v0
	v_mov_b32_e32 v44, v0
	v_mov_b32_e32 v45, v0
	v_mov_b32_e32 v46, v0
	v_mov_b32_e32 v47, v0
	v_mov_b32_e32 v48, v0
	v_mov_b32_e32 v49, v0
	v_mov_b32_e32 v50, v0
	v_mov_b32_e32 v51, v0
	v_mov_b32_e32 v52, v0
	v_mov_b32_e32 v53, v0
	v_mov_b32_e32 v54, v0
	v_mov_b32_e32 v55, v0
	v_mov_b32_e32 v56, v0
	v_mov_b32_e32 v57, v0
	v_mov_b32_e32 v58, v0
	v_mov_b32_e32 v59, v0
	v_mov_b32_e32 v60, v0
	v_mov_b32_e32 v61, v0
	v_mov_b32_e32 v62, v0
	v_mov_b32_e32 v63, v0
	v_mov_b32_e32 v64, v0
	v_mov_b32_e32 v65, v0
	v_mov_b32_e32 v66, v0
	v_mov_b32_e32 v67, v0
	v_mov_b32_e32 v68, v0
	v_mov_b32_e32 v69, v0
	v_mov_b32_e32 v70, v0
	v_mov_b32_e32 v71, v0
	v_mov_b32_e32 v72, v0
	v_mov_b32_e32 v73, v0
	v_mov_b32_e32 v74, v0
	v_mov_b32_e32 v75, v0
	v_mov_b32_e32 v76, v0
	v_mov_b32_e32 v77, v0
	v_mov_b32_e32 v78, v0
	v_mov_b32_e32 v79, v0
	v_mov_b32_e32 v80, v0
	v_mov_b32_e32 v81, v0
	v_mov_b32_e32 v82, v0
	v_mov_b32_e32 v83, v0
	v_mov_b32_e32 v84, v0
	v_mov_b32_e32 v85, v0
	v_mov_b32_e32 v86, v0
	v_mov_b32_e32 v87, v0
	v_mov_b32_e32 v88, v0
	v_mov_b32_e32 v89, v0
	v_mov_b32_e32 v90, v0
	v_mov_b32_e32 v91, v0
	v_mov_b32_e32 v92, v0
	v_mov_b32_e32 v93, v0
	v_mov_b32_e32 v94, v0
	v_mov_b32_e32 v95, v0
	v_mov_b32_e32 v96, v0
	v_mov_b32_e32 v97, v0
	v_mov_b32_e32 v98, v0
	v_mov_b32_e32 v99, v0
	v_mov_b32_e32 v100, v0
	v_mov_b32_e32 v101, v0
	v_mov_b32_e32 v102, v0
	v_mov_b32_e32 v103, v0
	v_mov_b32_e32 v104, v0
	v_mov_b32_e32 v105, v0
	v_mov_b32_e32 v106, v0
	v_mov_b32_e32 v107, v0
	v_mov_b32_e32 v108, v0
	v_mov_b32_e32 v109, v0
	v_mov_b32_e32 v110, v0
	v_mov_b32_e32 v111, v0
	v_mov_b32_e32 v112, v0
	v_mov_b32_e32 v113, v0
	v_mov_b32_e32 v114, v0
	v_mov_b32_e32 v115, v0
	v_mov_b32_e32 v116, v0
	v_mov_b32_e32 v117, v0
	v_mov_b32_e32 v118, v0
	v_mov_b32_e32 v119, v0
	v_mov_b32_e32 v120, v0
	v_mov_b32_e32 v121, v0
	v_mov_b32_e32 v122, v0
	v_mov_b32_e32 v123, v0
	v_mov_b32_e32 v124, v0
	v_mov_b32_e32 v125, v0
	v_mov_b32_e32 v126, v0
	v_mov_b32_e32 v127, v0
	s_barrier

.LBB0_833:
	v_mov_b32_e32 v182, v234
	s_lshl_b32 s47, s46, 8
	v_lshlrev_b32_e32 v159, 3, v182
	v_and_b32_e32 v66, 0xf8, v159
	v_ashrrev_i32_e32 v174, 5, v182
	v_add_u32_e32 v172, s47, v174
	v_mov_b64_e32 v[156:157], s[58:59]
	v_lshlrev_b32_e32 v192, 1, v66
	v_add_u32_e32 v66, 0x200, v182
	v_mad_i64_i32 v[64:65], s[0:1], v172, s94, v[156:157]
	s_lshl_b32 s90, s10, 1
	v_ashrrev_i32_e32 v175, 5, v66
	v_lshl_add_u64 v[64:65], v[64:65], 0, s[90:91]
	v_add_u32_e32 v170, s47, v175
	v_lshl_add_u64 v[64:65], v[64:65], 0, v[192:193]
	v_mad_i64_i32 v[66:67], s[0:1], v170, s94, v[156:157]
	v_add_co_u32_e32 v64, vcc, s8, v64
	v_lshl_add_u64 v[66:67], v[66:67], 0, s[90:91]
	s_nop 0
	v_addc_co_u32_e32 v65, vcc, 0, v65, vcc
	v_lshl_add_u64 v[66:67], v[66:67], 0, v[192:193]
	v_add_co_u32_e32 v66, vcc, s8, v66
	v_lshrrev_b32_e32 v161, 1, v182
	s_nop 0
	v_addc_co_u32_e32 v67, vcc, 0, v67, vcc
	global_load_dwordx4 v[184:187], v[64:65], off offset:32 nt
	global_load_dwordx4 v[148:151], v[66:67], off offset:32 nt
	v_add_u32_e32 v64, 0x400, v182
	v_ashrrev_i32_e32 v176, 5, v64
	v_add_u32_e32 v168, s47, v176
	v_add_u32_e32 v66, 0x600, v182
	v_mad_i64_i32 v[64:65], s[0:1], v168, s94, v[156:157]
	v_ashrrev_i32_e32 v177, 5, v66
	v_lshl_add_u64 v[64:65], v[64:65], 0, s[90:91]
	v_add_u32_e32 v166, s47, v177
	v_lshl_add_u64 v[64:65], v[64:65], 0, v[192:193]
	v_mad_i64_i32 v[66:67], s[0:1], v166, s94, v[156:157]
	v_add_co_u32_e32 v64, vcc, s8, v64
	v_lshl_add_u64 v[66:67], v[66:67], 0, s[90:91]
	s_nop 0
	v_addc_co_u32_e32 v65, vcc, 0, v65, vcc
	v_lshl_add_u64 v[66:67], v[66:67], 0, v[192:193]
	v_add_co_u32_e32 v66, vcc, s8, v66
	v_and_b32_e32 v190, 0x60, v161
	s_nop 0
	v_addc_co_u32_e32 v67, vcc, 0, v67, vcc
	global_load_dwordx4 v[84:87], v[64:65], off offset:32 nt
	global_load_dwordx4 v[80:83], v[66:67], off offset:32 nt
	v_add_u32_e32 v64, 0x800, v182
	v_ashrrev_i32_e32 v178, 5, v64
	v_add_u32_e32 v164, s47, v178
	v_add_u32_e32 v66, 0xa00, v182
	v_mad_i64_i32 v[64:65], s[0:1], v164, s94, v[156:157]
	v_ashrrev_i32_e32 v179, 5, v66
	v_lshl_add_u64 v[64:65], v[64:65], 0, s[90:91]
	v_add_u32_e32 v162, s47, v179
	v_lshl_add_u64 v[64:65], v[64:65], 0, v[192:193]
	v_mad_i64_i32 v[66:67], s[0:1], v162, s94, v[156:157]
	v_add_co_u32_e32 v64, vcc, s8, v64
	v_lshl_add_u64 v[66:67], v[66:67], 0, s[90:91]
	s_nop 0
	v_addc_co_u32_e32 v65, vcc, 0, v65, vcc
	v_lshl_add_u64 v[66:67], v[66:67], 0, v[192:193]
	v_add_co_u32_e32 v66, vcc, s8, v66
	v_lshrrev_b32_e32 v161, 3, v182
	s_nop 0
	v_addc_co_u32_e32 v67, vcc, 0, v67, vcc
	global_load_dwordx4 v[76:79], v[64:65], off offset:32 nt
	global_load_dwordx4 v[72:75], v[66:67], off offset:32 nt
	v_add_u32_e32 v64, 0xc00, v182
	v_ashrrev_i32_e32 v180, 5, v64
	v_add_u32_e32 v160, s47, v180
	v_add_u32_e32 v66, 0xe00, v182
	v_mad_i64_i32 v[64:65], s[0:1], v160, s94, v[156:157]
	v_ashrrev_i32_e32 v181, 5, v66
	v_lshl_add_u64 v[64:65], v[64:65], 0, s[90:91]
	v_add_u32_e32 v158, s47, v181
	v_lshl_add_u64 v[64:65], v[64:65], 0, v[192:193]
	v_mad_i64_i32 v[66:67], s[0:1], v158, s94, v[156:157]
	v_add_co_u32_e32 v64, vcc, s8, v64
	v_lshl_add_u64 v[66:67], v[66:67], 0, s[90:91]
	s_nop 0
	v_addc_co_u32_e32 v65, vcc, 0, v65, vcc
	v_lshl_add_u64 v[66:67], v[66:67], 0, v[192:193]
	v_add_co_u32_e32 v66, vcc, s8, v66
	v_and_b32_e32 v161, 48, v161
	s_nop 0
	v_addc_co_u32_e32 v67, vcc, 0, v67, vcc
	global_load_dwordx4 v[68:71], v[64:65], off offset:32 nt
	s_nop 0
	global_load_dwordx4 v[64:67], v[66:67], off offset:32 nt
	s_movk_i32 s0, 0xf8
	v_and_b32_e32 v188, 15, v182
	v_bfe_u32 v189, v182, 4, 2
	v_bitop3_b32 v159, v159, v161, s0 bitop3:0x6c
	v_or_b32_e32 v191, v190, v188
	v_lshlrev_b32_e32 v195, 4, v189
	v_lshl_add_u32 v183, v159, 2, 0
	v_ashrrev_i32_e32 v173, 31, v172
	v_ashrrev_i32_e32 v171, 31, v170
	v_ashrrev_i32_e32 v169, 31, v168
	v_ashrrev_i32_e32 v167, 31, v166
	v_ashrrev_i32_e32 v165, 31, v164
	v_ashrrev_i32_e32 v163, 31, v162
	v_ashrrev_i32_e32 v161, 31, v160
	v_ashrrev_i32_e32 v159, 31, v158
	v_lshlrev_b32_e32 v182, 8, v182
	v_bitop3_b32 v188, v190, v195, v188 bitop3:0x36
	v_and_b32_e32 v182, 0xffff0000, v182
	v_lshlrev_b32_e32 v188, 2, v188
	v_lshl_or_b32 v189, v189, 12, v182
	v_add3_u32 v182, 0, v188, v189
	s_barrier
	ds_write2st64_b32 v182, v116, v117 offset1:4
	ds_write2st64_b32 v182, v118, v119 offset0:8 offset1:12
	v_bitop3_b32 v116, v191, v195, 16 bitop3:0x36
	v_lshlrev_b32_e32 v116, 2, v116
	v_add3_u32 v116, 0, v116, v189
	s_movk_i32 s0, 0x80
	ds_write2st64_b32 v116, v88, v89 offset1:4
	ds_write2st64_b32 v116, v90, v91 offset0:8 offset1:12
	ds_write2st64_b32 v182, v92, v93 offset0:64 offset1:68
	ds_write2st64_b32 v182, v94, v95 offset0:72 offset1:76
	ds_write2st64_b32 v116, v96, v97 offset0:64 offset1:68
	ds_write2st64_b32 v116, v98, v99 offset0:72 offset1:76
	ds_write2st64_b32 v182, v100, v101 offset0:128 offset1:132
	ds_write2st64_b32 v182, v102, v103 offset0:136 offset1:140
	ds_write2st64_b32 v116, v104, v105 offset0:128 offset1:132
	ds_write2st64_b32 v116, v106, v107 offset0:136 offset1:140
	ds_write2st64_b32 v182, v108, v109 offset0:192 offset1:196
	ds_write2st64_b32 v182, v110, v111 offset0:200 offset1:204
	ds_write2st64_b32 v116, v112, v113 offset0:192 offset1:196
	ds_write2st64_b32 v116, v114, v115 offset0:200 offset1:204
	v_bitop3_b32 v88, v191, v195, s0 bitop3:0x36
	v_lshlrev_b32_e32 v88, 2, v88
	s_movk_i32 s0, 0x90
	v_add3_u32 v110, 0, v88, v189
	v_bitop3_b32 v88, v191, v195, s0 bitop3:0x36
	v_lshlrev_b32_e32 v88, 2, v88
	v_add3_u32 v111, 0, v88, v189
	s_waitcnt vmcnt(0)
	v_lshlrev_b32_e32 v88, 16, v184
	v_and_b32_e32 v89, 0xffff0000, v184
	v_mul_f32_e32 v88, 0xbfb8aa3b, v88
	v_exp_f32_e32 v88, v88
	v_mul_f32_e32 v89, 0xbfb8aa3b, v89
	v_exp_f32_e32 v89, v89
	v_lshlrev_b32_e32 v90, 16, v185
	v_add_f32_e32 v88, 1.0, v88
	v_lshlrev_b32_e32 v99, 16, v186
	v_rcp_f32_e32 v96, v88
	v_add_f32_e32 v88, 1.0, v89
	v_and_b32_e32 v91, 0xffff0000, v185
	v_rcp_f32_e32 v97, v88
	v_mul_f32_e32 v88, 0xbfb8aa3b, v90
	v_mul_f32_e32 v99, 0xbfb8aa3b, v99
	v_and_b32_e32 v100, 0xffff0000, v186
	v_exp_f32_e32 v98, v88
	v_mul_f32_e32 v88, 0xbfb8aa3b, v91
	v_exp_f32_e32 v105, v99
	v_exp_f32_e32 v104, v88
	v_mul_f32_e32 v99, 0xbfb8aa3b, v100
	v_lshlrev_b32_e32 v101, 16, v187
	v_exp_f32_e32 v106, v99
	v_and_b32_e32 v103, 0xffff0000, v187
	v_mul_f32_e32 v101, 0xbfb8aa3b, v101
	v_add_f32_e32 v100, 1.0, v105
	v_exp_f32_e32 v105, v101
	v_mul_f32_e32 v101, 0xbfb8aa3b, v103
	v_lshl_add_u32 v102, v174, 10, v183
	v_add_f32_e32 v104, 1.0, v104
	v_exp_f32_e32 v103, v101
	ds_write2st64_b32 v110, v152, v153 offset1:4
	ds_write2st64_b32 v110, v154, v155 offset0:8 offset1:12
	ds_write2st64_b32 v111, v120, v121 offset1:4
	ds_write2st64_b32 v111, v122, v123 offset0:8 offset1:12
	ds_write2st64_b32 v110, v124, v125 offset0:64 offset1:68
	ds_write2st64_b32 v110, v126, v127 offset0:72 offset1:76
	ds_write2st64_b32 v111, v128, v129 offset0:64 offset1:68
	ds_write2st64_b32 v111, v130, v131 offset0:72 offset1:76
	ds_write2st64_b32 v110, v132, v133 offset0:128 offset1:132
	ds_write2st64_b32 v110, v134, v135 offset0:136 offset1:140
	ds_write2st64_b32 v111, v136, v137 offset0:128 offset1:132
	ds_write2st64_b32 v111, v138, v139 offset0:136 offset1:140
	ds_write2st64_b32 v110, v140, v141 offset0:192 offset1:196
	ds_write2st64_b32 v110, v142, v143 offset0:200 offset1:204
	ds_write2st64_b32 v111, v144, v145 offset0:192 offset1:196
	ds_write2st64_b32 v111, v146, v147 offset0:200 offset1:204
	s_waitcnt lgkmcnt(0)
	s_barrier
	ds_read_b128 v[88:91], v102
	ds_read_b128 v[92:95], v102 offset:16
	v_add_f32_e32 v98, 1.0, v98
	v_rcp_f32_e32 v99, v104
	v_add_f32_e32 v104, 1.0, v106
	v_rcp_f32_e32 v98, v98
	v_rcp_f32_e32 v100, v100
	v_rcp_f32_e32 v101, v104
	v_add_f32_e32 v104, 1.0, v105
	v_add_f32_e32 v103, 1.0, v103
	v_rcp_f32_e32 v104, v104
	v_rcp_f32_e32 v105, v103
	s_waitcnt lgkmcnt(1)
	v_pk_mul_f32 v[88:89], v[96:97], v[88:89]
	v_pk_mul_f32 v[90:91], v[98:99], v[90:91]
	s_waitcnt lgkmcnt(0)
	v_pk_mul_f32 v[92:93], v[100:101], v[92:93]
	v_cvt_pk_bf16_f32 v88, v88, v89
	v_cvt_pk_bf16_f32 v89, v90, v91
	v_cvt_pk_bf16_f32 v90, v92, v93
	v_lshlrev_b64 v[92:93], 11, v[172:173]
	v_lshl_add_u64 v[92:93], s[66:67], 0, v[92:93]
	v_pk_mul_f32 v[94:95], v[104:105], v[94:95]
	v_lshl_add_u64 v[92:93], v[92:93], 0, s[90:91]
	v_cvt_pk_bf16_f32 v91, v94, v95
	v_lshl_add_u64 v[92:93], v[92:93], 0, v[192:193]
	global_store_dwordx4 v[92:93], v[88:91], off
	v_lshlrev_b32_e32 v99, 16, v150
	v_and_b32_e32 v100, 0xffff0000, v150
	v_lshlrev_b32_e32 v88, 16, v148
	v_and_b32_e32 v89, 0xffff0000, v148
	v_mul_f32_e32 v88, 0xbfb8aa3b, v88
	v_exp_f32_e32 v88, v88
	v_mul_f32_e32 v89, 0xbfb8aa3b, v89
	v_exp_f32_e32 v89, v89
	v_lshlrev_b32_e32 v90, 16, v149
	v_add_f32_e32 v88, 1.0, v88
	v_rcp_f32_e32 v96, v88
	v_add_f32_e32 v88, 1.0, v89
	v_and_b32_e32 v91, 0xffff0000, v149
	v_rcp_f32_e32 v97, v88
	v_mul_f32_e32 v88, 0xbfb8aa3b, v90
	v_exp_f32_e32 v98, v88
	v_mul_f32_e32 v88, 0xbfb8aa3b, v91
	v_mul_f32_e32 v99, 0xbfb8aa3b, v99
	v_exp_f32_e32 v105, v88
	v_exp_f32_e32 v106, v99
	v_mul_f32_e32 v99, 0xbfb8aa3b, v100
	v_exp_f32_e32 v107, v99
	v_lshlrev_b32_e32 v101, 16, v151
	v_and_b32_e32 v104, 0xffff0000, v151
	v_mul_f32_e32 v101, 0xbfb8aa3b, v101
	v_add_f32_e32 v105, 1.0, v105
	v_add_f32_e32 v100, 1.0, v106
	v_exp_f32_e32 v106, v101
	v_mul_f32_e32 v101, 0xbfb8aa3b, v104
	v_lshl_add_u32 v103, v175, 10, v183
	v_rcp_f32_e32 v99, v105
	v_add_f32_e32 v105, 1.0, v107
	v_exp_f32_e32 v107, v101
	ds_read_b128 v[88:91], v103
	ds_read_b128 v[92:95], v103 offset:16
	v_add_f32_e32 v98, 1.0, v98
	v_rcp_f32_e32 v98, v98
	v_rcp_f32_e32 v100, v100
	v_rcp_f32_e32 v101, v105
	v_add_f32_e32 v104, 1.0, v106
	v_add_f32_e32 v105, 1.0, v107
	v_rcp_f32_e32 v104, v104
	v_rcp_f32_e32 v105, v105
	s_waitcnt lgkmcnt(1)
	v_pk_mul_f32 v[88:89], v[96:97], v[88:89]
	v_pk_mul_f32 v[90:91], v[98:99], v[90:91]
	s_waitcnt lgkmcnt(0)
	v_pk_mul_f32 v[92:93], v[100:101], v[92:93]
	v_cvt_pk_bf16_f32 v88, v88, v89
	v_cvt_pk_bf16_f32 v89, v90, v91
	v_cvt_pk_bf16_f32 v90, v92, v93
	v_lshlrev_b64 v[92:93], 11, v[170:171]
	v_lshl_add_u64 v[92:93], s[66:67], 0, v[92:93]
	v_pk_mul_f32 v[94:95], v[104:105], v[94:95]
	v_lshl_add_u64 v[92:93], v[92:93], 0, s[90:91]
	v_cvt_pk_bf16_f32 v91, v94, v95
	v_lshl_add_u64 v[92:93], v[92:93], 0, v[192:193]
	global_store_dwordx4 v[92:93], v[88:91], off
	v_lshlrev_b32_e32 v95, 16, v86
	v_and_b32_e32 v96, 0xffff0000, v86
	v_lshlrev_b32_e32 v88, 16, v84
	v_and_b32_e32 v84, 0xffff0000, v84
	v_mul_f32_e32 v84, 0xbfb8aa3b, v84
	v_exp_f32_e32 v84, v84
	v_lshlrev_b32_e32 v89, 16, v85
	v_and_b32_e32 v85, 0xffff0000, v85
	v_mul_f32_e32 v95, 0xbfb8aa3b, v95
	v_add_f32_e32 v84, 1.0, v84
	v_rcp_f32_e32 v93, v84
	v_mul_f32_e32 v84, 0xbfb8aa3b, v89
	v_exp_f32_e32 v94, v84
	v_mul_f32_e32 v84, 0xbfb8aa3b, v85
	v_mul_f32_e32 v86, 0xbfb8aa3b, v88
	v_exp_f32_e32 v99, v84
	v_exp_f32_e32 v100, v95
	v_mul_f32_e32 v95, 0xbfb8aa3b, v96
	v_exp_f32_e32 v86, v86
	v_exp_f32_e32 v101, v95
	v_lshlrev_b32_e32 v97, 16, v87
	v_and_b32_e32 v98, 0xffff0000, v87
	v_mul_f32_e32 v97, 0xbfb8aa3b, v97
	v_add_f32_e32 v99, 1.0, v99
	v_add_f32_e32 v96, 1.0, v100
	v_exp_f32_e32 v100, v97
	v_mul_f32_e32 v97, 0xbfb8aa3b, v98
	v_lshl_add_u32 v104, v176, 10, v183
	v_add_f32_e32 v86, 1.0, v86
	v_rcp_f32_e32 v95, v99
	v_add_f32_e32 v99, 1.0, v101
	v_exp_f32_e32 v101, v97
	v_rcp_f32_e32 v92, v86
	ds_read_b128 v[84:87], v104
	ds_read_b128 v[88:91], v104 offset:16
	v_add_f32_e32 v94, 1.0, v94
	v_rcp_f32_e32 v94, v94
	v_rcp_f32_e32 v96, v96
	v_rcp_f32_e32 v97, v99
	v_add_f32_e32 v98, 1.0, v100
	v_add_f32_e32 v99, 1.0, v101
	v_rcp_f32_e32 v98, v98
	v_rcp_f32_e32 v99, v99
	s_waitcnt lgkmcnt(1)
	v_pk_mul_f32 v[84:85], v[92:93], v[84:85]
	v_pk_mul_f32 v[86:87], v[94:95], v[86:87]
	s_waitcnt lgkmcnt(0)
	v_pk_mul_f32 v[88:89], v[96:97], v[88:89]
	v_cvt_pk_bf16_f32 v84, v84, v85
	v_cvt_pk_bf16_f32 v85, v86, v87
	v_cvt_pk_bf16_f32 v86, v88, v89
	v_lshlrev_b64 v[88:89], 11, v[168:169]
	v_lshl_add_u64 v[88:89], s[66:67], 0, v[88:89]
	v_pk_mul_f32 v[90:91], v[98:99], v[90:91]
	v_lshl_add_u64 v[88:89], v[88:89], 0, s[90:91]
	v_cvt_pk_bf16_f32 v87, v90, v91
	v_lshl_add_u64 v[88:89], v[88:89], 0, v[192:193]
	global_store_dwordx4 v[88:89], v[84:87], off
	v_lshlrev_b32_e32 v91, 16, v82
	v_and_b32_e32 v92, 0xffff0000, v82
	v_lshlrev_b32_e32 v84, 16, v80
	v_and_b32_e32 v80, 0xffff0000, v80
	v_mul_f32_e32 v80, 0xbfb8aa3b, v80
	v_exp_f32_e32 v80, v80
	v_lshlrev_b32_e32 v85, 16, v81
	v_and_b32_e32 v81, 0xffff0000, v81
	v_mul_f32_e32 v91, 0xbfb8aa3b, v91
	v_add_f32_e32 v80, 1.0, v80
	v_rcp_f32_e32 v89, v80
	v_mul_f32_e32 v80, 0xbfb8aa3b, v85
	v_exp_f32_e32 v90, v80
	v_mul_f32_e32 v80, 0xbfb8aa3b, v81
	v_mul_f32_e32 v82, 0xbfb8aa3b, v84
	v_exp_f32_e32 v95, v80
	v_exp_f32_e32 v96, v91
	v_mul_f32_e32 v91, 0xbfb8aa3b, v92
	v_exp_f32_e32 v82, v82
	v_exp_f32_e32 v97, v91
	v_lshlrev_b32_e32 v93, 16, v83
	v_and_b32_e32 v94, 0xffff0000, v83
	v_mul_f32_e32 v93, 0xbfb8aa3b, v93
	v_add_f32_e32 v95, 1.0, v95
	v_add_f32_e32 v92, 1.0, v96
	v_exp_f32_e32 v96, v93
	v_mul_f32_e32 v93, 0xbfb8aa3b, v94
	v_lshl_add_u32 v105, v177, 10, v183
	v_add_f32_e32 v82, 1.0, v82
	v_rcp_f32_e32 v91, v95
	v_add_f32_e32 v95, 1.0, v97
	v_exp_f32_e32 v97, v93
	v_rcp_f32_e32 v88, v82
	ds_read_b128 v[80:83], v105
	ds_read_b128 v[84:87], v105 offset:16
	v_add_f32_e32 v90, 1.0, v90
	v_rcp_f32_e32 v90, v90
	v_rcp_f32_e32 v92, v92
	v_rcp_f32_e32 v93, v95
	v_add_f32_e32 v94, 1.0, v96
	v_add_f32_e32 v95, 1.0, v97
	v_rcp_f32_e32 v94, v94
	v_rcp_f32_e32 v95, v95
	s_waitcnt lgkmcnt(1)
	v_pk_mul_f32 v[80:81], v[88:89], v[80:81]
	v_pk_mul_f32 v[82:83], v[90:91], v[82:83]
	s_waitcnt lgkmcnt(0)
	v_pk_mul_f32 v[84:85], v[92:93], v[84:85]
	v_cvt_pk_bf16_f32 v80, v80, v81
	v_cvt_pk_bf16_f32 v81, v82, v83
	v_cvt_pk_bf16_f32 v82, v84, v85
	v_lshlrev_b64 v[84:85], 11, v[166:167]
	v_lshl_add_u64 v[84:85], s[66:67], 0, v[84:85]
	v_pk_mul_f32 v[86:87], v[94:95], v[86:87]
	v_lshl_add_u64 v[84:85], v[84:85], 0, s[90:91]
	v_cvt_pk_bf16_f32 v83, v86, v87
	v_lshl_add_u64 v[84:85], v[84:85], 0, v[192:193]
	global_store_dwordx4 v[84:85], v[80:83], off
	v_lshlrev_b32_e32 v87, 16, v78
	v_and_b32_e32 v88, 0xffff0000, v78
	v_lshlrev_b32_e32 v80, 16, v76
	v_and_b32_e32 v76, 0xffff0000, v76
	v_mul_f32_e32 v76, 0xbfb8aa3b, v76
	v_exp_f32_e32 v76, v76
	v_lshlrev_b32_e32 v81, 16, v77
	v_and_b32_e32 v77, 0xffff0000, v77
	v_mul_f32_e32 v87, 0xbfb8aa3b, v87
	v_add_f32_e32 v76, 1.0, v76
	v_rcp_f32_e32 v85, v76
	v_mul_f32_e32 v76, 0xbfb8aa3b, v81
	v_exp_f32_e32 v86, v76
	v_mul_f32_e32 v76, 0xbfb8aa3b, v77
	v_mul_f32_e32 v78, 0xbfb8aa3b, v80
	v_exp_f32_e32 v91, v76
	v_exp_f32_e32 v92, v87
	v_mul_f32_e32 v87, 0xbfb8aa3b, v88
	v_exp_f32_e32 v78, v78
	v_exp_f32_e32 v93, v87
	v_lshlrev_b32_e32 v89, 16, v79
	v_and_b32_e32 v90, 0xffff0000, v79
	v_mul_f32_e32 v89, 0xbfb8aa3b, v89
	v_add_f32_e32 v91, 1.0, v91
	v_add_f32_e32 v88, 1.0, v92
	v_exp_f32_e32 v92, v89
	v_mul_f32_e32 v89, 0xbfb8aa3b, v90
	v_lshl_add_u32 v106, v178, 10, v183
	v_add_f32_e32 v78, 1.0, v78
	v_rcp_f32_e32 v87, v91
	v_add_f32_e32 v91, 1.0, v93
	v_exp_f32_e32 v93, v89
	v_rcp_f32_e32 v84, v78
	ds_read_b128 v[76:79], v106
	ds_read_b128 v[80:83], v106 offset:16
	v_add_f32_e32 v86, 1.0, v86
	v_rcp_f32_e32 v86, v86
	v_rcp_f32_e32 v88, v88
	v_rcp_f32_e32 v89, v91
	v_add_f32_e32 v90, 1.0, v92
	v_add_f32_e32 v91, 1.0, v93
	v_rcp_f32_e32 v90, v90
	v_rcp_f32_e32 v91, v91
	s_waitcnt lgkmcnt(1)
	v_pk_mul_f32 v[76:77], v[84:85], v[76:77]
	v_pk_mul_f32 v[78:79], v[86:87], v[78:79]
	s_waitcnt lgkmcnt(0)
	v_pk_mul_f32 v[80:81], v[88:89], v[80:81]
	v_cvt_pk_bf16_f32 v76, v76, v77
	v_cvt_pk_bf16_f32 v77, v78, v79
	v_cvt_pk_bf16_f32 v78, v80, v81
	v_lshlrev_b64 v[80:81], 11, v[164:165]
	v_lshl_add_u64 v[80:81], s[66:67], 0, v[80:81]
	v_pk_mul_f32 v[82:83], v[90:91], v[82:83]
	v_lshl_add_u64 v[80:81], v[80:81], 0, s[90:91]
	v_cvt_pk_bf16_f32 v79, v82, v83
	v_lshl_add_u64 v[80:81], v[80:81], 0, v[192:193]
	global_store_dwordx4 v[80:81], v[76:79], off
	v_lshlrev_b32_e32 v83, 16, v74
	v_and_b32_e32 v84, 0xffff0000, v74
	v_lshlrev_b32_e32 v76, 16, v72
	v_and_b32_e32 v72, 0xffff0000, v72
	v_mul_f32_e32 v72, 0xbfb8aa3b, v72
	v_exp_f32_e32 v72, v72
	v_lshlrev_b32_e32 v77, 16, v73
	v_and_b32_e32 v73, 0xffff0000, v73
	v_mul_f32_e32 v83, 0xbfb8aa3b, v83
	v_add_f32_e32 v72, 1.0, v72
	v_rcp_f32_e32 v81, v72
	v_mul_f32_e32 v72, 0xbfb8aa3b, v77
	v_exp_f32_e32 v82, v72
	v_mul_f32_e32 v72, 0xbfb8aa3b, v73
	v_mul_f32_e32 v74, 0xbfb8aa3b, v76
	v_exp_f32_e32 v87, v72
	v_exp_f32_e32 v88, v83
	v_mul_f32_e32 v83, 0xbfb8aa3b, v84
	v_exp_f32_e32 v74, v74
	v_exp_f32_e32 v89, v83
	v_lshlrev_b32_e32 v85, 16, v75
	v_and_b32_e32 v86, 0xffff0000, v75
	v_mul_f32_e32 v85, 0xbfb8aa3b, v85
	v_add_f32_e32 v87, 1.0, v87
	v_add_f32_e32 v84, 1.0, v88
	v_exp_f32_e32 v88, v85
	v_mul_f32_e32 v85, 0xbfb8aa3b, v86
	v_lshl_add_u32 v107, v179, 10, v183
	v_add_f32_e32 v74, 1.0, v74
	v_rcp_f32_e32 v83, v87
	v_add_f32_e32 v87, 1.0, v89
	v_exp_f32_e32 v89, v85
	v_rcp_f32_e32 v80, v74
	ds_read_b128 v[72:75], v107
	ds_read_b128 v[76:79], v107 offset:16
	v_add_f32_e32 v82, 1.0, v82
	v_rcp_f32_e32 v82, v82
	v_rcp_f32_e32 v84, v84
	v_rcp_f32_e32 v85, v87
	v_add_f32_e32 v86, 1.0, v88
	v_add_f32_e32 v87, 1.0, v89
	v_rcp_f32_e32 v86, v86
	v_rcp_f32_e32 v87, v87
	s_waitcnt lgkmcnt(1)
	v_pk_mul_f32 v[72:73], v[80:81], v[72:73]
	v_pk_mul_f32 v[74:75], v[82:83], v[74:75]
	s_waitcnt lgkmcnt(0)
	v_pk_mul_f32 v[76:77], v[84:85], v[76:77]
	v_cvt_pk_bf16_f32 v72, v72, v73
	v_cvt_pk_bf16_f32 v73, v74, v75
	v_cvt_pk_bf16_f32 v74, v76, v77
	v_lshlrev_b64 v[76:77], 11, v[162:163]
	v_lshl_add_u64 v[76:77], s[66:67], 0, v[76:77]
	v_pk_mul_f32 v[78:79], v[86:87], v[78:79]
	v_lshl_add_u64 v[76:77], v[76:77], 0, s[90:91]
	v_cvt_pk_bf16_f32 v75, v78, v79
	v_lshl_add_u64 v[76:77], v[76:77], 0, v[192:193]
	global_store_dwordx4 v[76:77], v[72:75], off
	v_lshlrev_b32_e32 v79, 16, v70
	v_and_b32_e32 v80, 0xffff0000, v70
	v_lshlrev_b32_e32 v72, 16, v68
	v_and_b32_e32 v68, 0xffff0000, v68
	v_mul_f32_e32 v68, 0xbfb8aa3b, v68
	v_exp_f32_e32 v68, v68
	v_lshlrev_b32_e32 v73, 16, v69
	v_and_b32_e32 v69, 0xffff0000, v69
	v_mul_f32_e32 v79, 0xbfb8aa3b, v79
	v_add_f32_e32 v68, 1.0, v68
	v_rcp_f32_e32 v77, v68
	v_mul_f32_e32 v68, 0xbfb8aa3b, v73
	v_exp_f32_e32 v78, v68
	v_mul_f32_e32 v68, 0xbfb8aa3b, v69
	v_mul_f32_e32 v70, 0xbfb8aa3b, v72
	v_exp_f32_e32 v83, v68
	v_exp_f32_e32 v84, v79
	v_mul_f32_e32 v79, 0xbfb8aa3b, v80
	v_exp_f32_e32 v70, v70
	v_exp_f32_e32 v85, v79
	v_lshlrev_b32_e32 v81, 16, v71
	v_and_b32_e32 v82, 0xffff0000, v71
	v_mul_f32_e32 v81, 0xbfb8aa3b, v81
	v_add_f32_e32 v83, 1.0, v83
	v_add_f32_e32 v80, 1.0, v84
	v_exp_f32_e32 v84, v81
	v_mul_f32_e32 v81, 0xbfb8aa3b, v82
	v_lshl_add_u32 v108, v180, 10, v183
	v_add_f32_e32 v70, 1.0, v70
	v_rcp_f32_e32 v79, v83
	v_add_f32_e32 v83, 1.0, v85
	v_exp_f32_e32 v85, v81
	v_rcp_f32_e32 v76, v70
	ds_read_b128 v[68:71], v108
	ds_read_b128 v[72:75], v108 offset:16
	v_add_f32_e32 v78, 1.0, v78
	v_rcp_f32_e32 v78, v78
	v_rcp_f32_e32 v80, v80
	v_rcp_f32_e32 v81, v83
	v_add_f32_e32 v82, 1.0, v84
	v_add_f32_e32 v83, 1.0, v85
	v_rcp_f32_e32 v82, v82
	v_rcp_f32_e32 v83, v83
	s_waitcnt lgkmcnt(1)
	v_pk_mul_f32 v[68:69], v[76:77], v[68:69]
	v_pk_mul_f32 v[70:71], v[78:79], v[70:71]
	s_waitcnt lgkmcnt(0)
	v_pk_mul_f32 v[72:73], v[80:81], v[72:73]
	v_cvt_pk_bf16_f32 v68, v68, v69
	v_cvt_pk_bf16_f32 v69, v70, v71
	v_cvt_pk_bf16_f32 v70, v72, v73
	v_lshlrev_b64 v[72:73], 11, v[160:161]
	v_lshl_add_u64 v[72:73], s[66:67], 0, v[72:73]
	v_pk_mul_f32 v[74:75], v[82:83], v[74:75]
	v_lshl_add_u64 v[72:73], v[72:73], 0, s[90:91]
	v_cvt_pk_bf16_f32 v71, v74, v75
	v_lshl_add_u64 v[72:73], v[72:73], 0, v[192:193]
	global_store_dwordx4 v[72:73], v[68:71], off
	v_lshlrev_b32_e32 v75, 16, v66
	v_and_b32_e32 v76, 0xffff0000, v66
	v_lshlrev_b32_e32 v68, 16, v64
	v_and_b32_e32 v64, 0xffff0000, v64
	v_mul_f32_e32 v64, 0xbfb8aa3b, v64
	v_exp_f32_e32 v64, v64
	v_lshlrev_b32_e32 v69, 16, v65
	v_and_b32_e32 v65, 0xffff0000, v65
	v_mul_f32_e32 v75, 0xbfb8aa3b, v75
	v_add_f32_e32 v64, 1.0, v64
	v_rcp_f32_e32 v73, v64
	v_mul_f32_e32 v64, 0xbfb8aa3b, v69
	v_exp_f32_e32 v74, v64
	v_mul_f32_e32 v64, 0xbfb8aa3b, v65
	v_mul_f32_e32 v66, 0xbfb8aa3b, v68
	v_exp_f32_e32 v79, v64
	v_exp_f32_e32 v80, v75
	v_mul_f32_e32 v75, 0xbfb8aa3b, v76
	v_exp_f32_e32 v66, v66
	v_exp_f32_e32 v81, v75
	v_lshlrev_b32_e32 v77, 16, v67
	v_and_b32_e32 v78, 0xffff0000, v67
	v_mul_f32_e32 v77, 0xbfb8aa3b, v77
	v_add_f32_e32 v79, 1.0, v79
	v_add_f32_e32 v76, 1.0, v80
	v_exp_f32_e32 v80, v77
	v_mul_f32_e32 v77, 0xbfb8aa3b, v78
	v_lshl_add_u32 v109, v181, 10, v183
	v_add_f32_e32 v66, 1.0, v66
	v_rcp_f32_e32 v75, v79
	v_add_f32_e32 v79, 1.0, v81
	v_exp_f32_e32 v81, v77
	v_rcp_f32_e32 v72, v66
	ds_read_b128 v[64:67], v109
	ds_read_b128 v[68:71], v109 offset:16
	v_add_f32_e32 v74, 1.0, v74
	v_rcp_f32_e32 v74, v74
	v_rcp_f32_e32 v76, v76
	v_rcp_f32_e32 v77, v79
	v_add_f32_e32 v78, 1.0, v80
	v_add_f32_e32 v79, 1.0, v81
	v_rcp_f32_e32 v78, v78
	v_rcp_f32_e32 v79, v79
	s_waitcnt lgkmcnt(1)
	v_pk_mul_f32 v[64:65], v[72:73], v[64:65]
	v_pk_mul_f32 v[66:67], v[74:75], v[66:67]
	s_waitcnt lgkmcnt(0)
	v_pk_mul_f32 v[68:69], v[76:77], v[68:69]
	v_cvt_pk_bf16_f32 v64, v64, v65
	v_cvt_pk_bf16_f32 v65, v66, v67
	v_cvt_pk_bf16_f32 v66, v68, v69
	v_lshlrev_b64 v[68:69], 11, v[158:159]
	v_lshl_add_u64 v[68:69], s[66:67], 0, v[68:69]
	v_pk_mul_f32 v[70:71], v[78:79], v[70:71]
	v_lshl_add_u64 v[68:69], v[68:69], 0, s[90:91]
	s_or_b32 s46, s47, 0x80
	v_cvt_pk_bf16_f32 v67, v70, v71
	v_lshl_add_u64 v[68:69], v[68:69], 0, v[192:193]
	v_add_u32_e32 v122, s46, v174
	global_store_dwordx4 v[68:69], v[64:67], off
	v_add_u32_e32 v100, s46, v175
	v_add_u32_e32 v98, s46, v176
	v_mad_i64_i32 v[64:65], s[0:1], v122, s94, v[156:157]
	v_lshl_add_u64 v[64:65], v[64:65], 0, s[90:91]
	v_lshl_add_u64 v[64:65], v[64:65], 0, v[192:193]
	v_mad_i64_i32 v[66:67], s[0:1], v100, s94, v[156:157]
	v_add_co_u32_e32 v64, vcc, s8, v64
	v_lshl_add_u64 v[66:67], v[66:67], 0, s[90:91]
	s_nop 0
	v_addc_co_u32_e32 v65, vcc, 0, v65, vcc
	v_lshl_add_u64 v[66:67], v[66:67], 0, v[192:193]
	v_add_co_u32_e32 v66, vcc, s8, v66
	v_add_u32_e32 v96, s46, v177
	s_nop 0
	v_addc_co_u32_e32 v67, vcc, 0, v67, vcc
	global_load_dwordx4 v[112:115], v[64:65], off offset:32 nt
	global_load_dwordx4 v[118:121], v[66:67], off offset:32 nt
	v_mad_i64_i32 v[64:65], s[0:1], v98, s94, v[156:157]
	v_lshl_add_u64 v[64:65], v[64:65], 0, s[90:91]
	v_lshl_add_u64 v[64:65], v[64:65], 0, v[192:193]
	v_mad_i64_i32 v[66:67], s[0:1], v96, s94, v[156:157]
	v_add_co_u32_e32 v64, vcc, s8, v64
	v_lshl_add_u64 v[66:67], v[66:67], 0, s[90:91]
	s_nop 0
	v_addc_co_u32_e32 v65, vcc, 0, v65, vcc
	v_lshl_add_u64 v[66:67], v[66:67], 0, v[192:193]
	v_add_co_u32_e32 v66, vcc, s8, v66
	v_add_u32_e32 v94, s46, v178
	s_nop 0
	v_addc_co_u32_e32 v67, vcc, 0, v67, vcc
	global_load_dwordx4 v[84:87], v[64:65], off offset:32 nt
	global_load_dwordx4 v[80:83], v[66:67], off offset:32 nt
	v_mad_i64_i32 v[64:65], s[0:1], v94, s94, v[156:157]
	v_lshl_add_u64 v[64:65], v[64:65], 0, s[90:91]
	v_add_u32_e32 v92, s46, v179
	v_lshl_add_u64 v[64:65], v[64:65], 0, v[192:193]
	v_mad_i64_i32 v[66:67], s[0:1], v92, s94, v[156:157]
	v_add_co_u32_e32 v64, vcc, s8, v64
	v_lshl_add_u64 v[66:67], v[66:67], 0, s[90:91]
	s_nop 0
	v_addc_co_u32_e32 v65, vcc, 0, v65, vcc
	v_lshl_add_u64 v[66:67], v[66:67], 0, v[192:193]
	v_add_co_u32_e32 v66, vcc, s8, v66
	v_add_u32_e32 v90, s46, v180
	s_nop 0
	v_addc_co_u32_e32 v67, vcc, 0, v67, vcc
	global_load_dwordx4 v[76:79], v[64:65], off offset:32 nt
	global_load_dwordx4 v[72:75], v[66:67], off offset:32 nt
	v_mad_i64_i32 v[64:65], s[0:1], v90, s94, v[156:157]
	v_lshl_add_u64 v[64:65], v[64:65], 0, s[90:91]
	v_add_u32_e32 v88, s46, v181
	v_lshl_add_u64 v[64:65], v[64:65], 0, v[192:193]
	v_mad_i64_i32 v[66:67], s[0:1], v88, s94, v[156:157]
	v_add_co_u32_e32 v64, vcc, s8, v64
	v_lshl_add_u64 v[66:67], v[66:67], 0, s[90:91]
	s_nop 0
	v_addc_co_u32_e32 v65, vcc, 0, v65, vcc
	v_lshl_add_u64 v[66:67], v[66:67], 0, v[192:193]
	v_add_co_u32_e32 v66, vcc, s8, v66
	v_ashrrev_i32_e32 v123, 31, v122
	s_nop 0
	v_addc_co_u32_e32 v67, vcc, 0, v67, vcc
	global_load_dwordx4 v[68:71], v[64:65], off offset:32 nt
	s_nop 0
	global_load_dwordx4 v[64:67], v[66:67], off offset:32 nt
	v_ashrrev_i32_e32 v101, 31, v100
	v_ashrrev_i32_e32 v99, 31, v98
	v_ashrrev_i32_e32 v97, 31, v96
	v_ashrrev_i32_e32 v95, 31, v94
	v_ashrrev_i32_e32 v93, 31, v92
	v_ashrrev_i32_e32 v91, 31, v90
	v_ashrrev_i32_e32 v89, 31, v88
	s_barrier
	ds_write2st64_b32 v182, v0, v1 offset1:4
	ds_write2st64_b32 v182, v2, v3 offset0:8 offset1:12
	ds_write2st64_b32 v116, v4, v5 offset1:4
	ds_write2st64_b32 v116, v6, v7 offset0:8 offset1:12
	ds_write2st64_b32 v182, v8, v9 offset0:64 offset1:68
	ds_write2st64_b32 v182, v10, v11 offset0:72 offset1:76
	ds_write2st64_b32 v116, v12, v13 offset0:64 offset1:68
	ds_write2st64_b32 v116, v14, v15 offset0:72 offset1:76
	ds_write2st64_b32 v182, v16, v17 offset0:128 offset1:132
	ds_write2st64_b32 v182, v18, v19 offset0:136 offset1:140
	ds_write2st64_b32 v116, v20, v21 offset0:128 offset1:132
	ds_write2st64_b32 v116, v22, v23 offset0:136 offset1:140
	ds_write2st64_b32 v182, v24, v25 offset0:192 offset1:196
	ds_write2st64_b32 v182, v26, v27 offset0:200 offset1:204
	ds_write2st64_b32 v116, v28, v29 offset0:192 offset1:196
	ds_write2st64_b32 v116, v30, v31 offset0:200 offset1:204
	ds_write2st64_b32 v110, v32, v33 offset1:4
	ds_write2st64_b32 v110, v34, v35 offset0:8 offset1:12
	ds_write2st64_b32 v111, v36, v37 offset1:4
	ds_write2st64_b32 v111, v38, v39 offset0:8 offset1:12
	ds_write2st64_b32 v110, v40, v41 offset0:64 offset1:68
	ds_write2st64_b32 v110, v42, v43 offset0:72 offset1:76
	ds_write2st64_b32 v111, v44, v45 offset0:64 offset1:68
	ds_write2st64_b32 v111, v46, v47 offset0:72 offset1:76
	ds_write2st64_b32 v110, v48, v49 offset0:128 offset1:132
	ds_write2st64_b32 v110, v50, v51 offset0:136 offset1:140
	ds_write2st64_b32 v111, v52, v53 offset0:128 offset1:132
	ds_write2st64_b32 v111, v54, v55 offset0:136 offset1:140
	ds_write2st64_b32 v110, v56, v57 offset0:192 offset1:196
	ds_write2st64_b32 v110, v58, v59 offset0:200 offset1:204
	ds_write2st64_b32 v111, v60, v61 offset0:192 offset1:196
	ds_write2st64_b32 v111, v62, v63 offset0:200 offset1:204
	s_waitcnt vmcnt(7)
	v_lshlrev_b32_e32 v0, 16, v112
	v_and_b32_e32 v1, 0xffff0000, v112
	v_mul_f32_e32 v0, 0xbfb8aa3b, v0
	v_exp_f32_e32 v0, v0
	v_mul_f32_e32 v1, 0xbfb8aa3b, v1
	v_exp_f32_e32 v1, v1
	v_lshlrev_b32_e32 v2, 16, v113
	v_add_f32_e32 v0, 1.0, v0
	v_rcp_f32_e32 v8, v0
	v_add_f32_e32 v0, 1.0, v1
	v_and_b32_e32 v3, 0xffff0000, v113
	v_lshlrev_b32_e32 v11, 16, v114
	v_rcp_f32_e32 v9, v0
	v_mul_f32_e32 v0, 0xbfb8aa3b, v2
	v_and_b32_e32 v12, 0xffff0000, v114
	v_exp_f32_e32 v10, v0
	v_mul_f32_e32 v0, 0xbfb8aa3b, v3
	v_mul_f32_e32 v11, 0xbfb8aa3b, v11
	v_exp_f32_e32 v15, v0
	v_exp_f32_e32 v16, v11
	v_mul_f32_e32 v11, 0xbfb8aa3b, v12
	v_exp_f32_e32 v17, v11
	v_lshlrev_b32_e32 v13, 16, v115
	v_and_b32_e32 v14, 0xffff0000, v115
	v_mul_f32_e32 v13, 0xbfb8aa3b, v13
	v_add_f32_e32 v15, 1.0, v15
	v_add_f32_e32 v12, 1.0, v16
	v_exp_f32_e32 v16, v13
	v_mul_f32_e32 v13, 0xbfb8aa3b, v14
	v_rcp_f32_e32 v11, v15
	v_add_f32_e32 v15, 1.0, v17
	v_exp_f32_e32 v17, v13
	s_waitcnt lgkmcnt(0)
	s_barrier
	ds_read_b128 v[0:3], v102
	ds_read_b128 v[4:7], v102 offset:16
	v_add_f32_e32 v10, 1.0, v10
	v_rcp_f32_e32 v10, v10
	v_rcp_f32_e32 v12, v12
	v_rcp_f32_e32 v13, v15
	v_add_f32_e32 v14, 1.0, v16
	v_add_f32_e32 v15, 1.0, v17
	v_rcp_f32_e32 v14, v14
	v_rcp_f32_e32 v15, v15
	s_waitcnt lgkmcnt(1)
	v_pk_mul_f32 v[0:1], v[8:9], v[0:1]
	v_pk_mul_f32 v[2:3], v[10:11], v[2:3]
	s_waitcnt lgkmcnt(0)
	v_pk_mul_f32 v[4:5], v[12:13], v[4:5]
	v_cvt_pk_bf16_f32 v0, v0, v1
	v_cvt_pk_bf16_f32 v1, v2, v3
	v_cvt_pk_bf16_f32 v2, v4, v5
	v_lshlrev_b64 v[4:5], 11, v[122:123]
	v_lshl_add_u64 v[4:5], s[66:67], 0, v[4:5]
	v_pk_mul_f32 v[6:7], v[14:15], v[6:7]
	v_lshl_add_u64 v[4:5], v[4:5], 0, s[90:91]
	v_cvt_pk_bf16_f32 v3, v6, v7
	v_lshl_add_u64 v[4:5], v[4:5], 0, v[192:193]
	global_store_dwordx4 v[4:5], v[0:3], off
	s_waitcnt vmcnt(7)
	v_lshlrev_b32_e32 v11, 16, v120
	v_and_b32_e32 v12, 0xffff0000, v120
	v_lshlrev_b32_e32 v0, 16, v118
	v_and_b32_e32 v1, 0xffff0000, v118
	v_mul_f32_e32 v0, 0xbfb8aa3b, v0
	v_exp_f32_e32 v0, v0
	v_mul_f32_e32 v1, 0xbfb8aa3b, v1
	v_exp_f32_e32 v1, v1
	v_lshlrev_b32_e32 v2, 16, v119
	v_add_f32_e32 v0, 1.0, v0
	v_rcp_f32_e32 v8, v0
	v_add_f32_e32 v0, 1.0, v1
	v_and_b32_e32 v3, 0xffff0000, v119
	v_rcp_f32_e32 v9, v0
	v_mul_f32_e32 v0, 0xbfb8aa3b, v2
	v_exp_f32_e32 v10, v0
	v_mul_f32_e32 v0, 0xbfb8aa3b, v3
	v_mul_f32_e32 v11, 0xbfb8aa3b, v11
	v_exp_f32_e32 v15, v0
	v_exp_f32_e32 v16, v11
	v_mul_f32_e32 v11, 0xbfb8aa3b, v12
	v_exp_f32_e32 v17, v11
	v_lshlrev_b32_e32 v13, 16, v121
	v_and_b32_e32 v14, 0xffff0000, v121
	v_mul_f32_e32 v13, 0xbfb8aa3b, v13
	v_add_f32_e32 v15, 1.0, v15
	v_add_f32_e32 v12, 1.0, v16
	v_exp_f32_e32 v16, v13
	v_mul_f32_e32 v13, 0xbfb8aa3b, v14
	v_rcp_f32_e32 v11, v15
	v_add_f32_e32 v15, 1.0, v17
	v_exp_f32_e32 v17, v13
	ds_read_b128 v[0:3], v103
	ds_read_b128 v[4:7], v103 offset:16
	v_add_f32_e32 v10, 1.0, v10
	v_rcp_f32_e32 v10, v10
	v_rcp_f32_e32 v12, v12
	v_rcp_f32_e32 v13, v15
	v_add_f32_e32 v14, 1.0, v16
	v_add_f32_e32 v15, 1.0, v17
	v_rcp_f32_e32 v14, v14
	v_rcp_f32_e32 v15, v15
	s_waitcnt lgkmcnt(1)
	v_pk_mul_f32 v[0:1], v[8:9], v[0:1]
	v_pk_mul_f32 v[2:3], v[10:11], v[2:3]
	s_waitcnt lgkmcnt(0)
	v_pk_mul_f32 v[4:5], v[12:13], v[4:5]
	v_cvt_pk_bf16_f32 v0, v0, v1
	v_cvt_pk_bf16_f32 v1, v2, v3
	v_cvt_pk_bf16_f32 v2, v4, v5
	v_lshlrev_b64 v[4:5], 11, v[100:101]
	v_lshl_add_u64 v[4:5], s[66:67], 0, v[4:5]
	v_pk_mul_f32 v[6:7], v[14:15], v[6:7]
	v_lshl_add_u64 v[4:5], v[4:5], 0, s[90:91]
	v_cvt_pk_bf16_f32 v3, v6, v7
	v_lshl_add_u64 v[4:5], v[4:5], 0, v[192:193]
	global_store_dwordx4 v[4:5], v[0:3], off
	s_waitcnt vmcnt(7)
	v_lshlrev_b32_e32 v11, 16, v86
	v_and_b32_e32 v12, 0xffff0000, v86
	v_lshlrev_b32_e32 v0, 16, v84
	v_and_b32_e32 v1, 0xffff0000, v84
	v_mul_f32_e32 v0, 0xbfb8aa3b, v0
	v_exp_f32_e32 v0, v0
	v_mul_f32_e32 v1, 0xbfb8aa3b, v1
	v_exp_f32_e32 v1, v1
	v_lshlrev_b32_e32 v2, 16, v85
	v_add_f32_e32 v0, 1.0, v0
	v_rcp_f32_e32 v8, v0
	v_add_f32_e32 v0, 1.0, v1
	v_and_b32_e32 v3, 0xffff0000, v85
	v_rcp_f32_e32 v9, v0
	v_mul_f32_e32 v0, 0xbfb8aa3b, v2
	v_exp_f32_e32 v10, v0
	v_mul_f32_e32 v0, 0xbfb8aa3b, v3
	v_mul_f32_e32 v11, 0xbfb8aa3b, v11
	v_exp_f32_e32 v15, v0
	v_exp_f32_e32 v16, v11
	v_mul_f32_e32 v11, 0xbfb8aa3b, v12
	v_exp_f32_e32 v17, v11
	v_lshlrev_b32_e32 v13, 16, v87
	v_and_b32_e32 v14, 0xffff0000, v87
	v_mul_f32_e32 v13, 0xbfb8aa3b, v13
	v_add_f32_e32 v15, 1.0, v15
	v_add_f32_e32 v12, 1.0, v16
	v_exp_f32_e32 v16, v13
	v_mul_f32_e32 v13, 0xbfb8aa3b, v14
	v_rcp_f32_e32 v11, v15
	v_add_f32_e32 v15, 1.0, v17
	v_exp_f32_e32 v17, v13
	ds_read_b128 v[0:3], v104
	ds_read_b128 v[4:7], v104 offset:16
	v_add_f32_e32 v10, 1.0, v10
	v_rcp_f32_e32 v10, v10
	v_rcp_f32_e32 v12, v12
	v_rcp_f32_e32 v13, v15
	v_add_f32_e32 v14, 1.0, v16
	v_add_f32_e32 v15, 1.0, v17
	v_rcp_f32_e32 v14, v14
	v_rcp_f32_e32 v15, v15
	s_waitcnt lgkmcnt(1)
	v_pk_mul_f32 v[0:1], v[8:9], v[0:1]
	v_pk_mul_f32 v[2:3], v[10:11], v[2:3]
	s_waitcnt lgkmcnt(0)
	v_pk_mul_f32 v[4:5], v[12:13], v[4:5]
	v_cvt_pk_bf16_f32 v0, v0, v1
	v_cvt_pk_bf16_f32 v1, v2, v3
	v_cvt_pk_bf16_f32 v2, v4, v5
	v_lshlrev_b64 v[4:5], 11, v[98:99]
	v_lshl_add_u64 v[4:5], s[66:67], 0, v[4:5]
	v_pk_mul_f32 v[6:7], v[14:15], v[6:7]
	v_lshl_add_u64 v[4:5], v[4:5], 0, s[90:91]
	v_cvt_pk_bf16_f32 v3, v6, v7
	v_lshl_add_u64 v[4:5], v[4:5], 0, v[192:193]
	global_store_dwordx4 v[4:5], v[0:3], off
	s_waitcnt vmcnt(7)
	v_lshlrev_b32_e32 v11, 16, v82
	v_and_b32_e32 v12, 0xffff0000, v82
	v_lshlrev_b32_e32 v0, 16, v80
	v_and_b32_e32 v1, 0xffff0000, v80
	v_mul_f32_e32 v0, 0xbfb8aa3b, v0
	v_exp_f32_e32 v0, v0
	v_mul_f32_e32 v1, 0xbfb8aa3b, v1
	v_exp_f32_e32 v1, v1
	v_lshlrev_b32_e32 v2, 16, v81
	v_add_f32_e32 v0, 1.0, v0
	v_rcp_f32_e32 v8, v0
	v_add_f32_e32 v0, 1.0, v1
	v_and_b32_e32 v3, 0xffff0000, v81
	v_rcp_f32_e32 v9, v0
	v_mul_f32_e32 v0, 0xbfb8aa3b, v2
	v_exp_f32_e32 v10, v0
	v_mul_f32_e32 v0, 0xbfb8aa3b, v3
	v_mul_f32_e32 v11, 0xbfb8aa3b, v11
	v_exp_f32_e32 v15, v0
	v_exp_f32_e32 v16, v11
	v_mul_f32_e32 v11, 0xbfb8aa3b, v12
	v_exp_f32_e32 v17, v11
	v_lshlrev_b32_e32 v13, 16, v83
	v_and_b32_e32 v14, 0xffff0000, v83
	v_mul_f32_e32 v13, 0xbfb8aa3b, v13
	v_add_f32_e32 v15, 1.0, v15
	v_add_f32_e32 v12, 1.0, v16
	v_exp_f32_e32 v16, v13
	v_mul_f32_e32 v13, 0xbfb8aa3b, v14
	v_rcp_f32_e32 v11, v15
	v_add_f32_e32 v15, 1.0, v17
	v_exp_f32_e32 v17, v13
	ds_read_b128 v[0:3], v105
	ds_read_b128 v[4:7], v105 offset:16
	v_add_f32_e32 v10, 1.0, v10
	v_rcp_f32_e32 v10, v10
	v_rcp_f32_e32 v12, v12
	v_rcp_f32_e32 v13, v15
	v_add_f32_e32 v14, 1.0, v16
	v_add_f32_e32 v15, 1.0, v17
	v_rcp_f32_e32 v14, v14
	v_rcp_f32_e32 v15, v15
	s_waitcnt lgkmcnt(1)
	v_pk_mul_f32 v[0:1], v[8:9], v[0:1]
	v_pk_mul_f32 v[2:3], v[10:11], v[2:3]
	s_waitcnt lgkmcnt(0)
	v_pk_mul_f32 v[4:5], v[12:13], v[4:5]
	v_cvt_pk_bf16_f32 v0, v0, v1
	v_cvt_pk_bf16_f32 v1, v2, v3
	v_cvt_pk_bf16_f32 v2, v4, v5
	v_lshlrev_b64 v[4:5], 11, v[96:97]
	v_lshl_add_u64 v[4:5], s[66:67], 0, v[4:5]
	v_pk_mul_f32 v[6:7], v[14:15], v[6:7]
	v_lshl_add_u64 v[4:5], v[4:5], 0, s[90:91]
	v_cvt_pk_bf16_f32 v3, v6, v7
	v_lshl_add_u64 v[4:5], v[4:5], 0, v[192:193]
	global_store_dwordx4 v[4:5], v[0:3], off
	s_waitcnt vmcnt(7)
	v_lshlrev_b32_e32 v11, 16, v78
	v_and_b32_e32 v12, 0xffff0000, v78
	v_lshlrev_b32_e32 v0, 16, v76
	v_and_b32_e32 v1, 0xffff0000, v76
	v_mul_f32_e32 v0, 0xbfb8aa3b, v0
	v_exp_f32_e32 v0, v0
	v_mul_f32_e32 v1, 0xbfb8aa3b, v1
	v_exp_f32_e32 v1, v1
	v_lshlrev_b32_e32 v2, 16, v77
	v_add_f32_e32 v0, 1.0, v0
	v_rcp_f32_e32 v8, v0
	v_add_f32_e32 v0, 1.0, v1
	v_and_b32_e32 v3, 0xffff0000, v77
	v_rcp_f32_e32 v9, v0
	v_mul_f32_e32 v0, 0xbfb8aa3b, v2
	v_exp_f32_e32 v10, v0
	v_mul_f32_e32 v0, 0xbfb8aa3b, v3
	v_mul_f32_e32 v11, 0xbfb8aa3b, v11
	v_exp_f32_e32 v15, v0
	v_exp_f32_e32 v16, v11
	v_mul_f32_e32 v11, 0xbfb8aa3b, v12
	v_exp_f32_e32 v17, v11
	v_lshlrev_b32_e32 v13, 16, v79
	v_and_b32_e32 v14, 0xffff0000, v79
	v_mul_f32_e32 v13, 0xbfb8aa3b, v13
	v_add_f32_e32 v15, 1.0, v15
	v_add_f32_e32 v12, 1.0, v16
	v_exp_f32_e32 v16, v13
	v_mul_f32_e32 v13, 0xbfb8aa3b, v14
	v_rcp_f32_e32 v11, v15
	v_add_f32_e32 v15, 1.0, v17
	v_exp_f32_e32 v17, v13
	ds_read_b128 v[0:3], v106
	ds_read_b128 v[4:7], v106 offset:16
	v_add_f32_e32 v10, 1.0, v10
	v_rcp_f32_e32 v10, v10
	v_rcp_f32_e32 v12, v12
	v_rcp_f32_e32 v13, v15
	v_add_f32_e32 v14, 1.0, v16
	v_add_f32_e32 v15, 1.0, v17
	v_rcp_f32_e32 v14, v14
	v_rcp_f32_e32 v15, v15
	s_waitcnt lgkmcnt(1)
	v_pk_mul_f32 v[0:1], v[8:9], v[0:1]
	v_pk_mul_f32 v[2:3], v[10:11], v[2:3]
	s_waitcnt lgkmcnt(0)
	v_pk_mul_f32 v[4:5], v[12:13], v[4:5]
	v_cvt_pk_bf16_f32 v0, v0, v1
	v_cvt_pk_bf16_f32 v1, v2, v3
	v_cvt_pk_bf16_f32 v2, v4, v5
	v_lshlrev_b64 v[4:5], 11, v[94:95]
	v_lshl_add_u64 v[4:5], s[66:67], 0, v[4:5]
	v_pk_mul_f32 v[6:7], v[14:15], v[6:7]
	v_lshl_add_u64 v[4:5], v[4:5], 0, s[90:91]
	v_cvt_pk_bf16_f32 v3, v6, v7
	v_lshl_add_u64 v[4:5], v[4:5], 0, v[192:193]
	global_store_dwordx4 v[4:5], v[0:3], off
	s_waitcnt vmcnt(7)
	v_lshlrev_b32_e32 v11, 16, v74
	v_and_b32_e32 v12, 0xffff0000, v74
	v_lshlrev_b32_e32 v0, 16, v72
	v_and_b32_e32 v1, 0xffff0000, v72
	v_mul_f32_e32 v0, 0xbfb8aa3b, v0
	v_exp_f32_e32 v0, v0
	v_mul_f32_e32 v1, 0xbfb8aa3b, v1
	v_exp_f32_e32 v1, v1
	v_lshlrev_b32_e32 v2, 16, v73
	v_add_f32_e32 v0, 1.0, v0
	v_rcp_f32_e32 v8, v0
	v_add_f32_e32 v0, 1.0, v1
	v_and_b32_e32 v3, 0xffff0000, v73
	v_rcp_f32_e32 v9, v0
	v_mul_f32_e32 v0, 0xbfb8aa3b, v2
	v_exp_f32_e32 v10, v0
	v_mul_f32_e32 v0, 0xbfb8aa3b, v3
	v_mul_f32_e32 v11, 0xbfb8aa3b, v11
	v_exp_f32_e32 v15, v0
	v_exp_f32_e32 v16, v11
	v_mul_f32_e32 v11, 0xbfb8aa3b, v12
	v_exp_f32_e32 v17, v11
	v_lshlrev_b32_e32 v13, 16, v75
	v_and_b32_e32 v14, 0xffff0000, v75
	v_mul_f32_e32 v13, 0xbfb8aa3b, v13
	v_add_f32_e32 v15, 1.0, v15
	v_add_f32_e32 v12, 1.0, v16
	v_exp_f32_e32 v16, v13
	v_mul_f32_e32 v13, 0xbfb8aa3b, v14
	v_rcp_f32_e32 v11, v15
	v_add_f32_e32 v15, 1.0, v17
	v_exp_f32_e32 v17, v13
	ds_read_b128 v[0:3], v107
	ds_read_b128 v[4:7], v107 offset:16
	v_add_f32_e32 v10, 1.0, v10
	v_rcp_f32_e32 v10, v10
	v_rcp_f32_e32 v12, v12
	v_rcp_f32_e32 v13, v15
	v_add_f32_e32 v14, 1.0, v16
	v_add_f32_e32 v15, 1.0, v17
	v_rcp_f32_e32 v14, v14
	v_rcp_f32_e32 v15, v15
	s_waitcnt lgkmcnt(1)
	v_pk_mul_f32 v[0:1], v[8:9], v[0:1]
	v_pk_mul_f32 v[2:3], v[10:11], v[2:3]
	s_waitcnt lgkmcnt(0)
	v_pk_mul_f32 v[4:5], v[12:13], v[4:5]
	v_cvt_pk_bf16_f32 v0, v0, v1
	v_cvt_pk_bf16_f32 v1, v2, v3
	v_cvt_pk_bf16_f32 v2, v4, v5
	v_lshlrev_b64 v[4:5], 11, v[92:93]
	v_lshl_add_u64 v[4:5], s[66:67], 0, v[4:5]
	v_pk_mul_f32 v[6:7], v[14:15], v[6:7]
	v_lshl_add_u64 v[4:5], v[4:5], 0, s[90:91]
	v_cvt_pk_bf16_f32 v3, v6, v7
	v_lshl_add_u64 v[4:5], v[4:5], 0, v[192:193]
	global_store_dwordx4 v[4:5], v[0:3], off
	s_waitcnt vmcnt(7)
	v_lshlrev_b32_e32 v11, 16, v70
	v_and_b32_e32 v12, 0xffff0000, v70
	v_lshlrev_b32_e32 v0, 16, v68
	v_and_b32_e32 v1, 0xffff0000, v68
	v_mul_f32_e32 v0, 0xbfb8aa3b, v0
	v_exp_f32_e32 v0, v0
	v_mul_f32_e32 v1, 0xbfb8aa3b, v1
	v_exp_f32_e32 v1, v1
	v_lshlrev_b32_e32 v2, 16, v69
	v_add_f32_e32 v0, 1.0, v0
	v_rcp_f32_e32 v8, v0
	v_add_f32_e32 v0, 1.0, v1
	v_and_b32_e32 v3, 0xffff0000, v69
	v_rcp_f32_e32 v9, v0
	v_mul_f32_e32 v0, 0xbfb8aa3b, v2
	v_exp_f32_e32 v10, v0
	v_mul_f32_e32 v0, 0xbfb8aa3b, v3
	v_mul_f32_e32 v11, 0xbfb8aa3b, v11
	v_exp_f32_e32 v15, v0
	v_exp_f32_e32 v16, v11
	v_mul_f32_e32 v11, 0xbfb8aa3b, v12
	v_exp_f32_e32 v17, v11
	v_lshlrev_b32_e32 v13, 16, v71
	v_and_b32_e32 v14, 0xffff0000, v71
	v_mul_f32_e32 v13, 0xbfb8aa3b, v13
	v_add_f32_e32 v15, 1.0, v15
	v_add_f32_e32 v12, 1.0, v16
	v_exp_f32_e32 v16, v13
	v_mul_f32_e32 v13, 0xbfb8aa3b, v14
	v_rcp_f32_e32 v11, v15
	v_add_f32_e32 v15, 1.0, v17
	v_exp_f32_e32 v17, v13
	ds_read_b128 v[0:3], v108
	ds_read_b128 v[4:7], v108 offset:16
	v_add_f32_e32 v10, 1.0, v10
	v_rcp_f32_e32 v10, v10
	v_rcp_f32_e32 v12, v12
	v_rcp_f32_e32 v13, v15
	v_add_f32_e32 v14, 1.0, v16
	v_add_f32_e32 v15, 1.0, v17
	v_rcp_f32_e32 v14, v14
	v_rcp_f32_e32 v15, v15
	s_waitcnt lgkmcnt(1)
	v_pk_mul_f32 v[0:1], v[8:9], v[0:1]
	v_pk_mul_f32 v[2:3], v[10:11], v[2:3]
	s_waitcnt lgkmcnt(0)
	v_pk_mul_f32 v[4:5], v[12:13], v[4:5]
	v_cvt_pk_bf16_f32 v0, v0, v1
	v_cvt_pk_bf16_f32 v1, v2, v3
	v_cvt_pk_bf16_f32 v2, v4, v5
	v_lshlrev_b64 v[4:5], 11, v[90:91]
	v_lshl_add_u64 v[4:5], s[66:67], 0, v[4:5]
	v_pk_mul_f32 v[6:7], v[14:15], v[6:7]
	v_lshl_add_u64 v[4:5], v[4:5], 0, s[90:91]
	v_cvt_pk_bf16_f32 v3, v6, v7
	v_lshl_add_u64 v[4:5], v[4:5], 0, v[192:193]
	global_store_dwordx4 v[4:5], v[0:3], off
	s_waitcnt vmcnt(7)
	v_lshlrev_b32_e32 v11, 16, v66
	v_and_b32_e32 v12, 0xffff0000, v66
	v_lshlrev_b32_e32 v0, 16, v64
	v_and_b32_e32 v1, 0xffff0000, v64
	v_mul_f32_e32 v0, 0xbfb8aa3b, v0
	v_exp_f32_e32 v0, v0
	v_mul_f32_e32 v1, 0xbfb8aa3b, v1
	v_exp_f32_e32 v1, v1
	v_lshlrev_b32_e32 v2, 16, v65
	v_add_f32_e32 v0, 1.0, v0
	v_rcp_f32_e32 v8, v0
	v_add_f32_e32 v0, 1.0, v1
	v_and_b32_e32 v3, 0xffff0000, v65
	v_rcp_f32_e32 v9, v0
	v_mul_f32_e32 v0, 0xbfb8aa3b, v2
	v_exp_f32_e32 v10, v0
	v_mul_f32_e32 v0, 0xbfb8aa3b, v3
	v_mul_f32_e32 v11, 0xbfb8aa3b, v11
	v_exp_f32_e32 v15, v0
	v_exp_f32_e32 v16, v11
	v_mul_f32_e32 v11, 0xbfb8aa3b, v12
	v_exp_f32_e32 v17, v11
	v_lshlrev_b32_e32 v13, 16, v67
	v_and_b32_e32 v14, 0xffff0000, v67
	v_mul_f32_e32 v13, 0xbfb8aa3b, v13
	v_add_f32_e32 v15, 1.0, v15
	v_add_f32_e32 v12, 1.0, v16
	v_exp_f32_e32 v16, v13
	v_mul_f32_e32 v13, 0xbfb8aa3b, v14
	v_rcp_f32_e32 v11, v15
	v_add_f32_e32 v15, 1.0, v17
	v_exp_f32_e32 v17, v13
	ds_read_b128 v[0:3], v109
	ds_read_b128 v[4:7], v109 offset:16
	v_add_f32_e32 v10, 1.0, v10
	v_rcp_f32_e32 v10, v10
	v_rcp_f32_e32 v12, v12
	v_rcp_f32_e32 v13, v15
	v_add_f32_e32 v14, 1.0, v16
	v_add_f32_e32 v15, 1.0, v17
	v_rcp_f32_e32 v14, v14
	v_rcp_f32_e32 v15, v15
	s_waitcnt lgkmcnt(1)
	v_pk_mul_f32 v[0:1], v[8:9], v[0:1]
	v_pk_mul_f32 v[2:3], v[10:11], v[2:3]
	s_waitcnt lgkmcnt(0)
	v_pk_mul_f32 v[4:5], v[12:13], v[4:5]
	v_cvt_pk_bf16_f32 v0, v0, v1
	v_cvt_pk_bf16_f32 v1, v2, v3
	v_cvt_pk_bf16_f32 v2, v4, v5
	v_lshlrev_b64 v[4:5], 11, v[88:89]
	v_lshl_add_u64 v[4:5], s[66:67], 0, v[4:5]
	v_pk_mul_f32 v[6:7], v[14:15], v[6:7]
	v_lshl_add_u64 v[4:5], v[4:5], 0, s[90:91]
	v_cvt_pk_bf16_f32 v3, v6, v7
	v_lshl_add_u64 v[4:5], v[4:5], 0, v[192:193]
	global_store_dwordx4 v[4:5], v[0:3], off
	s_barrier
	s_nop 0
	v_mov_b32_e32 v1, v234
	s_lshl_b32 s0, s48, 1
	v_bfe_i32 v3, v1, 27, 1
	v_lshlrev_b32_e32 v0, 4, v1
	v_lshrrev_b32_e32 v3, 22, v3
	v_add_u32_e32 v3, v0, v3
	v_and_b32_e32 v3, 0xfffffc00, v3
	v_sub_u32_e32 v3, v0, v3
	v_lshrrev_b32_e32 v4, 4, v3
	v_ashrrev_i32_e32 v2, 31, v1
	v_bitop3_b32 v3, v4, v3, 32 bitop3:0x6c
	v_lshrrev_b32_e32 v2, 26, v2
	v_ashrrev_i32_e32 v5, 31, v3
	v_add_u32_e32 v2, v1, v2
	v_lshrrev_b32_e32 v5, 26, v5
	v_ashrrev_i32_e32 v2, 6, v2
	v_add_u32_e32 v5, v3, v5
	v_lshlrev_b32_e32 v4, 3, v2
	v_lshrrev_b32_e32 v6, 6, v5
	v_and_b32_e32 v5, 0xc0, v5
	v_readfirstlane_b32 s52, v1
	v_and_b32_e32 v4, 0x3ffff0, v4
	v_lshlrev_b32_e32 v2, 5, v2
	v_sub_u32_e32 v3, v3, v5
	s_ashr_i32 s38, s52, 8
	v_add_u32_e32 v4, v6, v4
	v_and_b32_e32 v2, 32, v2
	v_ashrrev_i16_sdwa v3, v238, sext(v3) dst_sel:DWORD dst_unused:UNUSED_PAD src0_sel:DWORD src1_sel:BYTE_0
	v_add_u32_e32 v128, s77, v0
	v_bfe_i32 v3, v3, 0, 16
	v_lshl_or_b32 v2, v4, 9, v2
	s_add_u32 s0, s43, s0
	v_readfirstlane_b32 s2, v128
	v_add_u32_e32 v129, 0x2000, v128
	v_add_lshl_u32 v192, v2, v3, 1
	s_addc_u32 s1, s44, 0
	s_mov_b32 m0, s2
	v_readfirstlane_b32 s2, v129
	global_load_lds_dwordx4 v192, s[0:1]
	s_mov_b32 m0, s2
	s_lshl_b32 s2, s49, 1
	v_lshl_add_u64 v[2:3], s[0:1], 0, v[192:193]
	s_add_u32 s2, s64, s2
	v_add_u32_e32 v130, 0, v0
	v_lshl_add_u64 v[2:3], v[2:3], 0, s[6:7]
	s_addc_u32 s3, s65, 0
	v_readfirstlane_b32 s12, v130
	v_add_u32_e32 v131, 0x2000, v130
	global_load_lds_dwordx4 v[2:3], off
	v_lshl_add_u64 v[2:3], s[2:3], 0, v[192:193]
	s_mov_b32 m0, s12
	v_readfirstlane_b32 s12, v131
	v_add_u32_e32 v132, s33, v0
	global_load_lds_dwordx4 v192, s[2:3]
	v_lshl_add_u64 v[2:3], v[2:3], 0, s[6:7]
	s_mov_b32 m0, s12
	s_add_u32 s36, s43, s50
	v_readfirstlane_b32 s12, v132
	v_add_u32_e32 v133, 0x2000, v132
	global_load_lds_dwordx4 v[2:3], off
	s_addc_u32 s37, s44, 0
	s_mov_b32 m0, s12
	v_readfirstlane_b32 s12, v133
	v_lshl_add_u64 v[2:3], s[36:37], 0, v[192:193]
	global_load_lds_dwordx4 v192, s[36:37]
	s_mov_b32 m0, s12
	s_add_u32 s12, s64, s51
	v_add_u32_e32 v134, 0x4000, v130
	v_lshl_add_u64 v[2:3], v[2:3], 0, s[6:7]
	s_addc_u32 s13, s65, 0
	v_readfirstlane_b32 s39, v134
	v_add_u32_e32 v135, 0x6000, v130
	global_load_lds_dwordx4 v[2:3], off
	v_lshl_add_u64 v[2:3], s[12:13], 0, v[192:193]
	s_mov_b32 m0, s39
	v_readfirstlane_b32 s39, v135
	global_load_lds_dwordx4 v192, s[12:13]
	v_lshl_add_u64 v[2:3], v[2:3], 0, s[6:7]
	s_mov_b32 m0, s39
	s_cmp_lg_u32 s38, 1
	global_load_lds_dwordx4 v[2:3], off
	s_cbranch_scc1 .LBB0_835
	s_barrier

.LBB0_1019:
	v_and_b32_e32 v2, 15, v1
	v_and_b32_e32 v3, 48, v1
	v_lshlrev_b32_e32 v2, 6, v2
	v_lshlrev_b32_e32 v1, 2, v1
	v_or_b32_e32 v4, v2, v3
	v_and_b32_e32 v1, 32, v1
	s_lshl_b32 s3, s48, 13
	v_bitop3_b32 v4, v4, s3, v1 bitop3:0xde
	s_lshl_b32 s3, s53, 6
	s_and_b32 s3, s3, 0x3000
	v_bitop3_b32 v2, v2, v1, v3 bitop3:0x36
	s_add_u32 s48, s38, 0x80
	v_add_u32_e32 v137, s93, v0
	v_or_b32_e32 v136, s3, v2
	s_addc_u32 s49, s39, 0
	v_readfirstlane_b32 s3, v137
	v_add_u32_e32 v138, 0x2000, v137
	v_lshl_add_u64 v[2:3], s[48:49], 0, v[192:193]
	s_mov_b32 m0, s3
	v_readfirstlane_b32 s3, v138
	s_add_u32 s48, s40, 0x80
	v_add_u32_e32 v139, 0x8000, v130
	s_waitcnt vmcnt(4)
	s_barrier
	global_load_lds_dwordx4 v[2:3], off
	v_lshl_add_u64 v[2:3], v[2:3], 0, s[34:35]
	s_mov_b32 m0, s3
	s_addc_u32 s49, s41, 0
	v_readfirstlane_b32 s3, v139
	v_add_u32_e32 v140, 0xa000, v130
	global_load_lds_dwordx4 v[2:3], off
	v_lshl_add_u64 v[2:3], s[48:49], 0, v[192:193]
	s_mov_b32 m0, s3
	v_readfirstlane_b32 s3, v140
	s_add_u32 s48, s44, 0x80
	v_add_u32_e32 v141, s89, v0
	global_load_lds_dwordx4 v[2:3], off
	v_lshl_add_u64 v[2:3], v[2:3], 0, s[34:35]
	s_mov_b32 m0, s3
	s_addc_u32 s49, s45, 0
	v_readfirstlane_b32 s3, v141
	v_add_u32_e32 v142, 0x2000, v141
	global_load_lds_dwordx4 v[2:3], off
	v_lshl_add_u64 v[2:3], s[48:49], 0, v[192:193]
	s_mov_b32 m0, s3
	v_readfirstlane_b32 s3, v142
	global_load_lds_dwordx4 v[2:3], off
	v_lshl_add_u64 v[0:1], v[2:3], 0, s[34:35]
	s_mov_b32 m0, s3
	s_mov_b32 s3, -2
	global_load_lds_dwordx4 v[0:1], off
	s_waitcnt vmcnt(6)
	v_mov_b32_e32 v0, 0
	s_mov_b64 s[48:49], 0
	v_add_u32_e32 v195, 0, v4
	v_mov_b32_e32 v1, v0
	v_mov_b32_e32 v2, v0
	v_mov_b32_e32 v3, v0
	v_mov_b32_e32 v4, v0
	v_mov_b32_e32 v5, v0
	v_mov_b32_e32 v6, v0
	v_mov_b32_e32 v7, v0
	v_mov_b32_e32 v8, v0
	v_mov_b32_e32 v9, v0
	v_mov_b32_e32 v10, v0
	v_mov_b32_e32 v11, v0
	v_mov_b32_e32 v12, v0
	v_mov_b32_e32 v13, v0
	v_mov_b32_e32 v14, v0
	v_mov_b32_e32 v15, v0
	v_mov_b32_e32 v16, v0
	v_mov_b32_e32 v17, v0
	v_mov_b32_e32 v18, v0
	v_mov_b32_e32 v19, v0
	v_mov_b32_e32 v20, v0
	v_mov_b32_e32 v21, v0
	v_mov_b32_e32 v22, v0
	v_mov_b32_e32 v23, v0
	v_mov_b32_e32 v24, v0
	v_mov_b32_e32 v25, v0
	v_mov_b32_e32 v26, v0
	v_mov_b32_e32 v27, v0
	v_mov_b32_e32 v28, v0
	v_mov_b32_e32 v29, v0
	v_mov_b32_e32 v30, v0
	v_mov_b32_e32 v31, v0
	v_mov_b32_e32 v32, v0
	v_mov_b32_e32 v33, v0
	v_mov_b32_e32 v34, v0
	v_mov_b32_e32 v35, v0
	v_mov_b32_e32 v36, v0
	v_mov_b32_e32 v37, v0
	v_mov_b32_e32 v38, v0
	v_mov_b32_e32 v39, v0
	v_mov_b32_e32 v40, v0
	v_mov_b32_e32 v41, v0
	v_mov_b32_e32 v42, v0
	v_mov_b32_e32 v43, v0
	v_mov_b32_e32 v44, v0
	v_mov_b32_e32 v45, v0
	v_mov_b32_e32 v46, v0
	v_mov_b32_e32 v47, v0
	v_mov_b32_e32 v48, v0
	v_mov_b32_e32 v49, v0
	v_mov_b32_e32 v50, v0
	v_mov_b32_e32 v51, v0
	v_mov_b32_e32 v52, v0
	v_mov_b32_e32 v53, v0
	v_mov_b32_e32 v54, v0
	v_mov_b32_e32 v55, v0
	v_mov_b32_e32 v56, v0
	v_mov_b32_e32 v57, v0
	v_mov_b32_e32 v58, v0
	v_mov_b32_e32 v59, v0
	v_mov_b32_e32 v60, v0
	v_mov_b32_e32 v61, v0
	v_mov_b32_e32 v62, v0
	v_mov_b32_e32 v63, v0
	v_mov_b32_e32 v64, v0
	v_mov_b32_e32 v65, v0
	v_mov_b32_e32 v66, v0
	v_mov_b32_e32 v67, v0
	v_mov_b32_e32 v68, v0
	v_mov_b32_e32 v69, v0
	v_mov_b32_e32 v70, v0
	v_mov_b32_e32 v71, v0
	v_mov_b32_e32 v72, v0
	v_mov_b32_e32 v73, v0
	v_mov_b32_e32 v74, v0
	v_mov_b32_e32 v75, v0
	v_mov_b32_e32 v76, v0
	v_mov_b32_e32 v77, v0
	v_mov_b32_e32 v78, v0
	v_mov_b32_e32 v79, v0
	v_mov_b32_e32 v80, v0
	v_mov_b32_e32 v81, v0
	v_mov_b32_e32 v82, v0
	v_mov_b32_e32 v83, v0
	v_mov_b32_e32 v84, v0
	v_mov_b32_e32 v85, v0
	v_mov_b32_e32 v86, v0
	v_mov_b32_e32 v87, v0
	v_mov_b32_e32 v88, v0
	v_mov_b32_e32 v89, v0
	v_mov_b32_e32 v90, v0
	v_mov_b32_e32 v91, v0
	v_mov_b32_e32 v92, v0
	v_mov_b32_e32 v93, v0
	v_mov_b32_e32 v94, v0
	v_mov_b32_e32 v95, v0
	v_mov_b32_e32 v96, v0
	v_mov_b32_e32 v97, v0
	v_mov_b32_e32 v98, v0
	v_mov_b32_e32 v99, v0
	v_mov_b32_e32 v100, v0
	v_mov_b32_e32 v101, v0
	v_mov_b32_e32 v102, v0
	v_mov_b32_e32 v103, v0
	v_mov_b32_e32 v104, v0
	v_mov_b32_e32 v105, v0
	v_mov_b32_e32 v106, v0
	v_mov_b32_e32 v107, v0
	v_mov_b32_e32 v108, v0
	v_mov_b32_e32 v109, v0
	v_mov_b32_e32 v110, v0
	v_mov_b32_e32 v111, v0
	v_mov_b32_e32 v112, v0
	v_mov_b32_e32 v113, v0
	v_mov_b32_e32 v114, v0
	v_mov_b32_e32 v115, v0
	v_mov_b32_e32 v116, v0
	v_mov_b32_e32 v117, v0
	v_mov_b32_e32 v118, v0
	v_mov_b32_e32 v119, v0
	v_mov_b32_e32 v120, v0
	v_mov_b32_e32 v121, v0
	v_mov_b32_e32 v122, v0
	v_mov_b32_e32 v123, v0
	v_mov_b32_e32 v124, v0
	v_mov_b32_e32 v125, v0
	v_mov_b32_e32 v126, v0
	v_mov_b32_e32 v127, v0
	s_barrier

.LBB0_1023:
	v_lshlrev_b32_e32 v248, 5, v234
	v_add_u32_e32 v248, 0x20020, v248
	s_cmp_lt_i32 s52, 16
	s_cselect_b64 s[46:47], -1, 0
	v_readlane_b32 s16, v253, 42
	s_and_b64 s[38:39], s[46:47], exec
	v_readlane_b32 s17, v253, 43
	v_readlane_b32 s18, v253, 44
	v_readlane_b32 s19, v253, 45
	v_readlane_b32 s20, v253, 46
	v_readlane_b32 s21, v253, 47
	v_readlane_b32 s22, v253, 48
	v_readlane_b32 s23, v253, 49
	v_readlane_b32 s24, v253, 50
	v_readlane_b32 s25, v253, 51
	v_readlane_b32 s26, v253, 52
	v_readlane_b32 s27, v253, 53
	v_readlane_b32 s28, v253, 54
	v_readlane_b32 s29, v253, 55
	v_readlane_b32 s30, v253, 56
	v_readlane_b32 s31, v253, 57
	v_readlane_b32 s3, v255, 29
	v_readlane_b32 s8, v255, 30
	s_cselect_b32 s3, s16, s3
	s_cselect_b32 s13, s17, s8
	v_readlane_b32 s8, v255, 47
	v_readlane_b32 s16, v254, 12
	v_readlane_b32 s9, v255, 48
	v_readlane_b32 s17, v254, 13
	v_readlane_b32 s18, v254, 14
	v_readlane_b32 s19, v254, 15
	v_readlane_b32 s20, v254, 16
	v_readlane_b32 s21, v254, 17
	v_readlane_b32 s22, v254, 18
	v_readlane_b32 s23, v254, 19
	v_readlane_b32 s24, v254, 20
	v_readlane_b32 s25, v254, 21
	s_and_b64 s[38:39], s[8:9], exec
	v_readlane_b32 s26, v254, 22
	v_readlane_b32 s27, v254, 23
	v_readlane_b32 s28, v254, 24
	v_readlane_b32 s29, v254, 25
	v_readlane_b32 s30, v254, 26
	v_readlane_b32 s31, v254, 27
	s_mov_b64 s[16:17], s[24:25]
	v_mov_b32_e32 v241, v234
	s_cselect_b32 s13, s13, s17
	s_cselect_b32 s3, s3, s16
	s_lshl_b64 s[44:45], s[0:1], 2
	v_lshlrev_b32_e32 v192, 3, v241
	v_ashrrev_i32_e32 v252, 5, v241
	v_and_b32_e32 v198, 0xf8, v192
	s_add_u32 s38, s3, s44
	v_add_u32_e32 v232, s12, v252
	s_addc_u32 s39, s13, s45
	v_lshlrev_b32_e32 v196, 2, v198
	v_mov_b32_e32 v197, v193
	v_ashrrev_i32_e32 v233, 31, v232
	v_lshl_add_u64 v[200:201], s[38:39], 0, v[196:197]
	v_lshlrev_b64 v[230:231], 12, v[232:233]
	v_lshl_add_u64 v[64:65], v[200:201], 0, v[230:231]
	global_load_dwordx4 v[120:123], v[64:65], off offset:16 nt
	global_load_dwordx4 v[124:127], v[64:65], off nt
	v_add_u32_e32 v64, 0x200, v241
	v_ashrrev_i32_e32 v233, 5, v64
	v_add_u32_e32 v228, s12, v233
	v_ashrrev_i32_e32 v229, 31, v228
	v_lshlrev_b64 v[226:227], 12, v[228:229]
	v_lshl_add_u64 v[64:65], v[200:201], 0, v[226:227]
	global_load_dwordx4 v[112:115], v[64:65], off offset:16 nt
	global_load_dwordx4 v[116:119], v[64:65], off nt
	v_add_u32_e32 v64, 0x400, v241
	v_ashrrev_i32_e32 v229, 5, v64
	v_add_u32_e32 v224, s12, v229
	v_ashrrev_i32_e32 v225, 31, v224
	v_lshlrev_b64 v[222:223], 12, v[224:225]
	v_lshl_add_u64 v[64:65], v[200:201], 0, v[222:223]
	global_load_dwordx4 v[104:107], v[64:65], off offset:16 nt
	global_load_dwordx4 v[108:111], v[64:65], off nt
	v_add_u32_e32 v64, 0x600, v241
	v_ashrrev_i32_e32 v225, 5, v64
	v_add_u32_e32 v220, s12, v225
	v_ashrrev_i32_e32 v221, 31, v220
	v_lshlrev_b64 v[218:219], 12, v[220:221]
	v_lshl_add_u64 v[64:65], v[200:201], 0, v[218:219]
	global_load_dwordx4 v[96:99], v[64:65], off offset:16 nt
	global_load_dwordx4 v[100:103], v[64:65], off nt
	v_add_u32_e32 v64, 0x800, v241
	v_ashrrev_i32_e32 v221, 5, v64
	v_add_u32_e32 v216, s12, v221
	v_ashrrev_i32_e32 v217, 31, v216
	v_lshlrev_b64 v[214:215], 12, v[216:217]
	v_lshl_add_u64 v[64:65], v[200:201], 0, v[214:215]
	global_load_dwordx4 v[88:91], v[64:65], off offset:16 nt
	global_load_dwordx4 v[92:95], v[64:65], off nt
	v_add_u32_e32 v64, 0xa00, v241
	v_ashrrev_i32_e32 v217, 5, v64
	v_add_u32_e32 v212, s12, v217
	v_ashrrev_i32_e32 v213, 31, v212
	v_lshlrev_b64 v[210:211], 12, v[212:213]
	v_lshl_add_u64 v[64:65], v[200:201], 0, v[210:211]
	global_load_dwordx4 v[80:83], v[64:65], off offset:16 nt
	global_load_dwordx4 v[84:87], v[64:65], off nt
	v_add_u32_e32 v64, 0xc00, v241
	v_ashrrev_i32_e32 v213, 5, v64
	v_add_u32_e32 v208, s12, v213
	v_ashrrev_i32_e32 v209, 31, v208
	v_lshlrev_b64 v[206:207], 12, v[208:209]
	v_lshl_add_u64 v[64:65], v[200:201], 0, v[206:207]
	global_load_dwordx4 v[72:75], v[64:65], off offset:16 nt
	global_load_dwordx4 v[76:79], v[64:65], off nt
	v_add_u32_e32 v64, 0xe00, v241
	v_ashrrev_i32_e32 v195, 5, v64
	v_add_u32_e32 v204, s12, v195
	v_ashrrev_i32_e32 v205, 31, v204
	v_lshlrev_b64 v[202:203], 12, v[204:205]
	v_lshl_add_u64 v[68:69], v[200:201], 0, v[202:203]
	global_load_dwordx4 v[64:67], v[68:69], off offset:16 nt
	s_nop 0
	global_load_dwordx4 v[68:71], v[68:69], off nt
	v_lshrrev_b32_e32 v199, 1, v241
	v_and_b32_e32 v209, 0x60, v199
	v_lshrrev_b32_e32 v199, 3, v241
	v_and_b32_e32 v199, 48, v199
	s_movk_i32 s3, 0xf8
	v_bitop3_b32 v192, v192, v199, s3 bitop3:0x6c
	s_cmp_gt_i32 s52, 15
	v_lshl_add_u32 v240, v192, 2, 0
	s_cselect_b64 s[38:39], -1, 0
	v_or_b32_e32 v192, s0, v198
	s_movk_i32 s3, 0x1ff
	v_and_b32_e32 v197, 15, v241
	v_bfe_u32 v205, v241, 4, 2
	s_and_b64 s[48:49], s[8:9], s[38:39]
	v_cmp_lt_i32_e64 s[38:39], s3, v192
	v_ashrrev_i32_e32 v199, 31, v192
	v_mov_b32_e32 v198, v192
	s_mov_b64 s[18:19], s[26:27]
	s_mov_b64 s[20:21], s[28:29]
	s_mov_b64 s[22:23], s[30:31]
	v_or_b32_e32 v242, v209, v197
	v_lshlrev_b32_e32 v243, 4, v205
	v_bitop3_b32 v197, v209, v243, v197 bitop3:0x36
	v_lshlrev_b32_e32 v209, 8, v241
	v_and_b32_e32 v209, 0xffff0000, v209
	v_lshl_add_u32 v197, v197, 2, 0
	v_lshl_or_b32 v241, v205, 12, v209
	v_add_u32_e32 v205, v197, v241
	s_barrier
	ds_write2st64_b32 v205, v156, v157 offset1:4
	ds_write2st64_b32 v205, v158, v159 offset0:8 offset1:12
	v_bitop3_b32 v156, v242, v243, 16 bitop3:0x36
	v_lshl_add_u32 v156, v156, 2, 0
	v_add_u32_e32 v209, v156, v241
	s_movk_i32 s3, 0x80
	ds_write2st64_b32 v209, v128, v129 offset1:4
	ds_write2st64_b32 v209, v130, v131 offset0:8 offset1:12
	ds_write2st64_b32 v205, v132, v133 offset0:64 offset1:68
	ds_write2st64_b32 v205, v134, v135 offset0:72 offset1:76
	ds_write2st64_b32 v209, v136, v137 offset0:64 offset1:68
	ds_write2st64_b32 v209, v138, v139 offset0:72 offset1:76
	ds_write2st64_b32 v205, v140, v141 offset0:128 offset1:132
	ds_write2st64_b32 v205, v142, v143 offset0:136 offset1:140
	ds_write2st64_b32 v209, v144, v145 offset0:128 offset1:132
	ds_write2st64_b32 v209, v146, v147 offset0:136 offset1:140
	ds_write2st64_b32 v205, v148, v149 offset0:192 offset1:196
	ds_write2st64_b32 v205, v150, v151 offset0:200 offset1:204
	ds_write2st64_b32 v209, v152, v153 offset0:192 offset1:196
	ds_write2st64_b32 v209, v154, v155 offset0:200 offset1:204
	v_bitop3_b32 v128, v242, v243, s3 bitop3:0x36
	v_lshl_add_u32 v128, v128, 2, 0
	s_movk_i32 s3, 0x90
	v_add_u32_e32 v244, v128, v241
	v_bitop3_b32 v128, v242, v243, s3 bitop3:0x36
	v_lshl_add_u32 v128, v128, 2, 0
	ds_write2st64_b32 v244, v188, v189 offset1:4
	ds_write2st64_b32 v244, v190, v191 offset0:8 offset1:12
	v_add_u32_e32 v188, v128, v241
	v_lshlrev_b32_e32 v128, 10, v252
	ds_write2st64_b32 v188, v160, v161 offset1:4
	ds_write2st64_b32 v188, v162, v163 offset0:8 offset1:12
	ds_write2st64_b32 v244, v164, v165 offset0:64 offset1:68
	ds_write2st64_b32 v244, v166, v167 offset0:72 offset1:76
	ds_write2st64_b32 v188, v168, v169 offset0:64 offset1:68
	ds_write2st64_b32 v188, v170, v171 offset0:72 offset1:76
	ds_write2st64_b32 v244, v172, v173 offset0:128 offset1:132
	ds_write2st64_b32 v244, v174, v175 offset0:136 offset1:140
	ds_write2st64_b32 v188, v176, v177 offset0:128 offset1:132
	ds_write2st64_b32 v188, v178, v179 offset0:136 offset1:140
	ds_write2st64_b32 v244, v180, v181 offset0:192 offset1:196
	ds_write2st64_b32 v244, v182, v183 offset0:200 offset1:204
	ds_write2st64_b32 v188, v184, v185 offset0:192 offset1:196
	ds_write2st64_b32 v188, v186, v187 offset0:200 offset1:204
	v_add_u32_e32 v164, v240, v128
	s_waitcnt lgkmcnt(0)
	s_barrier
	s_waitcnt vmcnt(0)
	ds_read_b128 v[132:135], v164
	ds_read_b128 v[128:131], v164 offset:16
	v_cndmask_b32_e64 v136, 0, 1, s[48:49]
	v_readlane_b32 s24, v253, 58
	s_movk_i32 s26, 0xf800
	v_cmp_ne_u32_e64 s[40:41], 1, v136
	s_andn2_b64 vcc, exec, s[48:49]
	v_readlane_b32 s25, v253, 59
	s_mov_b32 s27, -1
	s_cbranch_vccnz .LBB0_1029
	s_and_saveexec_b64 s[48:49], s[38:39]
	s_xor_b64 s[48:49], exec, s[48:49]
	v_lshlrev_b32_e32 v136, 11, v252
	v_and_b32_e32 v136, 0x1f800, v136
	v_mov_b32_e32 v137, v193
	v_lshl_add_u64 v[136:137], s[24:25], 0, v[136:137]
	v_lshl_add_u64 v[136:137], v[192:193], 2, v[136:137]
	v_lshl_add_u64 v[136:137], v[136:137], 0, s[26:27]
	s_andn2_saveexec_b64 s[48:49], s[48:49]
	s_cbranch_execz .LBB0_1028
	v_lshlrev_b32_e32 v136, 5, v232
	v_readlane_b32 s80, v253, 0
	v_and_b32_e32 v136, 0xf800, v136
	v_mov_b32_e32 v137, v193
	v_readlane_b32 s86, v253, 6
	v_readlane_b32 s87, v253, 7
	v_readlane_b32 s81, v253, 1
	v_readlane_b32 s82, v253, 2
	v_lshl_add_u64 v[136:137], s[86:87], 0, v[136:137]
	v_lshl_add_u64 v[136:137], v[198:199], 2, v[136:137]
	v_readlane_b32 s83, v253, 3
	v_readlane_b32 s84, v253, 4
	v_readlane_b32 s85, v253, 5

.LBB0_1029:
	s_add_i32 s3, s12, 0xfffff000
	s_lshr_b32 s3, s3, 11
	s_add_i32 s3, s3, 1
	s_and_b64 s[12:13], s[46:47], exec
	s_cselect_b32 s3, 0, s3
	v_readlane_b32 s8, v255, 51
	s_add_i32 s3, s3, s8
	v_readlane_b32 s80, v253, 0
	s_mul_hi_u32 s12, s3, 0x3000
	s_mulk_i32 s3, 0x3000
	v_readlane_b32 s84, v253, 4
	v_readlane_b32 s85, v253, 5
	s_add_u32 s3, s84, s3
	s_addc_u32 s13, s85, s12
	s_add_u32 s12, s3, s44
	s_addc_u32 s13, s13, s45
	v_mov_b32_e32 v197, v193
	v_lshl_add_u64 v[148:149], s[12:13], 0, v[196:197]
	s_mov_b64 s[12:13], 0x2000
	v_lshl_add_u64 v[136:137], v[148:149], 0, s[12:13]
	v_readlane_b32 s8, v254, 12
	v_readlane_b32 s16, v254, 20
	v_readlane_b32 s17, v254, 21
	s_movk_i32 s3, 0x2000
	v_lshl_add_u64 v[138:139], v[148:149], 0, s[34:35]
	v_lshl_add_u64 v[140:141], s[16:17], 0, v[230:231]
	v_lshl_add_u64 v[140:141], v[140:141], 0, s[44:45]
	v_lshl_add_u64 v[156:157], v[140:141], 0, v[196:197]
	v_add_co_u32_e32 v140, vcc, s3, v148
	s_mov_b32 s3, 0x20000
	s_nop 0
	v_addc_co_u32_e32 v141, vcc, 0, v149, vcc
	v_add_co_u32_e32 v148, vcc, s3, v148
	global_load_dwordx4 v[140:143], v[140:141], off
	s_nop 0
	global_load_dwordx4 v[144:147], v[136:137], off offset:16
	v_addc_co_u32_e32 v149, vcc, 0, v149, vcc
	global_load_dwordx4 v[148:151], v[148:149], off
	s_nop 0
	global_load_dwordx4 v[152:155], v[138:139], off offset:16
	s_and_b64 vcc, exec, s[40:41]
	s_movk_i32 s78, 0x600
	s_movk_i32 s79, 0x37f
	v_readlane_b32 s81, v253, 1
	v_readlane_b32 s82, v253, 2
	v_readlane_b32 s83, v253, 3
	v_readlane_b32 s86, v253, 6
	v_readlane_b32 s87, v253, 7
	v_readlane_b32 s9, v254, 13
	v_readlane_b32 s10, v254, 14
	v_readlane_b32 s11, v254, 15
	v_readlane_b32 s12, v254, 16
	v_readlane_b32 s13, v254, 17
	v_readlane_b32 s14, v254, 18
	v_readlane_b32 s15, v254, 19
	v_readlane_b32 s18, v254, 22
	v_readlane_b32 s19, v254, 23
	v_readlane_b32 s20, v254, 24
	v_readlane_b32 s21, v254, 25
	v_readlane_b32 s22, v254, 26
	v_readlane_b32 s23, v254, 27
	s_waitcnt vmcnt(1)
	v_pk_add_f32 v[140:141], v[140:141], v[148:149]
	ds_write_b64 v248, v[140:141]
	s_waitcnt lgkmcnt(1)
	v_pk_fma_f32 v[124:125], v[132:133], v[140:141], v[124:125]
	v_pk_add_f32 v[132:133], v[142:143], v[150:151]
	ds_write_b64 v248, v[132:133] offset:8
	s_nop 0
	v_pk_fma_f32 v[126:127], v[134:135], v[132:133], v[126:127]
	s_waitcnt vmcnt(0)
	v_pk_add_f32 v[132:133], v[144:145], v[152:153]
	ds_write_b64 v248, v[132:133] offset:16
	s_waitcnt lgkmcnt(0)
	v_pk_fma_f32 v[120:121], v[128:129], v[132:133], v[120:121]
	v_pk_add_f32 v[128:129], v[146:147], v[154:155]
	ds_write_b64 v248, v[128:129] offset:24
	s_nop 0
	v_pk_fma_f32 v[122:123], v[130:131], v[128:129], v[122:123]
	global_store_dwordx4 v[156:157], v[124:127], off
	global_store_dwordx4 v[156:157], v[120:123], off offset:16
	s_nop 1
	v_lshlrev_b32_e32 v120, 10, v233
	v_add_u32_e32 v166, v240, v120
	ds_read_b128 v[124:127], v166
	ds_read_b128 v[120:123], v166 offset:16
	s_cbranch_vccnz .LBB0_1035
	s_and_saveexec_b64 s[12:13], s[38:39]
	s_xor_b64 s[12:13], exec, s[12:13]
	v_lshlrev_b32_e32 v128, 11, v233
	v_and_b32_e32 v128, 0x1f800, v128
	v_mov_b32_e32 v129, v193
	v_lshl_add_u64 v[128:129], s[24:25], 0, v[128:129]
	v_lshl_add_u64 v[128:129], v[192:193], 2, v[128:129]
	v_lshl_add_u64 v[128:129], v[128:129], 0, s[26:27]
	s_andn2_saveexec_b64 s[12:13], s[12:13]
	s_cbranch_execz .LBB0_1034
	v_lshlrev_b32_e32 v128, 5, v228
	v_readlane_b32 s80, v253, 0
	v_and_b32_e32 v128, 0xf800, v128
	v_mov_b32_e32 v129, v193
	v_readlane_b32 s86, v253, 6
	v_readlane_b32 s87, v253, 7
	v_readlane_b32 s81, v253, 1
	v_readlane_b32 s82, v253, 2
	v_lshl_add_u64 v[128:129], s[86:87], 0, v[128:129]
	v_lshl_add_u64 v[128:129], v[198:199], 2, v[128:129]
	v_readlane_b32 s83, v253, 3
	v_readlane_b32 s84, v253, 4
	v_readlane_b32 s85, v253, 5

.LBB0_1035:
	v_readlane_b32 s8, v254, 12
	v_readlane_b32 s16, v254, 20
	v_readlane_b32 s17, v254, 21
	v_mov_b32_e32 v197, v193
	s_movk_i32 s82, 0xfc00
	v_lshl_add_u64 v[128:129], s[16:17], 0, v[226:227]
	v_lshl_add_u64 v[128:129], s[0:1], 2, v[128:129]
	v_lshl_add_u64 v[148:149], v[128:129], 0, v[196:197]
	ds_read_b128 v[128:131], v248 offset:16
	ds_read_b128 v[132:135], v248
	s_and_b64 vcc, exec, s[40:41]
	s_mov_b64 s[84:85], 0x200
	s_mov_b32 s83, -1
	v_readlane_b32 s9, v254, 13
	v_readlane_b32 s10, v254, 14
	v_readlane_b32 s11, v254, 15
	v_readlane_b32 s12, v254, 16
	v_readlane_b32 s13, v254, 17
	v_readlane_b32 s14, v254, 18
	v_readlane_b32 s15, v254, 19
	v_readlane_b32 s18, v254, 22
	v_readlane_b32 s19, v254, 23
	v_readlane_b32 s20, v254, 24
	v_readlane_b32 s21, v254, 25
	v_readlane_b32 s22, v254, 26
	v_readlane_b32 s23, v254, 27
	s_waitcnt lgkmcnt(0)
	s_waitcnt lgkmcnt(1)
	v_pk_fma_f32 v[116:117], v[124:125], v[132:133], v[116:117]
	v_mov_b64_e32 v[124:125], v[134:135]
	s_nop 0
	v_pk_fma_f32 v[118:119], v[126:127], v[124:125], v[118:119]
	v_mov_b64_e32 v[124:125], v[128:129]
	s_waitcnt lgkmcnt(0)
	v_pk_fma_f32 v[112:113], v[120:121], v[124:125], v[112:113]
	v_mov_b64_e32 v[120:121], v[130:131]
	s_nop 0
	v_pk_fma_f32 v[114:115], v[122:123], v[120:121], v[114:115]
	global_store_dwordx4 v[148:149], v[116:119], off
	global_store_dwordx4 v[148:149], v[112:115], off offset:16
	s_nop 1
	v_lshlrev_b32_e32 v112, 10, v229
	v_add_u32_e32 v165, v240, v112
	ds_read_b128 v[116:119], v165
	ds_read_b128 v[112:115], v165 offset:16
	s_cbranch_vccnz .LBB0_1041
	s_and_saveexec_b64 s[12:13], s[38:39]
	s_xor_b64 s[12:13], exec, s[12:13]
	v_lshlrev_b32_e32 v120, 11, v229
	v_and_b32_e32 v120, 0x1f800, v120
	v_mov_b32_e32 v121, v193
	v_lshl_add_u64 v[120:121], s[24:25], 0, v[120:121]
	v_lshl_add_u64 v[120:121], v[192:193], 2, v[120:121]
	v_lshl_add_u64 v[120:121], v[120:121], 0, s[26:27]
	s_andn2_saveexec_b64 s[12:13], s[12:13]
	s_cbranch_execz .LBB0_1040
	v_lshlrev_b32_e32 v120, 5, v224
	v_readlane_b32 s80, v253, 0
	v_and_b32_e32 v120, 0xf800, v120
	v_mov_b32_e32 v121, v193
	v_readlane_b32 s82, v253, 2
	v_readlane_b32 s83, v253, 3
	v_readlane_b32 s86, v253, 6
	v_readlane_b32 s87, v253, 7
	v_readlane_b32 s84, v253, 4
	v_readlane_b32 s85, v253, 5
	s_movk_i32 s82, 0xfc00
	v_lshl_add_u64 v[120:121], s[86:87], 0, v[120:121]
	s_mov_b32 s83, -1
	s_mov_b64 s[84:85], 0x200
	v_lshl_add_u64 v[120:121], v[198:199], 2, v[120:121]
	v_readlane_b32 s81, v253, 1

.LBB0_1041:
	v_readlane_b32 s8, v254, 12
	v_readlane_b32 s16, v254, 20
	v_readlane_b32 s17, v254, 21
	v_mov_b32_e32 v197, v193
	s_and_b64 vcc, exec, s[40:41]
	v_lshl_add_u64 v[120:121], s[16:17], 0, v[222:223]
	v_lshl_add_u64 v[120:121], s[0:1], 2, v[120:121]
	v_lshl_add_u64 v[140:141], v[120:121], 0, v[196:197]
	ds_read_b128 v[120:123], v248 offset:16
	ds_read_b128 v[124:127], v248
	v_readlane_b32 s9, v254, 13
	v_readlane_b32 s10, v254, 14
	v_readlane_b32 s11, v254, 15
	v_readlane_b32 s12, v254, 16
	v_readlane_b32 s13, v254, 17
	v_readlane_b32 s14, v254, 18
	v_readlane_b32 s15, v254, 19
	v_readlane_b32 s18, v254, 22
	v_readlane_b32 s19, v254, 23
	v_readlane_b32 s20, v254, 24
	v_readlane_b32 s21, v254, 25
	v_readlane_b32 s22, v254, 26
	v_readlane_b32 s23, v254, 27
	s_waitcnt lgkmcnt(0)
	s_waitcnt lgkmcnt(1)
	v_pk_fma_f32 v[108:109], v[116:117], v[124:125], v[108:109]
	v_mov_b64_e32 v[116:117], v[126:127]
	s_nop 0
	v_pk_fma_f32 v[110:111], v[118:119], v[116:117], v[110:111]
	v_mov_b64_e32 v[116:117], v[120:121]
	s_waitcnt lgkmcnt(0)
	v_pk_fma_f32 v[104:105], v[112:113], v[116:117], v[104:105]
	v_mov_b64_e32 v[112:113], v[122:123]
	s_nop 0
	v_pk_fma_f32 v[106:107], v[114:115], v[112:113], v[106:107]
	global_store_dwordx4 v[140:141], v[108:111], off
	global_store_dwordx4 v[140:141], v[104:107], off offset:16
	s_nop 1
	v_lshlrev_b32_e32 v104, 10, v225
	v_add_u32_e32 v167, v240, v104
	ds_read_b128 v[108:111], v167
	ds_read_b128 v[104:107], v167 offset:16
	s_cbranch_vccnz .LBB0_1047
	s_and_saveexec_b64 s[12:13], s[38:39]
	s_xor_b64 s[12:13], exec, s[12:13]
	v_lshlrev_b32_e32 v112, 11, v225
	v_and_b32_e32 v112, 0x1f800, v112
	v_mov_b32_e32 v113, v193
	v_lshl_add_u64 v[112:113], s[24:25], 0, v[112:113]
	v_lshl_add_u64 v[112:113], v[192:193], 2, v[112:113]
	v_lshl_add_u64 v[112:113], v[112:113], 0, s[26:27]
	s_andn2_saveexec_b64 s[12:13], s[12:13]
	s_cbranch_execz .LBB0_1046
	v_lshlrev_b32_e32 v112, 5, v220
	v_readlane_b32 s80, v253, 0
	v_and_b32_e32 v112, 0xf800, v112
	v_mov_b32_e32 v113, v193
	v_readlane_b32 s82, v253, 2
	v_readlane_b32 s83, v253, 3
	v_readlane_b32 s86, v253, 6
	v_readlane_b32 s87, v253, 7
	v_readlane_b32 s84, v253, 4
	v_readlane_b32 s85, v253, 5
	s_movk_i32 s82, 0xfc00
	v_lshl_add_u64 v[112:113], s[86:87], 0, v[112:113]
	s_mov_b32 s83, -1
	s_mov_b64 s[84:85], 0x200
	v_lshl_add_u64 v[112:113], v[198:199], 2, v[112:113]
	v_readlane_b32 s81, v253, 1

.LBB0_1047:
	v_readlane_b32 s8, v254, 12
	v_readlane_b32 s16, v254, 20
	v_readlane_b32 s17, v254, 21
	v_mov_b32_e32 v197, v193
	s_and_b64 vcc, exec, s[40:41]
	v_lshl_add_u64 v[112:113], s[16:17], 0, v[218:219]
	v_lshl_add_u64 v[112:113], s[0:1], 2, v[112:113]
	v_lshl_add_u64 v[128:129], v[112:113], 0, v[196:197]
	ds_read_b128 v[112:115], v248 offset:16
	ds_read_b128 v[116:119], v248
	v_readlane_b32 s9, v254, 13
	v_readlane_b32 s10, v254, 14
	v_readlane_b32 s11, v254, 15
	v_readlane_b32 s12, v254, 16
	v_readlane_b32 s13, v254, 17
	v_readlane_b32 s14, v254, 18
	v_readlane_b32 s15, v254, 19
	v_readlane_b32 s18, v254, 22
	v_readlane_b32 s19, v254, 23
	v_readlane_b32 s20, v254, 24
	v_readlane_b32 s21, v254, 25
	v_readlane_b32 s22, v254, 26
	v_readlane_b32 s23, v254, 27
	s_waitcnt lgkmcnt(0)
	s_waitcnt lgkmcnt(1)
	v_pk_fma_f32 v[100:101], v[108:109], v[116:117], v[100:101]
	v_mov_b64_e32 v[108:109], v[118:119]
	s_nop 0
	v_pk_fma_f32 v[102:103], v[110:111], v[108:109], v[102:103]
	v_mov_b64_e32 v[108:109], v[112:113]
	s_waitcnt lgkmcnt(0)
	v_pk_fma_f32 v[96:97], v[104:105], v[108:109], v[96:97]
	v_mov_b64_e32 v[104:105], v[114:115]
	s_nop 0
	v_pk_fma_f32 v[98:99], v[106:107], v[104:105], v[98:99]
	global_store_dwordx4 v[128:129], v[100:103], off
	global_store_dwordx4 v[128:129], v[96:99], off offset:16
	s_nop 1
	v_lshlrev_b32_e32 v96, 10, v221
	v_add_u32_e32 v168, v240, v96
	ds_read_b128 v[100:103], v168
	ds_read_b128 v[96:99], v168 offset:16
	s_cbranch_vccnz .LBB0_1053
	s_and_saveexec_b64 s[12:13], s[38:39]
	s_xor_b64 s[12:13], exec, s[12:13]
	v_lshlrev_b32_e32 v104, 11, v221
	v_and_b32_e32 v104, 0x1f800, v104
	v_mov_b32_e32 v105, v193
	v_lshl_add_u64 v[104:105], s[24:25], 0, v[104:105]
	v_lshl_add_u64 v[104:105], v[192:193], 2, v[104:105]
	v_lshl_add_u64 v[104:105], v[104:105], 0, s[26:27]
	s_andn2_saveexec_b64 s[12:13], s[12:13]
	s_cbranch_execz .LBB0_1052
	v_lshlrev_b32_e32 v104, 5, v216
	v_readlane_b32 s80, v253, 0
	v_and_b32_e32 v104, 0xf800, v104
	v_mov_b32_e32 v105, v193
	v_readlane_b32 s82, v253, 2
	v_readlane_b32 s83, v253, 3
	v_readlane_b32 s86, v253, 6
	v_readlane_b32 s87, v253, 7
	v_readlane_b32 s84, v253, 4
	v_readlane_b32 s85, v253, 5
	s_movk_i32 s82, 0xfc00
	v_lshl_add_u64 v[104:105], s[86:87], 0, v[104:105]
	s_mov_b32 s83, -1
	s_mov_b64 s[84:85], 0x200
	v_lshl_add_u64 v[104:105], v[198:199], 2, v[104:105]
	v_readlane_b32 s81, v253, 1

.LBB0_1053:
	v_readlane_b32 s8, v254, 12
	v_readlane_b32 s16, v254, 20
	v_readlane_b32 s17, v254, 21
	v_mov_b32_e32 v197, v193
	s_and_b64 vcc, exec, s[40:41]
	v_lshl_add_u64 v[104:105], s[16:17], 0, v[214:215]
	v_lshl_add_u64 v[104:105], s[0:1], 2, v[104:105]
	v_lshl_add_u64 v[120:121], v[104:105], 0, v[196:197]
	ds_read_b128 v[104:107], v248 offset:16
	ds_read_b128 v[108:111], v248
	v_readlane_b32 s9, v254, 13
	v_readlane_b32 s10, v254, 14
	v_readlane_b32 s11, v254, 15
	v_readlane_b32 s12, v254, 16
	v_readlane_b32 s13, v254, 17
	v_readlane_b32 s14, v254, 18
	v_readlane_b32 s15, v254, 19
	v_readlane_b32 s18, v254, 22
	v_readlane_b32 s19, v254, 23
	v_readlane_b32 s20, v254, 24
	v_readlane_b32 s21, v254, 25
	v_readlane_b32 s22, v254, 26
	v_readlane_b32 s23, v254, 27
	s_waitcnt lgkmcnt(0)
	s_waitcnt lgkmcnt(1)
	v_pk_fma_f32 v[92:93], v[100:101], v[108:109], v[92:93]
	v_mov_b64_e32 v[100:101], v[110:111]
	s_nop 0
	v_pk_fma_f32 v[94:95], v[102:103], v[100:101], v[94:95]
	v_mov_b64_e32 v[100:101], v[104:105]
	s_waitcnt lgkmcnt(0)
	v_pk_fma_f32 v[88:89], v[96:97], v[100:101], v[88:89]
	v_mov_b64_e32 v[96:97], v[106:107]
	s_nop 0
	v_pk_fma_f32 v[90:91], v[98:99], v[96:97], v[90:91]
	global_store_dwordx4 v[120:121], v[92:95], off
	global_store_dwordx4 v[120:121], v[88:91], off offset:16
	s_nop 1
	v_lshlrev_b32_e32 v88, 10, v217
	v_add_u32_e32 v169, v240, v88
	ds_read_b128 v[92:95], v169
	ds_read_b128 v[88:91], v169 offset:16
	s_cbranch_vccnz .LBB0_1059
	s_and_saveexec_b64 s[12:13], s[38:39]
	s_xor_b64 s[12:13], exec, s[12:13]
	v_lshlrev_b32_e32 v96, 11, v217
	v_and_b32_e32 v96, 0x1f800, v96
	v_mov_b32_e32 v97, v193
	v_lshl_add_u64 v[96:97], s[24:25], 0, v[96:97]
	v_lshl_add_u64 v[96:97], v[192:193], 2, v[96:97]
	v_lshl_add_u64 v[96:97], v[96:97], 0, s[26:27]
	s_andn2_saveexec_b64 s[12:13], s[12:13]
	s_cbranch_execz .LBB0_1058
	v_lshlrev_b32_e32 v96, 5, v212
	v_readlane_b32 s80, v253, 0
	v_and_b32_e32 v96, 0xf800, v96
	v_mov_b32_e32 v97, v193
	v_readlane_b32 s82, v253, 2
	v_readlane_b32 s83, v253, 3
	v_readlane_b32 s86, v253, 6
	v_readlane_b32 s87, v253, 7
	v_readlane_b32 s84, v253, 4
	v_readlane_b32 s85, v253, 5
	s_movk_i32 s82, 0xfc00
	v_lshl_add_u64 v[96:97], s[86:87], 0, v[96:97]
	s_mov_b32 s83, -1
	s_mov_b64 s[84:85], 0x200
	v_lshl_add_u64 v[96:97], v[198:199], 2, v[96:97]
	v_readlane_b32 s81, v253, 1

.LBB0_1059:
	v_readlane_b32 s8, v254, 12
	v_readlane_b32 s16, v254, 20
	v_readlane_b32 s17, v254, 21
	v_mov_b32_e32 v197, v193
	s_and_b64 vcc, exec, s[40:41]
	v_lshl_add_u64 v[96:97], s[16:17], 0, v[210:211]
	v_lshl_add_u64 v[96:97], s[0:1], 2, v[96:97]
	v_lshl_add_u64 v[112:113], v[96:97], 0, v[196:197]
	ds_read_b128 v[96:99], v248 offset:16
	ds_read_b128 v[100:103], v248
	v_readlane_b32 s9, v254, 13
	v_readlane_b32 s10, v254, 14
	v_readlane_b32 s11, v254, 15
	v_readlane_b32 s12, v254, 16
	v_readlane_b32 s13, v254, 17
	v_readlane_b32 s14, v254, 18
	v_readlane_b32 s15, v254, 19
	v_readlane_b32 s18, v254, 22
	v_readlane_b32 s19, v254, 23
	v_readlane_b32 s20, v254, 24
	v_readlane_b32 s21, v254, 25
	v_readlane_b32 s22, v254, 26
	v_readlane_b32 s23, v254, 27
	s_waitcnt lgkmcnt(0)
	s_waitcnt lgkmcnt(1)
	v_pk_fma_f32 v[84:85], v[92:93], v[100:101], v[84:85]
	v_mov_b64_e32 v[92:93], v[102:103]
	s_nop 0
	v_pk_fma_f32 v[86:87], v[94:95], v[92:93], v[86:87]
	v_mov_b64_e32 v[92:93], v[96:97]
	s_waitcnt lgkmcnt(0)
	v_pk_fma_f32 v[80:81], v[88:89], v[92:93], v[80:81]
	v_mov_b64_e32 v[88:89], v[98:99]
	s_nop 0
	v_pk_fma_f32 v[82:83], v[90:91], v[88:89], v[82:83]
	global_store_dwordx4 v[112:113], v[84:87], off
	global_store_dwordx4 v[112:113], v[80:83], off offset:16
	s_nop 1
	v_lshlrev_b32_e32 v80, 10, v213
	v_add_u32_e32 v170, v240, v80
	ds_read_b128 v[84:87], v170
	ds_read_b128 v[80:83], v170 offset:16
	s_cbranch_vccnz .LBB0_1065
	s_and_saveexec_b64 s[12:13], s[38:39]
	s_xor_b64 s[12:13], exec, s[12:13]
	v_lshlrev_b32_e32 v88, 11, v213
	v_and_b32_e32 v88, 0x1f800, v88
	v_mov_b32_e32 v89, v193
	v_lshl_add_u64 v[88:89], s[24:25], 0, v[88:89]
	v_lshl_add_u64 v[88:89], v[192:193], 2, v[88:89]
	v_lshl_add_u64 v[88:89], v[88:89], 0, s[26:27]
	s_andn2_saveexec_b64 s[12:13], s[12:13]
	s_cbranch_execz .LBB0_1064
	v_lshlrev_b32_e32 v88, 5, v208
	v_readlane_b32 s80, v253, 0
	v_and_b32_e32 v88, 0xf800, v88
	v_mov_b32_e32 v89, v193
	v_readlane_b32 s82, v253, 2
	v_readlane_b32 s83, v253, 3
	v_readlane_b32 s86, v253, 6
	v_readlane_b32 s87, v253, 7
	v_readlane_b32 s84, v253, 4
	v_readlane_b32 s85, v253, 5
	s_movk_i32 s82, 0xfc00
	v_lshl_add_u64 v[88:89], s[86:87], 0, v[88:89]
	s_mov_b32 s83, -1
	s_mov_b64 s[84:85], 0x200
	v_lshl_add_u64 v[88:89], v[198:199], 2, v[88:89]
	v_readlane_b32 s81, v253, 1

.LBB0_1065:
	v_readlane_b32 s8, v254, 12
	v_readlane_b32 s16, v254, 20
	v_readlane_b32 s17, v254, 21
	v_mov_b32_e32 v197, v193
	s_and_b64 vcc, exec, s[40:41]
	v_lshl_add_u64 v[88:89], s[16:17], 0, v[206:207]
	v_lshl_add_u64 v[88:89], s[0:1], 2, v[88:89]
	v_lshl_add_u64 v[104:105], v[88:89], 0, v[196:197]
	ds_read_b128 v[88:91], v248 offset:16
	ds_read_b128 v[92:95], v248
	v_readlane_b32 s9, v254, 13
	v_readlane_b32 s10, v254, 14
	v_readlane_b32 s11, v254, 15
	v_readlane_b32 s12, v254, 16
	v_readlane_b32 s13, v254, 17
	v_readlane_b32 s14, v254, 18
	v_readlane_b32 s15, v254, 19
	v_readlane_b32 s18, v254, 22
	v_readlane_b32 s19, v254, 23
	v_readlane_b32 s20, v254, 24
	v_readlane_b32 s21, v254, 25
	v_readlane_b32 s22, v254, 26
	v_readlane_b32 s23, v254, 27
	s_waitcnt lgkmcnt(0)
	s_waitcnt lgkmcnt(1)
	v_pk_fma_f32 v[76:77], v[84:85], v[92:93], v[76:77]
	v_mov_b64_e32 v[84:85], v[94:95]
	s_nop 0
	v_pk_fma_f32 v[78:79], v[86:87], v[84:85], v[78:79]
	v_mov_b64_e32 v[84:85], v[88:89]
	s_waitcnt lgkmcnt(0)
	v_pk_fma_f32 v[72:73], v[80:81], v[84:85], v[72:73]
	v_mov_b64_e32 v[80:81], v[90:91]
	s_nop 0
	v_pk_fma_f32 v[74:75], v[82:83], v[80:81], v[74:75]
	global_store_dwordx4 v[104:105], v[76:79], off
	global_store_dwordx4 v[104:105], v[72:75], off offset:16
	s_nop 1
	v_lshlrev_b32_e32 v72, 10, v195
	v_add_u32_e32 v171, v240, v72
	ds_read_b128 v[76:79], v171
	ds_read_b128 v[72:75], v171 offset:16
	s_cbranch_vccnz .LBB0_1071
	s_and_saveexec_b64 s[12:13], s[38:39]
	s_xor_b64 s[12:13], exec, s[12:13]
	v_lshlrev_b32_e32 v80, 11, v195
	v_and_b32_e32 v80, 0x1f800, v80
	v_mov_b32_e32 v81, v193
	v_lshl_add_u64 v[80:81], s[24:25], 0, v[80:81]
	v_lshl_add_u64 v[80:81], v[192:193], 2, v[80:81]
	v_lshl_add_u64 v[80:81], v[80:81], 0, s[26:27]
	s_andn2_saveexec_b64 s[12:13], s[12:13]
	s_cbranch_execz .LBB0_1070
	v_lshlrev_b32_e32 v80, 5, v204
	v_readlane_b32 s80, v253, 0
	v_and_b32_e32 v80, 0xf800, v80
	v_mov_b32_e32 v81, v193
	v_readlane_b32 s82, v253, 2
	v_readlane_b32 s83, v253, 3
	v_readlane_b32 s86, v253, 6
	v_readlane_b32 s87, v253, 7
	v_readlane_b32 s84, v253, 4
	v_readlane_b32 s85, v253, 5
	s_movk_i32 s82, 0xfc00
	v_lshl_add_u64 v[80:81], s[86:87], 0, v[80:81]
	s_mov_b32 s83, -1
	s_mov_b64 s[84:85], 0x200
	v_lshl_add_u64 v[80:81], v[198:199], 2, v[80:81]
	v_readlane_b32 s81, v253, 1

.LBB0_1071:
	ds_read_b128 v[84:87], v248
	ds_read_b128 v[88:91], v248 offset:16
	v_readlane_b32 s8, v254, 12
	v_readlane_b32 s16, v254, 20
	v_readlane_b32 s17, v254, 21
	v_add_u32_e32 v162, s2, v252
	v_add_u32_e32 v158, s2, v233
	v_lshl_add_u64 v[96:97], s[16:17], 0, v[202:203]
	v_add_u32_e32 v154, s2, v229
	v_mov_b32_e32 v197, v193
	v_add_u32_e32 v150, s2, v225
	v_add_u32_e32 v146, s2, v221
	v_add_u32_e32 v142, s2, v217
	v_add_u32_e32 v134, s2, v213
	v_add_u32_e32 v130, s2, v195
	v_lshl_add_u64 v[96:97], s[0:1], 2, v[96:97]
	v_ashrrev_i32_e32 v163, 31, v162
	v_ashrrev_i32_e32 v159, 31, v158
	v_ashrrev_i32_e32 v155, 31, v154
	v_ashrrev_i32_e32 v151, 31, v150
	v_ashrrev_i32_e32 v147, 31, v146
	v_ashrrev_i32_e32 v143, 31, v142
	v_ashrrev_i32_e32 v135, 31, v134
	v_ashrrev_i32_e32 v131, 31, v130
	v_lshl_add_u64 v[96:97], v[96:97], 0, v[196:197]
	v_lshlrev_b64 v[160:161], 12, v[162:163]
	v_lshlrev_b64 v[156:157], 12, v[158:159]
	v_lshlrev_b64 v[152:153], 12, v[154:155]
	v_lshlrev_b64 v[148:149], 12, v[150:151]
	v_lshlrev_b64 v[144:145], 12, v[146:147]
	v_lshlrev_b64 v[140:141], 12, v[142:143]
	v_lshlrev_b64 v[132:133], 12, v[134:135]
	v_lshlrev_b64 v[128:129], 12, v[130:131]
	v_lshl_add_u64 v[98:99], v[200:201], 0, v[160:161]
	v_lshl_add_u64 v[100:101], v[200:201], 0, v[156:157]
	v_lshl_add_u64 v[102:103], v[200:201], 0, v[152:153]
	v_lshl_add_u64 v[172:173], v[200:201], 0, v[148:149]
	v_lshl_add_u64 v[174:175], v[200:201], 0, v[144:145]
	v_lshl_add_u64 v[176:177], v[200:201], 0, v[140:141]
	v_lshl_add_u64 v[178:179], v[200:201], 0, v[132:133]
	v_lshl_add_u64 v[180:181], v[200:201], 0, v[128:129]
	v_readlane_b32 s9, v254, 13
	v_readlane_b32 s10, v254, 14
	v_readlane_b32 s11, v254, 15
	v_readlane_b32 s12, v254, 16
	v_readlane_b32 s13, v254, 17
	v_readlane_b32 s14, v254, 18
	v_readlane_b32 s15, v254, 19
	v_readlane_b32 s18, v254, 22
	v_readlane_b32 s19, v254, 23
	v_readlane_b32 s20, v254, 24
	v_readlane_b32 s21, v254, 25
	v_readlane_b32 s22, v254, 26
	v_readlane_b32 s23, v254, 27
	s_waitcnt lgkmcnt(0)
	v_mov_b64_e32 v[80:81], v[84:85]
	v_mov_b64_e32 v[82:83], v[86:87]
	v_mov_b64_e32 v[84:85], v[88:89]
	v_mov_b64_e32 v[86:87], v[90:91]
	s_waitcnt lgkmcnt(1)
	v_pk_fma_f32 v[68:69], v[76:77], v[80:81], v[68:69]
	v_pk_fma_f32 v[70:71], v[78:79], v[82:83], v[70:71]
	s_waitcnt lgkmcnt(0)
	v_pk_fma_f32 v[64:65], v[72:73], v[84:85], v[64:65]
	v_pk_fma_f32 v[66:67], v[74:75], v[86:87], v[66:67]
	global_store_dwordx4 v[96:97], v[68:71], off
	global_store_dwordx4 v[96:97], v[64:67], off offset:16
	global_load_dwordx4 v[120:123], v[98:99], off offset:16 nt
	global_load_dwordx4 v[124:127], v[98:99], off nt
	global_load_dwordx4 v[112:115], v[100:101], off offset:16 nt
	global_load_dwordx4 v[116:119], v[100:101], off nt
	global_load_dwordx4 v[104:107], v[102:103], off offset:16 nt
	global_load_dwordx4 v[108:111], v[102:103], off nt
	s_nop 0
	global_load_dwordx4 v[96:99], v[172:173], off offset:16 nt
	global_load_dwordx4 v[100:103], v[172:173], off nt
	global_load_dwordx4 v[88:91], v[174:175], off offset:16 nt
	global_load_dwordx4 v[92:95], v[174:175], off nt
	global_load_dwordx4 v[80:83], v[176:177], off offset:16 nt
	global_load_dwordx4 v[84:87], v[176:177], off nt
	global_load_dwordx4 v[72:75], v[178:179], off offset:16 nt
	global_load_dwordx4 v[76:79], v[178:179], off nt
	global_load_dwordx4 v[64:67], v[180:181], off offset:16 nt
	global_load_dwordx4 v[68:71], v[180:181], off nt
	s_barrier
	ds_write2st64_b32 v205, v0, v1 offset1:4
	ds_write2st64_b32 v205, v2, v3 offset0:8 offset1:12
	ds_write2st64_b32 v209, v4, v5 offset1:4
	ds_write2st64_b32 v209, v6, v7 offset0:8 offset1:12
	ds_write2st64_b32 v205, v8, v9 offset0:64 offset1:68
	ds_write2st64_b32 v205, v10, v11 offset0:72 offset1:76
	ds_write2st64_b32 v209, v12, v13 offset0:64 offset1:68
	ds_write2st64_b32 v209, v14, v15 offset0:72 offset1:76
	ds_write2st64_b32 v205, v16, v17 offset0:128 offset1:132
	ds_write2st64_b32 v205, v18, v19 offset0:136 offset1:140
	ds_write2st64_b32 v209, v20, v21 offset0:128 offset1:132
	ds_write2st64_b32 v209, v22, v23 offset0:136 offset1:140
	ds_write2st64_b32 v205, v24, v25 offset0:192 offset1:196
	ds_write2st64_b32 v205, v26, v27 offset0:200 offset1:204
	ds_write2st64_b32 v209, v28, v29 offset0:192 offset1:196
	ds_write2st64_b32 v209, v30, v31 offset0:200 offset1:204
	ds_write2st64_b32 v244, v32, v33 offset1:4
	ds_write2st64_b32 v244, v34, v35 offset0:8 offset1:12
	ds_write2st64_b32 v188, v36, v37 offset1:4
	ds_write2st64_b32 v188, v38, v39 offset0:8 offset1:12
	ds_write2st64_b32 v244, v40, v41 offset0:64 offset1:68
	ds_write2st64_b32 v244, v42, v43 offset0:72 offset1:76
	ds_write2st64_b32 v188, v44, v45 offset0:64 offset1:68
	ds_write2st64_b32 v188, v46, v47 offset0:72 offset1:76
	ds_write2st64_b32 v244, v48, v49 offset0:128 offset1:132
	ds_write2st64_b32 v244, v50, v51 offset0:136 offset1:140
	ds_write2st64_b32 v188, v52, v53 offset0:128 offset1:132
	ds_write2st64_b32 v188, v54, v55 offset0:136 offset1:140
	ds_write2st64_b32 v244, v56, v57 offset0:192 offset1:196
	ds_write2st64_b32 v244, v58, v59 offset0:200 offset1:204
	ds_write2st64_b32 v188, v60, v61 offset0:192 offset1:196
	ds_write2st64_b32 v188, v62, v63 offset0:200 offset1:204
	s_waitcnt lgkmcnt(0)
	s_barrier
	ds_read_b128 v[4:7], v164
	ds_read_b128 v[0:3], v164 offset:16
	s_and_b64 vcc, exec, s[40:41]
	s_cbranch_vccnz .LBB0_1077
	s_and_saveexec_b64 s[2:3], s[38:39]
	s_xor_b64 s[2:3], exec, s[2:3]
	v_lshlrev_b32_e32 v8, 11, v252
	v_and_b32_e32 v8, 0x1f800, v8
	v_mov_b32_e32 v9, v193
	v_lshl_add_u64 v[8:9], s[24:25], 0, v[8:9]
	v_lshl_add_u64 v[8:9], v[192:193], 2, v[8:9]
	v_lshl_add_u64 v[8:9], v[8:9], 0, s[26:27]
	s_andn2_saveexec_b64 s[2:3], s[2:3]
	s_cbranch_execz .LBB0_1076
	v_lshlrev_b32_e32 v8, 5, v162
	v_readlane_b32 s80, v253, 0
	v_and_b32_e32 v8, 0xf800, v8
	v_mov_b32_e32 v9, v193
	v_readlane_b32 s82, v253, 2
	v_readlane_b32 s83, v253, 3
	v_readlane_b32 s86, v253, 6
	v_readlane_b32 s87, v253, 7
	v_readlane_b32 s84, v253, 4
	v_readlane_b32 s85, v253, 5
	s_movk_i32 s82, 0xfc00
	v_lshl_add_u64 v[8:9], s[86:87], 0, v[8:9]
	s_mov_b32 s83, -1
	s_mov_b64 s[84:85], 0x200
	v_lshl_add_u64 v[8:9], v[198:199], 2, v[8:9]
	v_readlane_b32 s81, v253, 1

.LBB0_1077:
	v_readlane_b32 s8, v254, 12
	v_readlane_b32 s16, v254, 20
	v_readlane_b32 s17, v254, 21
	v_mov_b32_e32 v197, v193
	s_and_b64 vcc, exec, s[40:41]
	v_lshl_add_u64 v[8:9], s[16:17], 0, v[160:161]
	v_lshl_add_u64 v[8:9], s[0:1], 2, v[8:9]
	v_lshl_add_u64 v[24:25], v[8:9], 0, v[196:197]
	ds_read_b128 v[8:11], v248 offset:16
	ds_read_b128 v[12:15], v248
	v_readlane_b32 s9, v254, 13
	v_readlane_b32 s10, v254, 14
	v_readlane_b32 s11, v254, 15
	v_readlane_b32 s12, v254, 16
	v_readlane_b32 s13, v254, 17
	v_readlane_b32 s14, v254, 18
	v_readlane_b32 s15, v254, 19
	v_readlane_b32 s18, v254, 22
	v_readlane_b32 s19, v254, 23
	v_readlane_b32 s20, v254, 24
	v_readlane_b32 s21, v254, 25
	v_readlane_b32 s22, v254, 26
	v_readlane_b32 s23, v254, 27
	s_waitcnt vmcnt(0) lgkmcnt(0)
	s_waitcnt lgkmcnt(0)
	v_pk_fma_f32 v[0:1], v[0:1], v[8:9], v[120:121]
	v_pk_fma_f32 v[4:5], v[4:5], v[12:13], v[124:125]
	v_mov_b64_e32 v[12:13], v[14:15]
	v_mov_b64_e32 v[8:9], v[10:11]
	v_pk_fma_f32 v[6:7], v[6:7], v[12:13], v[126:127]
	v_pk_fma_f32 v[2:3], v[2:3], v[8:9], v[122:123]
	global_store_dwordx4 v[24:25], v[4:7], off
	global_store_dwordx4 v[24:25], v[0:3], off offset:16
	ds_read_b128 v[4:7], v166
	ds_read_b128 v[0:3], v166 offset:16
	s_cbranch_vccnz .LBB0_1083
	s_and_saveexec_b64 s[2:3], s[38:39]
	s_xor_b64 s[2:3], exec, s[2:3]
	v_lshlrev_b32_e32 v8, 11, v233
	v_and_b32_e32 v8, 0x1f800, v8
	v_mov_b32_e32 v9, v193
	v_lshl_add_u64 v[8:9], s[24:25], 0, v[8:9]
	v_lshl_add_u64 v[8:9], v[192:193], 2, v[8:9]
	v_lshl_add_u64 v[8:9], v[8:9], 0, s[26:27]
	s_andn2_saveexec_b64 s[2:3], s[2:3]
	s_cbranch_execz .LBB0_1082
	v_lshlrev_b32_e32 v8, 5, v158
	v_readlane_b32 s80, v253, 0
	v_and_b32_e32 v8, 0xf800, v8
	v_mov_b32_e32 v9, v193
	v_readlane_b32 s82, v253, 2
	v_readlane_b32 s83, v253, 3
	v_readlane_b32 s86, v253, 6
	v_readlane_b32 s87, v253, 7
	v_readlane_b32 s84, v253, 4
	v_readlane_b32 s85, v253, 5
	s_movk_i32 s82, 0xfc00
	v_lshl_add_u64 v[8:9], s[86:87], 0, v[8:9]
	s_mov_b32 s83, -1
	s_mov_b64 s[84:85], 0x200
	v_lshl_add_u64 v[8:9], v[198:199], 2, v[8:9]
	v_readlane_b32 s81, v253, 1

.LBB0_1083:
	v_readlane_b32 s8, v254, 12
	v_readlane_b32 s16, v254, 20
	v_readlane_b32 s17, v254, 21
	v_mov_b32_e32 v197, v193
	s_and_b64 vcc, exec, s[40:41]
	v_lshl_add_u64 v[8:9], s[16:17], 0, v[156:157]
	v_lshl_add_u64 v[8:9], s[0:1], 2, v[8:9]
	v_lshl_add_u64 v[24:25], v[8:9], 0, v[196:197]
	ds_read_b128 v[8:11], v248 offset:16
	ds_read_b128 v[12:15], v248
	v_readlane_b32 s9, v254, 13
	v_readlane_b32 s10, v254, 14
	v_readlane_b32 s11, v254, 15
	v_readlane_b32 s12, v254, 16
	v_readlane_b32 s13, v254, 17
	v_readlane_b32 s14, v254, 18
	v_readlane_b32 s15, v254, 19
	v_readlane_b32 s18, v254, 22
	v_readlane_b32 s19, v254, 23
	v_readlane_b32 s20, v254, 24
	v_readlane_b32 s21, v254, 25
	v_readlane_b32 s22, v254, 26
	v_readlane_b32 s23, v254, 27
	s_waitcnt lgkmcnt(0)
	s_waitcnt lgkmcnt(0)
	v_pk_fma_f32 v[0:1], v[0:1], v[8:9], v[112:113]
	v_pk_fma_f32 v[4:5], v[4:5], v[12:13], v[116:117]
	v_mov_b64_e32 v[12:13], v[14:15]
	v_mov_b64_e32 v[8:9], v[10:11]
	v_pk_fma_f32 v[6:7], v[6:7], v[12:13], v[118:119]
	v_pk_fma_f32 v[2:3], v[2:3], v[8:9], v[114:115]
	global_store_dwordx4 v[24:25], v[4:7], off
	global_store_dwordx4 v[24:25], v[0:3], off offset:16
	ds_read_b128 v[4:7], v165
	ds_read_b128 v[0:3], v165 offset:16
	s_cbranch_vccnz .LBB0_1089
	s_and_saveexec_b64 s[2:3], s[38:39]
	s_xor_b64 s[2:3], exec, s[2:3]
	v_lshlrev_b32_e32 v8, 11, v229
	v_and_b32_e32 v8, 0x1f800, v8
	v_mov_b32_e32 v9, v193
	v_lshl_add_u64 v[8:9], s[24:25], 0, v[8:9]
	v_lshl_add_u64 v[8:9], v[192:193], 2, v[8:9]
	v_lshl_add_u64 v[8:9], v[8:9], 0, s[26:27]
	s_andn2_saveexec_b64 s[2:3], s[2:3]
	s_cbranch_execz .LBB0_1088
	v_lshlrev_b32_e32 v8, 5, v154
	v_readlane_b32 s80, v253, 0
	v_and_b32_e32 v8, 0xf800, v8
	v_mov_b32_e32 v9, v193
	v_readlane_b32 s82, v253, 2
	v_readlane_b32 s83, v253, 3
	v_readlane_b32 s86, v253, 6
	v_readlane_b32 s87, v253, 7
	v_readlane_b32 s84, v253, 4
	v_readlane_b32 s85, v253, 5
	s_movk_i32 s82, 0xfc00
	v_lshl_add_u64 v[8:9], s[86:87], 0, v[8:9]
	s_mov_b32 s83, -1
	s_mov_b64 s[84:85], 0x200
	v_lshl_add_u64 v[8:9], v[198:199], 2, v[8:9]
	v_readlane_b32 s81, v253, 1

.LBB0_1089:
	v_readlane_b32 s8, v254, 12
	v_readlane_b32 s16, v254, 20
	v_readlane_b32 s17, v254, 21
	v_mov_b32_e32 v197, v193
	s_and_b64 vcc, exec, s[40:41]
	v_lshl_add_u64 v[8:9], s[16:17], 0, v[152:153]
	v_lshl_add_u64 v[8:9], s[0:1], 2, v[8:9]
	v_lshl_add_u64 v[24:25], v[8:9], 0, v[196:197]
	ds_read_b128 v[8:11], v248 offset:16
	ds_read_b128 v[12:15], v248
	v_readlane_b32 s9, v254, 13
	v_readlane_b32 s10, v254, 14
	v_readlane_b32 s11, v254, 15
	v_readlane_b32 s12, v254, 16
	v_readlane_b32 s13, v254, 17
	v_readlane_b32 s14, v254, 18
	v_readlane_b32 s15, v254, 19
	v_readlane_b32 s18, v254, 22
	v_readlane_b32 s19, v254, 23
	v_readlane_b32 s20, v254, 24
	v_readlane_b32 s21, v254, 25
	v_readlane_b32 s22, v254, 26
	v_readlane_b32 s23, v254, 27
	s_waitcnt lgkmcnt(0)
	s_waitcnt lgkmcnt(0)
	v_pk_fma_f32 v[0:1], v[0:1], v[8:9], v[104:105]
	v_pk_fma_f32 v[4:5], v[4:5], v[12:13], v[108:109]
	v_mov_b64_e32 v[12:13], v[14:15]
	v_mov_b64_e32 v[8:9], v[10:11]
	v_pk_fma_f32 v[6:7], v[6:7], v[12:13], v[110:111]
	v_pk_fma_f32 v[2:3], v[2:3], v[8:9], v[106:107]
	global_store_dwordx4 v[24:25], v[4:7], off
	global_store_dwordx4 v[24:25], v[0:3], off offset:16
	ds_read_b128 v[4:7], v167
	ds_read_b128 v[0:3], v167 offset:16
	s_cbranch_vccnz .LBB0_1095
	s_and_saveexec_b64 s[2:3], s[38:39]
	s_xor_b64 s[2:3], exec, s[2:3]
	v_lshlrev_b32_e32 v8, 11, v225
	v_and_b32_e32 v8, 0x1f800, v8
	v_mov_b32_e32 v9, v193
	v_lshl_add_u64 v[8:9], s[24:25], 0, v[8:9]
	v_lshl_add_u64 v[8:9], v[192:193], 2, v[8:9]
	v_lshl_add_u64 v[8:9], v[8:9], 0, s[26:27]
	s_andn2_saveexec_b64 s[2:3], s[2:3]
	s_cbranch_execz .LBB0_1094
	v_lshlrev_b32_e32 v8, 5, v150
	v_readlane_b32 s80, v253, 0
	v_and_b32_e32 v8, 0xf800, v8
	v_mov_b32_e32 v9, v193
	v_readlane_b32 s82, v253, 2
	v_readlane_b32 s83, v253, 3
	v_readlane_b32 s86, v253, 6
	v_readlane_b32 s87, v253, 7
	v_readlane_b32 s84, v253, 4
	v_readlane_b32 s85, v253, 5
	s_movk_i32 s82, 0xfc00
	v_lshl_add_u64 v[8:9], s[86:87], 0, v[8:9]
	s_mov_b32 s83, -1
	s_mov_b64 s[84:85], 0x200
	v_lshl_add_u64 v[8:9], v[198:199], 2, v[8:9]
	v_readlane_b32 s81, v253, 1

.LBB0_1095:
	v_readlane_b32 s8, v254, 12
	v_readlane_b32 s16, v254, 20
	v_readlane_b32 s17, v254, 21
	v_mov_b32_e32 v197, v193
	s_and_b64 vcc, exec, s[40:41]
	v_lshl_add_u64 v[8:9], s[16:17], 0, v[148:149]
	v_lshl_add_u64 v[8:9], s[0:1], 2, v[8:9]
	v_lshl_add_u64 v[24:25], v[8:9], 0, v[196:197]
	ds_read_b128 v[8:11], v248 offset:16
	ds_read_b128 v[12:15], v248
	v_readlane_b32 s9, v254, 13
	v_readlane_b32 s10, v254, 14
	v_readlane_b32 s11, v254, 15
	v_readlane_b32 s12, v254, 16
	v_readlane_b32 s13, v254, 17
	v_readlane_b32 s14, v254, 18
	v_readlane_b32 s15, v254, 19
	v_readlane_b32 s18, v254, 22
	v_readlane_b32 s19, v254, 23
	v_readlane_b32 s20, v254, 24
	v_readlane_b32 s21, v254, 25
	v_readlane_b32 s22, v254, 26
	v_readlane_b32 s23, v254, 27
	s_waitcnt lgkmcnt(0)
	s_waitcnt lgkmcnt(0)
	v_pk_fma_f32 v[0:1], v[0:1], v[8:9], v[96:97]
	v_pk_fma_f32 v[4:5], v[4:5], v[12:13], v[100:101]
	v_mov_b64_e32 v[12:13], v[14:15]
	v_mov_b64_e32 v[8:9], v[10:11]
	v_pk_fma_f32 v[6:7], v[6:7], v[12:13], v[102:103]
	v_pk_fma_f32 v[2:3], v[2:3], v[8:9], v[98:99]
	global_store_dwordx4 v[24:25], v[4:7], off
	global_store_dwordx4 v[24:25], v[0:3], off offset:16
	ds_read_b128 v[4:7], v168
	ds_read_b128 v[0:3], v168 offset:16
	s_cbranch_vccnz .LBB0_1101
	s_and_saveexec_b64 s[2:3], s[38:39]
	s_xor_b64 s[2:3], exec, s[2:3]
	v_lshlrev_b32_e32 v8, 11, v221
	v_and_b32_e32 v8, 0x1f800, v8
	v_mov_b32_e32 v9, v193
	v_lshl_add_u64 v[8:9], s[24:25], 0, v[8:9]
	v_lshl_add_u64 v[8:9], v[192:193], 2, v[8:9]
	v_lshl_add_u64 v[8:9], v[8:9], 0, s[26:27]
	s_andn2_saveexec_b64 s[2:3], s[2:3]
	s_cbranch_execz .LBB0_1100
	v_lshlrev_b32_e32 v8, 5, v146
	v_readlane_b32 s80, v253, 0
	v_and_b32_e32 v8, 0xf800, v8
	v_mov_b32_e32 v9, v193
	v_readlane_b32 s82, v253, 2
	v_readlane_b32 s83, v253, 3
	v_readlane_b32 s86, v253, 6
	v_readlane_b32 s87, v253, 7
	v_readlane_b32 s84, v253, 4
	v_readlane_b32 s85, v253, 5
	s_movk_i32 s82, 0xfc00
	v_lshl_add_u64 v[8:9], s[86:87], 0, v[8:9]
	s_mov_b32 s83, -1
	s_mov_b64 s[84:85], 0x200
	v_lshl_add_u64 v[8:9], v[198:199], 2, v[8:9]
	v_readlane_b32 s81, v253, 1

.LBB0_1101:
	v_readlane_b32 s8, v254, 12
	v_readlane_b32 s16, v254, 20
	v_readlane_b32 s17, v254, 21
	v_mov_b32_e32 v197, v193
	s_and_b64 vcc, exec, s[40:41]
	v_lshl_add_u64 v[8:9], s[16:17], 0, v[144:145]
	v_lshl_add_u64 v[8:9], s[0:1], 2, v[8:9]
	v_lshl_add_u64 v[24:25], v[8:9], 0, v[196:197]
	ds_read_b128 v[8:11], v248 offset:16
	ds_read_b128 v[12:15], v248
	v_readlane_b32 s9, v254, 13
	v_readlane_b32 s10, v254, 14
	v_readlane_b32 s11, v254, 15
	v_readlane_b32 s12, v254, 16
	v_readlane_b32 s13, v254, 17
	v_readlane_b32 s14, v254, 18
	v_readlane_b32 s15, v254, 19
	v_readlane_b32 s18, v254, 22
	v_readlane_b32 s19, v254, 23
	v_readlane_b32 s20, v254, 24
	v_readlane_b32 s21, v254, 25
	v_readlane_b32 s22, v254, 26
	v_readlane_b32 s23, v254, 27
	s_waitcnt lgkmcnt(0)
	s_waitcnt lgkmcnt(0)
	v_pk_fma_f32 v[0:1], v[0:1], v[8:9], v[88:89]
	v_pk_fma_f32 v[4:5], v[4:5], v[12:13], v[92:93]
	v_mov_b64_e32 v[12:13], v[14:15]
	v_mov_b64_e32 v[8:9], v[10:11]
	v_pk_fma_f32 v[6:7], v[6:7], v[12:13], v[94:95]
	v_pk_fma_f32 v[2:3], v[2:3], v[8:9], v[90:91]
	global_store_dwordx4 v[24:25], v[4:7], off
	global_store_dwordx4 v[24:25], v[0:3], off offset:16
	ds_read_b128 v[4:7], v169
	ds_read_b128 v[0:3], v169 offset:16
	s_cbranch_vccnz .LBB0_1107
	s_and_saveexec_b64 s[2:3], s[38:39]
	s_xor_b64 s[2:3], exec, s[2:3]
	v_lshlrev_b32_e32 v8, 11, v217
	v_and_b32_e32 v8, 0x1f800, v8
	v_mov_b32_e32 v9, v193
	v_lshl_add_u64 v[8:9], s[24:25], 0, v[8:9]
	v_lshl_add_u64 v[8:9], v[192:193], 2, v[8:9]
	v_lshl_add_u64 v[8:9], v[8:9], 0, s[26:27]
	s_andn2_saveexec_b64 s[2:3], s[2:3]
	s_cbranch_execz .LBB0_1106
	v_lshlrev_b32_e32 v8, 5, v142
	v_readlane_b32 s80, v253, 0
	v_and_b32_e32 v8, 0xf800, v8
	v_mov_b32_e32 v9, v193
	v_readlane_b32 s82, v253, 2
	v_readlane_b32 s83, v253, 3
	v_readlane_b32 s86, v253, 6
	v_readlane_b32 s87, v253, 7
	v_readlane_b32 s84, v253, 4
	v_readlane_b32 s85, v253, 5
	s_movk_i32 s82, 0xfc00
	v_lshl_add_u64 v[8:9], s[86:87], 0, v[8:9]
	s_mov_b32 s83, -1
	s_mov_b64 s[84:85], 0x200
	v_lshl_add_u64 v[8:9], v[198:199], 2, v[8:9]
	v_readlane_b32 s81, v253, 1

.LBB0_1107:
	v_readlane_b32 s8, v254, 12
	v_readlane_b32 s16, v254, 20
	v_readlane_b32 s17, v254, 21
	v_mov_b32_e32 v197, v193
	s_and_b64 vcc, exec, s[40:41]
	v_lshl_add_u64 v[8:9], s[16:17], 0, v[140:141]
	v_lshl_add_u64 v[8:9], s[0:1], 2, v[8:9]
	v_lshl_add_u64 v[24:25], v[8:9], 0, v[196:197]
	ds_read_b128 v[8:11], v248 offset:16
	ds_read_b128 v[12:15], v248
	v_readlane_b32 s9, v254, 13
	v_readlane_b32 s10, v254, 14
	v_readlane_b32 s11, v254, 15
	v_readlane_b32 s12, v254, 16
	v_readlane_b32 s13, v254, 17
	v_readlane_b32 s14, v254, 18
	v_readlane_b32 s15, v254, 19
	v_readlane_b32 s18, v254, 22
	v_readlane_b32 s19, v254, 23
	v_readlane_b32 s20, v254, 24
	v_readlane_b32 s21, v254, 25
	v_readlane_b32 s22, v254, 26
	v_readlane_b32 s23, v254, 27
	s_waitcnt lgkmcnt(0)
	s_waitcnt lgkmcnt(0)
	v_pk_fma_f32 v[0:1], v[0:1], v[8:9], v[80:81]
	v_pk_fma_f32 v[4:5], v[4:5], v[12:13], v[84:85]
	v_mov_b64_e32 v[12:13], v[14:15]
	v_mov_b64_e32 v[8:9], v[10:11]
	v_pk_fma_f32 v[6:7], v[6:7], v[12:13], v[86:87]
	v_pk_fma_f32 v[2:3], v[2:3], v[8:9], v[82:83]
	global_store_dwordx4 v[24:25], v[4:7], off
	global_store_dwordx4 v[24:25], v[0:3], off offset:16
	ds_read_b128 v[4:7], v170
	ds_read_b128 v[0:3], v170 offset:16
	s_cbranch_vccnz .LBB0_1113
	s_and_saveexec_b64 s[2:3], s[38:39]
	s_xor_b64 s[2:3], exec, s[2:3]
	v_lshlrev_b32_e32 v8, 11, v213
	v_and_b32_e32 v8, 0x1f800, v8
	v_mov_b32_e32 v9, v193
	v_lshl_add_u64 v[8:9], s[24:25], 0, v[8:9]
	v_lshl_add_u64 v[8:9], v[192:193], 2, v[8:9]
	v_lshl_add_u64 v[8:9], v[8:9], 0, s[26:27]
	s_andn2_saveexec_b64 s[2:3], s[2:3]
	s_cbranch_execz .LBB0_1112
	v_lshlrev_b32_e32 v8, 5, v134
	v_readlane_b32 s80, v253, 0
	v_and_b32_e32 v8, 0xf800, v8
	v_mov_b32_e32 v9, v193
	v_readlane_b32 s82, v253, 2
	v_readlane_b32 s83, v253, 3
	v_readlane_b32 s86, v253, 6
	v_readlane_b32 s87, v253, 7
	v_readlane_b32 s84, v253, 4
	v_readlane_b32 s85, v253, 5
	s_movk_i32 s82, 0xfc00
	v_lshl_add_u64 v[8:9], s[86:87], 0, v[8:9]
	s_mov_b32 s83, -1
	s_mov_b64 s[84:85], 0x200
	v_lshl_add_u64 v[8:9], v[198:199], 2, v[8:9]
	v_readlane_b32 s81, v253, 1

.LBB0_1113:
	v_readlane_b32 s8, v254, 12
	v_readlane_b32 s16, v254, 20
	v_readlane_b32 s17, v254, 21
	v_mov_b32_e32 v197, v193
	s_and_b64 vcc, exec, s[40:41]
	v_lshl_add_u64 v[8:9], s[16:17], 0, v[132:133]
	v_lshl_add_u64 v[8:9], s[0:1], 2, v[8:9]
	v_lshl_add_u64 v[24:25], v[8:9], 0, v[196:197]
	ds_read_b128 v[8:11], v248 offset:16
	ds_read_b128 v[12:15], v248
	v_readlane_b32 s9, v254, 13
	v_readlane_b32 s10, v254, 14
	v_readlane_b32 s11, v254, 15
	v_readlane_b32 s12, v254, 16
	v_readlane_b32 s13, v254, 17
	v_readlane_b32 s14, v254, 18
	v_readlane_b32 s15, v254, 19
	v_readlane_b32 s18, v254, 22
	v_readlane_b32 s19, v254, 23
	v_readlane_b32 s20, v254, 24
	v_readlane_b32 s21, v254, 25
	v_readlane_b32 s22, v254, 26
	v_readlane_b32 s23, v254, 27
	s_waitcnt lgkmcnt(0)
	s_waitcnt lgkmcnt(0)
	v_pk_fma_f32 v[0:1], v[0:1], v[8:9], v[72:73]
	v_pk_fma_f32 v[4:5], v[4:5], v[12:13], v[76:77]
	v_mov_b64_e32 v[12:13], v[14:15]
	v_mov_b64_e32 v[8:9], v[10:11]
	v_pk_fma_f32 v[6:7], v[6:7], v[12:13], v[78:79]
	v_pk_fma_f32 v[2:3], v[2:3], v[8:9], v[74:75]
	global_store_dwordx4 v[24:25], v[4:7], off
	global_store_dwordx4 v[24:25], v[0:3], off offset:16
	ds_read_b128 v[4:7], v171
	ds_read_b128 v[0:3], v171 offset:16
	s_cbranch_vccnz .LBB0_1012
	s_and_saveexec_b64 s[2:3], s[38:39]
	s_xor_b64 s[2:3], exec, s[2:3]
	v_lshlrev_b32_e32 v8, 11, v195
	v_and_b32_e32 v8, 0x1f800, v8
	v_mov_b32_e32 v9, v193
	v_lshl_add_u64 v[8:9], s[24:25], 0, v[8:9]
	v_lshl_add_u64 v[8:9], v[192:193], 2, v[8:9]
	v_lshl_add_u64 v[8:9], v[8:9], 0, s[26:27]
	s_andn2_saveexec_b64 s[2:3], s[2:3]
	s_cbranch_execz .LBB0_1011
	v_lshlrev_b32_e32 v8, 5, v130
	v_readlane_b32 s80, v253, 0
	v_and_b32_e32 v192, 0xf800, v8
	v_readlane_b32 s82, v253, 2
	v_readlane_b32 s83, v253, 3
	v_readlane_b32 s86, v253, 6
	v_readlane_b32 s87, v253, 7
	v_readlane_b32 s84, v253, 4
	v_readlane_b32 s85, v253, 5
	s_movk_i32 s82, 0xfc00
	v_lshl_add_u64 v[8:9], s[86:87], 0, v[192:193]
	s_mov_b32 s83, -1
	s_mov_b64 s[84:85], 0x200
	v_lshl_add_u64 v[8:9], v[198:199], 2, v[8:9]
	v_readlane_b32 s81, v253, 1
	s_branch .LBB0_1011

	.amdhsa_kernel _Z6k_mega6Params
		.amdhsa_group_segment_fixed_size 16416
		.amdhsa_private_segment_fixed_size 0
		.amdhsa_kernarg_size 688
		.amdhsa_user_sgpr_count 2
		.amdhsa_user_sgpr_dispatch_ptr 0
		.amdhsa_user_sgpr_queue_ptr 0
		.amdhsa_user_sgpr_kernarg_segment_ptr 1
		.amdhsa_user_sgpr_dispatch_id 0
		.amdhsa_user_sgpr_kernarg_preload_length 0
		.amdhsa_user_sgpr_kernarg_preload_offset 0
		.amdhsa_user_sgpr_private_segment_size 0
		.amdhsa_uses_dynamic_stack 0
		.amdhsa_enable_private_segment 0
		.amdhsa_system_sgpr_workgroup_id_x 1
		.amdhsa_system_sgpr_workgroup_id_y 0
		.amdhsa_system_sgpr_workgroup_id_z 0
		.amdhsa_system_sgpr_workgroup_info 0
		.amdhsa_system_vgpr_workitem_id 2
		.amdhsa_next_free_vgpr 256
		.amdhsa_next_free_sgpr 100
		.amdhsa_accum_offset 256
		.amdhsa_reserve_vcc 1
		.amdhsa_float_round_mode_32 0
		.amdhsa_float_round_mode_16_64 0
		.amdhsa_float_denorm_mode_32 3
		.amdhsa_float_denorm_mode_16_64 3
		.amdhsa_dx10_clamp 1
		.amdhsa_ieee_mode 1
		.amdhsa_fp16_overflow 0
		.amdhsa_tg_split 0
		.amdhsa_exception_fp_ieee_invalid_op 0
		.amdhsa_exception_fp_denorm_src 0
		.amdhsa_exception_fp_ieee_div_zero 0
		.amdhsa_exception_fp_ieee_overflow 0
		.amdhsa_exception_fp_ieee_underflow 0
		.amdhsa_exception_fp_ieee_inexact 0
		.amdhsa_exception_int_div_zero 0
	.end_amdhsa_kernel

amdhsa.kernels:
  - .agpr_count:     0
    .args:
      - .offset:         0
        .size:           432
        .value_kind:     by_value
      - .offset:         432
        .size:           4
        .value_kind:     hidden_block_count_x
      - .offset:         436
        .size:           4
        .value_kind:     hidden_block_count_y
      - .offset:         440
        .size:           4
        .value_kind:     hidden_block_count_z
      - .offset:         444
        .size:           2
        .value_kind:     hidden_group_size_x
      - .offset:         446
        .size:           2
        .value_kind:     hidden_group_size_y
      - .offset:         448
        .size:           2
        .value_kind:     hidden_group_size_z
      - .offset:         450
        .size:           2
        .value_kind:     hidden_remainder_x
      - .offset:         452
        .size:           2
        .value_kind:     hidden_remainder_y
      - .offset:         454
        .size:           2
        .value_kind:     hidden_remainder_z
      - .offset:         472
        .size:           8
        .value_kind:     hidden_global_offset_x
      - .offset:         480
        .size:           8
        .value_kind:     hidden_global_offset_y
      - .offset:         488
        .size:           8
        .value_kind:     hidden_global_offset_z
      - .offset:         496
        .size:           2
        .value_kind:     hidden_grid_dims
      - .offset:         520
        .size:           8
        .value_kind:     hidden_multigrid_sync_arg
      - .offset:         552
        .size:           4
        .value_kind:     hidden_dynamic_lds_size
    .group_segment_fixed_size: 16416
    .kernarg_segment_align: 8
    .kernarg_segment_size: 688
    .language:       OpenCL C
    .language_version:
      - 2
      - 0
    .max_flat_workgroup_size: 512
    .name:           _Z6k_mega6Params
    .private_segment_fixed_size: 0
    .sgpr_count:     106
    .sgpr_spill_count: 184
    .symbol:         _Z6k_mega6Params.kd
    .uniform_work_group_size: 1
    .uses_dynamic_stack: false
    .vgpr_count:     256
    .vgpr_spill_count: 0
    .wavefront_size: 64
